# 8-phase GEMM: coalesced 40 back-to-back s_setprio 0/1 pairs between MFMA clusters (on v52)
# baseline (speedup 1.0000x reference)
; #define PG8_STAGE(bufoff, gbase, voff) do { _Pragma("unroll") for (int _i = 0; _i < 2; ++_i) \
;         __builtin_amdgcn_global_load_lds((const unsigned*)((const char*)(gbase) + (voff)[_i]), (LAS unsigned*)(lds + (bufoff) + ldsw + _i * 8192), 16, 0, 0); } while (0)
; #define PG8_LDA(dst, b, h) do { _Pragma("unroll") for (int m = 0; m < 4; ++m) _Pragma("unroll") for (int k = 0; k < 2; ++k) dst[m][k] = *(const LAS bf16x8*)(lds + PG8_SA(b, h) + aoff + m * 2048 + k * 1024); } while (0)
; #define PG8_LDB(dst, b, h) do { _Pragma("unroll") for (int n = 0; n < 2; ++n) _Pragma("unroll") for (int k = 0; k < 2; ++k) dst[n][k] = *(const LAS bf16x8*)(lds + PG8_SB(b, h) + boff + n * 2048 + k * 1024); } while (0)
; #define PG8_MMA(ai, bj, At, Bt) do { __builtin_amdgcn_s_setprio(1); _Pragma("unroll") for (int m = 0; m < 4; ++m) _Pragma("unroll") for (int n = 0; n < 2; ++n) _Pragma("unroll") for (int k = 0; k < 2; ++k) \
;         acc[ai][bj][m][n] = __builtin_amdgcn_mfma_f32_16x16x32_bf16(Bt[n][k], At[m][k], acc[ai][bj][m][n], 0, 0, 0); __builtin_amdgcn_s_setprio(0); } while (0)
; #define PG8_WAIT_V(n) asm volatile("s_waitcnt vmcnt(" #n ")" ::: "memory")
; #define PG8_WAIT_L(n) asm volatile("s_waitcnt lgkmcnt(" #n ")" ::: "memory")
; #define PG8_BAR __builtin_amdgcn_s_barrier()
; template <class Epi, bool ALIGN_EPI, int M_, int N_, int K_, int LDA, int LDB>
; __device__ __forceinline__ void gemm_phase(LAS unsigned char* lds, const int tid_in, const int G_in, const int bx_in, const Gemm g, const Epi& E) {
;     ...
;         for (int t = 0; t < nt; t += 2) {
;             const bool last = (t == nt - 2);
;             const char* a1 = cA + (size_t)(t + 1) * kstep;
;             const char* a2 = last ? nA : cA + (size_t)(t + 2) * kstep; const char* b2 = last ? nB : cB + (size_t)(t + 2) * kstep;
;             const char* a3 = a2 + kstep; const char* b3 = b2 + kstep;
;             PG8_LDB(B0, 0, 0); PG8_LDB(B1, 0, 1); PG8_SCHED; PG8_LDA(At, 0, 0); PG8_STAGE(PG8_SA(1, 1), a1 + hstepA, voffA);
;             PG8_WAIT_V(8); PG8_WAIT_L(0); PG8_BAR; PG8_MMA(0, 0, At, B0); PG8_MMA(0, 1, At, B1); PG8_BAR; PG8_SCHED;
;             PG8_LDA(At, 0, 1); PG8_STAGE(PG8_SB(0, 0), b2, voffB); PG8_STAGE(PG8_SB(0, 1), b2 + hstepB, voffB); PG8_STAGE(PG8_SA(0, 0), a2, voffA);
;             PG8_WAIT_V(8); PG8_WAIT_L(0); PG8_BAR; PG8_MMA(1, 0, At, B0); PG8_MMA(1, 1, At, B1); PG8_BAR; PG8_SCHED;
.LBB0_65:
	s_add_u32 s0, s50, 0xfffc0080
	s_addc_u32 s1, s51, -1
	s_add_i32 s24, 0, 0x10000
	s_cmp_eq_u32 s96, 12
	s_cselect_b32 s63, s13, s1
	s_cselect_b32 s62, s43, s0
	s_cselect_b32 s61, s41, s85
	s_cselect_b32 s60, s49, s84
	s_add_i32 s58, 0, 0x14000
	v_add_u32_e32 v156, s24, v149
	v_add_u32_e32 v172, s58, v149
	ds_read_b128 v[140:143], v156
	ds_read_b128 v[144:147], v156 offset:1024
	ds_read_b128 v[152:155], v156 offset:2048
	ds_read_b128 v[156:159], v156 offset:3072
	ds_read_b128 v[160:163], v172
	ds_read_b128 v[164:167], v172 offset:1024
	ds_read_b128 v[168:171], v172 offset:2048
	ds_read_b128 v[172:175], v172 offset:3072
	v_lshl_add_u64 v[192:193], s[50:51], 0, v[136:137]
	s_add_i32 m0, s88, 0xc000
	ds_read_b128 v[176:179], v151
	ds_read_b128 v[180:183], v151 offset:1024
	ds_read_b128 v[184:187], v151 offset:2048
	ds_read_b128 v[188:191], v151 offset:3072
	ds_read_b128 v[202:205], v151 offset:4096
	ds_read_b128 v[206:209], v151 offset:5120
	ds_read_b128 v[210:213], v151 offset:6144
	ds_read_b128 v[214:217], v151 offset:7168
	global_load_lds_dwordx4 v[192:193], off
	v_lshl_add_u64 v[192:193], s[50:51], 0, v[138:139]
	s_add_i32 m0, s88, 0xe000
	s_nop 0
	global_load_lds_dwordx4 v[192:193], off
	s_waitcnt vmcnt(8)
	s_waitcnt lgkmcnt(0)
	s_barrier
	s_setprio 1
	s_waitcnt lgkmcnt(0)
	v_mfma_f32_16x16x32_bf16 v[126:129], v[140:143], v[176:179], v[126:129]
	v_mfma_f32_16x16x32_bf16 v[122:125], v[152:155], v[176:179], v[122:125]
	v_mfma_f32_16x16x32_bf16 v[110:113], v[140:143], v[184:187], v[110:113]
	v_mfma_f32_16x16x32_bf16 v[106:109], v[152:155], v[184:187], v[106:109]
	v_mfma_f32_16x16x32_bf16 v[94:97], v[140:143], v[202:205], v[94:97]
	v_mfma_f32_16x16x32_bf16 v[90:93], v[152:155], v[202:205], v[90:93]
	v_mfma_f32_16x16x32_bf16 v[78:81], v[140:143], v[210:213], v[78:81]
	v_mfma_f32_16x16x32_bf16 v[74:77], v[152:155], v[210:213], v[74:77]
	v_mfma_f32_16x16x32_bf16 v[126:129], v[144:147], v[180:183], v[126:129]
	v_mfma_f32_16x16x32_bf16 v[122:125], v[156:159], v[180:183], v[122:125]
	v_mfma_f32_16x16x32_bf16 v[110:113], v[144:147], v[188:191], v[110:113]
	v_mfma_f32_16x16x32_bf16 v[106:109], v[156:159], v[188:191], v[106:109]
	v_mfma_f32_16x16x32_bf16 v[94:97], v[144:147], v[206:209], v[94:97]
	v_mfma_f32_16x16x32_bf16 v[90:93], v[156:159], v[206:209], v[90:93]
	v_mfma_f32_16x16x32_bf16 v[78:81], v[144:147], v[214:217], v[78:81]
	v_mfma_f32_16x16x32_bf16 v[74:77], v[156:159], v[214:217], v[74:77]
	v_mfma_f32_16x16x32_bf16 v[118:121], v[160:163], v[176:179], v[118:121]
	v_mfma_f32_16x16x32_bf16 v[114:117], v[168:171], v[176:179], v[114:117]
	v_mfma_f32_16x16x32_bf16 v[102:105], v[160:163], v[184:187], v[102:105]
	v_mfma_f32_16x16x32_bf16 v[98:101], v[168:171], v[184:187], v[98:101]
	v_mfma_f32_16x16x32_bf16 v[86:89], v[160:163], v[202:205], v[86:89]
	v_mfma_f32_16x16x32_bf16 v[82:85], v[168:171], v[202:205], v[82:85]
	v_mfma_f32_16x16x32_bf16 v[70:73], v[160:163], v[210:213], v[70:73]
	v_mfma_f32_16x16x32_bf16 v[66:69], v[168:171], v[210:213], v[66:69]
	v_mfma_f32_16x16x32_bf16 v[118:121], v[164:167], v[180:183], v[118:121]
	v_mfma_f32_16x16x32_bf16 v[114:117], v[172:175], v[180:183], v[114:117]
	v_mfma_f32_16x16x32_bf16 v[102:105], v[164:167], v[188:191], v[102:105]
	v_mfma_f32_16x16x32_bf16 v[98:101], v[172:175], v[188:191], v[98:101]
	v_mfma_f32_16x16x32_bf16 v[86:89], v[164:167], v[206:209], v[86:89]
	v_mfma_f32_16x16x32_bf16 v[82:85], v[172:175], v[206:209], v[82:85]
	v_mfma_f32_16x16x32_bf16 v[70:73], v[164:167], v[214:217], v[70:73]
	v_mfma_f32_16x16x32_bf16 v[66:69], v[172:175], v[214:217], v[66:69]
	s_setprio 0
	s_barrier
	s_add_i32 s0, s24, s77
	v_lshl_add_u64 v[192:193], s[60:61], 0, v[0:1]
	s_mov_b32 m0, s0
	ds_read_b128 v[176:179], v151 offset:16384
	ds_read_b128 v[180:183], v151 offset:17408
	ds_read_b128 v[184:187], v151 offset:18432
	ds_read_b128 v[188:191], v151 offset:19456
	ds_read_b128 v[202:205], v151 offset:20480
	ds_read_b128 v[206:209], v151 offset:21504
	ds_read_b128 v[210:213], v151 offset:22528
	ds_read_b128 v[214:217], v151 offset:23552
	global_load_lds_dwordx4 v[192:193], off
	s_add_i32 m0, s0, 0x2000
	s_add_u32 s0, s60, 0x40000
	v_lshl_add_u64 v[200:201], s[60:61], 0, v[134:135]
	s_addc_u32 s1, s61, 0
	s_add_i32 s24, s58, s77
	global_load_lds_dwordx4 v[200:201], off
	v_lshl_add_u64 v[218:219], s[0:1], 0, v[0:1]
	s_mov_b32 m0, s24
	v_lshl_add_u64 v[220:221], s[62:63], 0, v[132:133]
	global_load_lds_dwordx4 v[218:219], off
	v_lshl_add_u64 v[218:219], s[0:1], 0, v[134:135]
	s_add_i32 m0, s24, 0x2000
	s_nop 0
	global_load_lds_dwordx4 v[218:219], off
	v_lshl_add_u64 v[218:219], s[62:63], 0, v[130:131]
	s_mov_b32 m0, s88
	s_nop 0
	global_load_lds_dwordx4 v[218:219], off
	s_mov_b32 m0, s89
	s_nop 0
	global_load_lds_dwordx4 v[220:221], off
	s_waitcnt vmcnt(8)
	s_waitcnt lgkmcnt(0)
	s_barrier
; #define PG8_STAGE(bufoff, gbase, voff) do { _Pragma("unroll") for (int _i = 0; _i < 2; ++_i) \
;         __builtin_amdgcn_global_load_lds((const unsigned*)((const char*)(gbase) + (voff)[_i]), (LAS unsigned*)(lds + (bufoff) + ldsw + _i * 8192), 16, 0, 0); } while (0)
; #define PG8_LDA(dst, b, h) do { _Pragma("unroll") for (int m = 0; m < 4; ++m) _Pragma("unroll") for (int k = 0; k < 2; ++k) dst[m][k] = *(const LAS bf16x8*)(lds + PG8_SA(b, h) + aoff + m * 2048 + k * 1024); } while (0)
; #define PG8_LDB(dst, b, h) do { _Pragma("unroll") for (int n = 0; n < 2; ++n) _Pragma("unroll") for (int k = 0; k < 2; ++k) dst[n][k] = *(const LAS bf16x8*)(lds + PG8_SB(b, h) + boff + n * 2048 + k * 1024); } while (0)
; #define PG8_MMA(ai, bj, At, Bt) do { __builtin_amdgcn_s_setprio(1); _Pragma("unroll") for (int m = 0; m < 4; ++m) _Pragma("unroll") for (int n = 0; n < 2; ++n) _Pragma("unroll") for (int k = 0; k < 2; ++k) \
;         acc[ai][bj][m][n] = __builtin_amdgcn_mfma_f32_16x16x32_bf16(Bt[n][k], At[m][k], acc[ai][bj][m][n], 0, 0, 0); __builtin_amdgcn_s_setprio(0); } while (0)
; #define PG8_WAIT_V(n) asm volatile("s_waitcnt vmcnt(" #n ")" ::: "memory")
; #define PG8_WAIT_L(n) asm volatile("s_waitcnt lgkmcnt(" #n ")" ::: "memory")
; #define PG8_BAR __builtin_amdgcn_s_barrier()
; #define PG8_SCHED __builtin_amdgcn_sched_barrier(0)
; template <class Epi, bool ALIGN_EPI, int M_, int N_, int K_, int LDA, int LDB>
; __device__ __forceinline__ void gemm_phase(LAS unsigned char* lds, const int tid_in, const int G_in, const int bx_in, const Gemm g, const Epi& E) {
;     ...
;             PG8_WAIT_V(8); PG8_WAIT_L(0); PG8_BAR; PG8_MMA(1, 0, At, B0); PG8_MMA(1, 1, At, B1); PG8_BAR; PG8_SCHED;
;             PG8_LDB(B0, 1, 0); PG8_LDB(B1, 1, 1); PG8_SCHED; PG8_LDA(At, 1, 0); PG8_STAGE(PG8_SA(0, 1), a2 + hstepA, voffA);
;             PG8_WAIT_V(8); PG8_WAIT_L(0); PG8_BAR; PG8_MMA(0, 0, At, B0); PG8_MMA(0, 1, At, B1); PG8_BAR; PG8_SCHED;
;             PG8_LDA(At, 1, 1); PG8_STAGE(PG8_SB(1, 0), b3, voffB); PG8_STAGE(PG8_SB(1, 1), b3 + hstepB, voffB); PG8_STAGE(PG8_SA(1, 0), a3, voffA);
;             PG8_WAIT_V(8); PG8_WAIT_L(0); PG8_BAR; PG8_MMA(1, 0, At, B0); PG8_MMA(1, 1, At, B1); PG8_BAR; PG8_SCHED;
	s_setprio 1
	s_waitcnt lgkmcnt(0)
	v_mfma_f32_16x16x32_bf16 v[62:65], v[140:143], v[176:179], v[62:65]
	v_mfma_f32_16x16x32_bf16 v[58:61], v[152:155], v[176:179], v[58:61]
	v_mfma_f32_16x16x32_bf16 v[46:49], v[140:143], v[184:187], v[46:49]
	v_mfma_f32_16x16x32_bf16 v[42:45], v[152:155], v[184:187], v[42:45]
	v_mfma_f32_16x16x32_bf16 v[30:33], v[140:143], v[202:205], v[30:33]
	v_mfma_f32_16x16x32_bf16 v[26:29], v[152:155], v[202:205], v[26:29]
	v_mfma_f32_16x16x32_bf16 v[14:17], v[140:143], v[210:213], v[14:17]
	v_mfma_f32_16x16x32_bf16 v[10:13], v[152:155], v[210:213], v[10:13]
	v_mfma_f32_16x16x32_bf16 v[62:65], v[144:147], v[180:183], v[62:65]
	v_mfma_f32_16x16x32_bf16 v[58:61], v[156:159], v[180:183], v[58:61]
	v_mfma_f32_16x16x32_bf16 v[46:49], v[144:147], v[188:191], v[46:49]
	v_mfma_f32_16x16x32_bf16 v[42:45], v[156:159], v[188:191], v[42:45]
	v_mfma_f32_16x16x32_bf16 v[30:33], v[144:147], v[206:209], v[30:33]
	v_mfma_f32_16x16x32_bf16 v[26:29], v[156:159], v[206:209], v[26:29]
	v_mfma_f32_16x16x32_bf16 v[14:17], v[144:147], v[214:217], v[14:17]
	v_mfma_f32_16x16x32_bf16 v[10:13], v[156:159], v[214:217], v[10:13]
	v_mfma_f32_16x16x32_bf16 v[54:57], v[160:163], v[176:179], v[54:57]
	v_mfma_f32_16x16x32_bf16 v[50:53], v[168:171], v[176:179], v[50:53]
	v_mfma_f32_16x16x32_bf16 v[38:41], v[160:163], v[184:187], v[38:41]
	v_mfma_f32_16x16x32_bf16 v[34:37], v[168:171], v[184:187], v[34:37]
	v_mfma_f32_16x16x32_bf16 v[22:25], v[160:163], v[202:205], v[22:25]
	v_mfma_f32_16x16x32_bf16 v[18:21], v[168:171], v[202:205], v[18:21]
	v_mfma_f32_16x16x32_bf16 v[6:9], v[160:163], v[210:213], v[6:9]
	v_mfma_f32_16x16x32_bf16 v[2:5], v[168:171], v[210:213], v[2:5]
	v_mfma_f32_16x16x32_bf16 v[54:57], v[164:167], v[180:183], v[54:57]
	v_mfma_f32_16x16x32_bf16 v[50:53], v[172:175], v[180:183], v[50:53]
	v_mfma_f32_16x16x32_bf16 v[38:41], v[164:167], v[188:191], v[38:41]
	v_mfma_f32_16x16x32_bf16 v[34:37], v[172:175], v[188:191], v[34:37]
	v_mfma_f32_16x16x32_bf16 v[22:25], v[164:167], v[206:209], v[22:25]
	v_mfma_f32_16x16x32_bf16 v[18:21], v[172:175], v[206:209], v[18:21]
	v_mfma_f32_16x16x32_bf16 v[6:9], v[164:167], v[214:217], v[6:9]
	v_mfma_f32_16x16x32_bf16 v[2:5], v[172:175], v[214:217], v[2:5]
	s_setprio 0
	s_barrier
	s_add_i32 s24, 0, 0x18000
	s_add_i32 s58, 0, 0x1c000
	v_add_u32_e32 v156, s24, v149
	v_add_u32_e32 v172, s58, v149
	ds_read_b128 v[140:143], v156
	ds_read_b128 v[144:147], v156 offset:1024
	ds_read_b128 v[152:155], v156 offset:2048
	ds_read_b128 v[156:159], v156 offset:3072
	ds_read_b128 v[160:163], v172
	ds_read_b128 v[164:167], v172 offset:1024
	ds_read_b128 v[168:171], v172 offset:2048
	ds_read_b128 v[172:175], v172 offset:3072
	s_add_u32 s0, s62, 0x40000
	s_addc_u32 s1, s63, 0
	s_mov_b32 m0, s90
	v_lshl_add_u64 v[222:223], s[0:1], 0, v[130:131]
	ds_read_b128 v[176:179], v151 offset:32768
	ds_read_b128 v[180:183], v151 offset:33792
	ds_read_b128 v[184:187], v151 offset:34816
	ds_read_b128 v[188:191], v151 offset:35840
	ds_read_b128 v[202:205], v151 offset:36864
	ds_read_b128 v[206:209], v151 offset:37888
	ds_read_b128 v[210:213], v151 offset:38912
	ds_read_b128 v[214:217], v151 offset:39936
	global_load_lds_dwordx4 v[222:223], off
	v_lshl_add_u64 v[222:223], s[0:1], 0, v[132:133]
	s_mov_b32 m0, s91
	s_nop 0
	global_load_lds_dwordx4 v[222:223], off
	s_waitcnt vmcnt(8)
	s_waitcnt lgkmcnt(0)
	s_barrier
	s_setprio 1
	s_waitcnt lgkmcnt(0)
	v_mfma_f32_16x16x32_bf16 v[126:129], v[140:143], v[176:179], v[126:129]
	v_mfma_f32_16x16x32_bf16 v[122:125], v[152:155], v[176:179], v[122:125]
	v_mfma_f32_16x16x32_bf16 v[110:113], v[140:143], v[184:187], v[110:113]
	v_mfma_f32_16x16x32_bf16 v[106:109], v[152:155], v[184:187], v[106:109]
	v_mfma_f32_16x16x32_bf16 v[94:97], v[140:143], v[202:205], v[94:97]
	v_mfma_f32_16x16x32_bf16 v[90:93], v[152:155], v[202:205], v[90:93]
	v_mfma_f32_16x16x32_bf16 v[78:81], v[140:143], v[210:213], v[78:81]
	v_mfma_f32_16x16x32_bf16 v[74:77], v[152:155], v[210:213], v[74:77]
	v_mfma_f32_16x16x32_bf16 v[126:129], v[144:147], v[180:183], v[126:129]
	v_mfma_f32_16x16x32_bf16 v[122:125], v[156:159], v[180:183], v[122:125]
	v_mfma_f32_16x16x32_bf16 v[110:113], v[144:147], v[188:191], v[110:113]
	v_mfma_f32_16x16x32_bf16 v[106:109], v[156:159], v[188:191], v[106:109]
	v_mfma_f32_16x16x32_bf16 v[94:97], v[144:147], v[206:209], v[94:97]
	v_mfma_f32_16x16x32_bf16 v[90:93], v[156:159], v[206:209], v[90:93]
	v_mfma_f32_16x16x32_bf16 v[78:81], v[144:147], v[214:217], v[78:81]
	v_mfma_f32_16x16x32_bf16 v[74:77], v[156:159], v[214:217], v[74:77]
	v_mfma_f32_16x16x32_bf16 v[118:121], v[160:163], v[176:179], v[118:121]
	v_mfma_f32_16x16x32_bf16 v[114:117], v[168:171], v[176:179], v[114:117]
	v_mfma_f32_16x16x32_bf16 v[102:105], v[160:163], v[184:187], v[102:105]
	v_mfma_f32_16x16x32_bf16 v[98:101], v[168:171], v[184:187], v[98:101]
	v_mfma_f32_16x16x32_bf16 v[86:89], v[160:163], v[202:205], v[86:89]
	v_mfma_f32_16x16x32_bf16 v[82:85], v[168:171], v[202:205], v[82:85]
	v_mfma_f32_16x16x32_bf16 v[70:73], v[160:163], v[210:213], v[70:73]
	v_mfma_f32_16x16x32_bf16 v[66:69], v[168:171], v[210:213], v[66:69]
	v_mfma_f32_16x16x32_bf16 v[118:121], v[164:167], v[180:183], v[118:121]
	v_mfma_f32_16x16x32_bf16 v[114:117], v[172:175], v[180:183], v[114:117]
	v_mfma_f32_16x16x32_bf16 v[102:105], v[164:167], v[188:191], v[102:105]
	v_mfma_f32_16x16x32_bf16 v[98:101], v[172:175], v[188:191], v[98:101]
	v_mfma_f32_16x16x32_bf16 v[86:89], v[164:167], v[206:209], v[86:89]
	v_mfma_f32_16x16x32_bf16 v[82:85], v[172:175], v[206:209], v[82:85]
	v_mfma_f32_16x16x32_bf16 v[70:73], v[164:167], v[214:217], v[70:73]
	v_mfma_f32_16x16x32_bf16 v[66:69], v[172:175], v[214:217], v[66:69]
	s_setprio 0
	s_barrier
; #define PG8_MMA(ai, bj, At, Bt) do { __builtin_amdgcn_s_setprio(1); _Pragma("unroll") for (int m = 0; m < 4; ++m) _Pragma("unroll") for (int n = 0; n < 2; ++n) _Pragma("unroll") for (int k = 0; k < 2; ++k) \
;         acc[ai][bj][m][n] = __builtin_amdgcn_mfma_f32_16x16x32_bf16(Bt[n][k], At[m][k], acc[ai][bj][m][n], 0, 0, 0); __builtin_amdgcn_s_setprio(0); } while (0)
; #define PG8_WAIT_V(n) asm volatile("s_waitcnt vmcnt(" #n ")" ::: "memory")
; #define PG8_WAIT_L(n) asm volatile("s_waitcnt lgkmcnt(" #n ")" ::: "memory")
; #define PG8_BAR __builtin_amdgcn_s_barrier()
; #define PG8_SCHED __builtin_amdgcn_sched_barrier(0)
; template <class Epi, bool ALIGN_EPI, int M_, int N_, int K_, int LDA, int LDB>
; __device__ __forceinline__ void gemm_phase(LAS unsigned char* lds, const int tid_in, const int G_in, const int bx_in, const Gemm g, const Epi& E) {
;     ...
;             PG8_WAIT_V(8); PG8_WAIT_L(0); PG8_BAR; PG8_MMA(1, 0, At, B0); PG8_MMA(1, 1, At, B1); PG8_BAR; PG8_SCHED;
;         }
;         if constexpr (ALIGN_EPI) { if (wr == 0) PG8_BAR; }
;         E(acc, cur, wr, wc, fr, fq);
;         if (!has_next) break;
	s_add_i32 s0, s24, s77
	v_lshl_add_u64 v[192:193], v[192:193], 0, s[54:55]
	s_mov_b32 m0, s0
	ds_read_b128 v[176:179], v151 offset:49152
	ds_read_b128 v[180:183], v151 offset:50176
	ds_read_b128 v[184:187], v151 offset:51200
	ds_read_b128 v[188:191], v151 offset:52224
	ds_read_b128 v[202:205], v151 offset:53248
	ds_read_b128 v[206:209], v151 offset:54272
	ds_read_b128 v[210:213], v151 offset:55296
	ds_read_b128 v[214:217], v151 offset:56320
	global_load_lds_dwordx4 v[192:193], off
	s_add_i32 m0, s0, 0x2000
	s_add_u32 s0, s60, 0x40080
	v_lshl_add_u64 v[192:193], v[200:201], 0, s[54:55]
	s_addc_u32 s1, s61, 0
	s_add_i32 s24, s58, s77
	global_load_lds_dwordx4 v[192:193], off
	v_lshl_add_u64 v[192:193], s[0:1], 0, v[0:1]
	s_mov_b32 m0, s24
	s_nop 0
	global_load_lds_dwordx4 v[192:193], off
	v_lshl_add_u64 v[192:193], s[0:1], 0, v[134:135]
	s_add_i32 m0, s24, 0x2000
	s_nop 0
	global_load_lds_dwordx4 v[192:193], off
	v_lshl_add_u64 v[192:193], v[218:219], 0, s[54:55]
	s_mov_b32 m0, s92
	s_nop 0
	global_load_lds_dwordx4 v[192:193], off
	v_lshl_add_u64 v[192:193], v[220:221], 0, s[54:55]
	s_mov_b32 m0, s93
	s_nop 0
	global_load_lds_dwordx4 v[192:193], off
	s_waitcnt vmcnt(8)
	s_waitcnt lgkmcnt(0)
	s_barrier
	s_setprio 1
	s_waitcnt lgkmcnt(0)
	v_mfma_f32_16x16x32_bf16 v[62:65], v[140:143], v[176:179], v[62:65]
	v_mfma_f32_16x16x32_bf16 v[58:61], v[152:155], v[176:179], v[58:61]
	v_mfma_f32_16x16x32_bf16 v[46:49], v[140:143], v[184:187], v[46:49]
	v_mfma_f32_16x16x32_bf16 v[42:45], v[152:155], v[184:187], v[42:45]
	v_mfma_f32_16x16x32_bf16 v[30:33], v[140:143], v[202:205], v[30:33]
	v_mfma_f32_16x16x32_bf16 v[26:29], v[152:155], v[202:205], v[26:29]
	v_mfma_f32_16x16x32_bf16 v[14:17], v[140:143], v[210:213], v[14:17]
	v_mfma_f32_16x16x32_bf16 v[10:13], v[152:155], v[210:213], v[10:13]
	v_mfma_f32_16x16x32_bf16 v[62:65], v[144:147], v[180:183], v[62:65]
	v_mfma_f32_16x16x32_bf16 v[58:61], v[156:159], v[180:183], v[58:61]
	v_mfma_f32_16x16x32_bf16 v[46:49], v[144:147], v[188:191], v[46:49]
	v_mfma_f32_16x16x32_bf16 v[42:45], v[156:159], v[188:191], v[42:45]
	v_mfma_f32_16x16x32_bf16 v[30:33], v[144:147], v[206:209], v[30:33]
	v_mfma_f32_16x16x32_bf16 v[26:29], v[156:159], v[206:209], v[26:29]
	v_mfma_f32_16x16x32_bf16 v[14:17], v[144:147], v[214:217], v[14:17]
	v_mfma_f32_16x16x32_bf16 v[10:13], v[156:159], v[214:217], v[10:13]
	v_mfma_f32_16x16x32_bf16 v[54:57], v[160:163], v[176:179], v[54:57]
	v_mfma_f32_16x16x32_bf16 v[50:53], v[168:171], v[176:179], v[50:53]
	v_mfma_f32_16x16x32_bf16 v[38:41], v[160:163], v[184:187], v[38:41]
	v_mfma_f32_16x16x32_bf16 v[34:37], v[168:171], v[184:187], v[34:37]
	v_mfma_f32_16x16x32_bf16 v[22:25], v[160:163], v[202:205], v[22:25]
	v_mfma_f32_16x16x32_bf16 v[18:21], v[168:171], v[202:205], v[18:21]
	v_mfma_f32_16x16x32_bf16 v[6:9], v[160:163], v[210:213], v[6:9]
	v_mfma_f32_16x16x32_bf16 v[2:5], v[168:171], v[210:213], v[2:5]
	v_mfma_f32_16x16x32_bf16 v[54:57], v[164:167], v[180:183], v[54:57]
	v_mfma_f32_16x16x32_bf16 v[50:53], v[172:175], v[180:183], v[50:53]
	v_mfma_f32_16x16x32_bf16 v[38:41], v[164:167], v[188:191], v[38:41]
	v_mfma_f32_16x16x32_bf16 v[34:37], v[172:175], v[188:191], v[34:37]
	v_mfma_f32_16x16x32_bf16 v[22:25], v[164:167], v[206:209], v[22:25]
	v_mfma_f32_16x16x32_bf16 v[18:21], v[172:175], v[206:209], v[18:21]
	v_mfma_f32_16x16x32_bf16 v[6:9], v[164:167], v[214:217], v[6:9]
	v_mfma_f32_16x16x32_bf16 v[2:5], v[172:175], v[214:217], v[2:5]
	s_setprio 0
	s_barrier
	s_add_i32 s96, s96, 2
	s_add_u32 s50, s50, 0x100
	s_addc_u32 s51, s51, 0
	s_add_u32 s84, s84, 0x100
	s_addc_u32 s85, s85, 0
	s_cmp_gt_u32 s96, 13
	s_cbranch_scc0 .LBB0_65
	v_readlane_b32 s96, v255, 14
	s_and_b64 vcc, exec, s[38:39]
	v_readlane_b32 s97, v255, 15
	s_cbranch_vccz .LBB0_68
	s_barrier

; #define PG8_STAGE(bufoff, gbase, voff) do { _Pragma("unroll") for (int _i = 0; _i < 2; ++_i) \
;         __builtin_amdgcn_global_load_lds((const unsigned*)((const char*)(gbase) + (voff)[_i]), (LAS unsigned*)(lds + (bufoff) + ldsw + _i * 8192), 16, 0, 0); } while (0)
; #define PG8_LDA(dst, b, h) do { _Pragma("unroll") for (int m = 0; m < 4; ++m) _Pragma("unroll") for (int k = 0; k < 2; ++k) dst[m][k] = *(const LAS bf16x8*)(lds + PG8_SA(b, h) + aoff + m * 2048 + k * 1024); } while (0)
; #define PG8_LDB(dst, b, h) do { _Pragma("unroll") for (int n = 0; n < 2; ++n) _Pragma("unroll") for (int k = 0; k < 2; ++k) dst[n][k] = *(const LAS bf16x8*)(lds + PG8_SB(b, h) + boff + n * 2048 + k * 1024); } while (0)
; #define PG8_MMA(ai, bj, At, Bt) do { __builtin_amdgcn_s_setprio(1); _Pragma("unroll") for (int m = 0; m < 4; ++m) _Pragma("unroll") for (int n = 0; n < 2; ++n) _Pragma("unroll") for (int k = 0; k < 2; ++k) \
;         acc[ai][bj][m][n] = __builtin_amdgcn_mfma_f32_16x16x32_bf16(Bt[n][k], At[m][k], acc[ai][bj][m][n], 0, 0, 0); __builtin_amdgcn_s_setprio(0); } while (0)
; #define PG8_WAIT_V(n) asm volatile("s_waitcnt vmcnt(" #n ")" ::: "memory")
; #define PG8_WAIT_L(n) asm volatile("s_waitcnt lgkmcnt(" #n ")" ::: "memory")
; #define PG8_BAR __builtin_amdgcn_s_barrier()
; template <class Epi, bool ALIGN_EPI, int M_, int N_, int K_, int LDA, int LDB>
; __device__ __forceinline__ void gemm_phase(LAS unsigned char* lds, const int tid_in, const int G_in, const int bx_in, const Gemm g, const Epi& E) {
;     ...
;         for (int t = 0; t < nt; t += 2) {
;             const bool last = (t == nt - 2);
;             const char* a1 = cA + (size_t)(t + 1) * kstep;
;             const char* a2 = last ? nA : cA + (size_t)(t + 2) * kstep; const char* b2 = last ? nB : cB + (size_t)(t + 2) * kstep;
;             const char* a3 = a2 + kstep; const char* b3 = b2 + kstep;
;             PG8_LDB(B0, 0, 0); PG8_LDB(B1, 0, 1); PG8_SCHED; PG8_LDA(At, 0, 0); PG8_STAGE(PG8_SA(1, 1), a1 + hstepA, voffA);
;             PG8_WAIT_V(8); PG8_WAIT_L(0); PG8_BAR; PG8_MMA(0, 0, At, B0); PG8_MMA(0, 1, At, B1); PG8_BAR; PG8_SCHED;
;             PG8_LDA(At, 0, 1); PG8_STAGE(PG8_SB(0, 0), b2, voffB); PG8_STAGE(PG8_SB(0, 1), b2 + hstepB, voffB); PG8_STAGE(PG8_SA(0, 0), a2, voffA);
;             PG8_WAIT_V(8); PG8_WAIT_L(0); PG8_BAR; PG8_MMA(1, 0, At, B0); PG8_MMA(1, 1, At, B1); PG8_BAR; PG8_SCHED;
.LBB0_95:
	s_add_u32 s0, s90, 0xfffc0080
	s_addc_u32 s1, s91, -1
	s_add_i32 s24, 0, 0x10000
	s_cmp_eq_u32 s75, 12
	s_cselect_b32 s63, s49, s1
	s_cselect_b32 s62, vcc_lo, s0
	s_cselect_b32 s61, s47, s93
	s_cselect_b32 s60, vcc_hi, s92
	s_add_i32 s58, 0, 0x14000
	v_add_u32_e32 v154, s24, v141
	v_add_u32_e32 v170, s58, v141
	ds_read_b128 v[136:139], v154
	ds_read_b128 v[146:149], v154 offset:1024
	ds_read_b128 v[150:153], v154 offset:2048
	ds_read_b128 v[154:157], v154 offset:3072
	ds_read_b128 v[158:161], v170
	ds_read_b128 v[162:165], v170 offset:1024
	ds_read_b128 v[166:169], v170 offset:2048
	ds_read_b128 v[170:173], v170 offset:3072
	v_lshl_add_u64 v[200:201], s[90:91], 0, v[132:133]
	s_add_i32 m0, s87, 0xc000
	ds_read_b128 v[174:177], v145
	ds_read_b128 v[178:181], v145 offset:1024
	ds_read_b128 v[182:185], v145 offset:2048
	ds_read_b128 v[186:189], v145 offset:3072
	ds_read_b128 v[190:193], v145 offset:4096
	ds_read_b128 v[202:205], v145 offset:5120
	ds_read_b128 v[206:209], v145 offset:6144
	ds_read_b128 v[210:213], v145 offset:7168
	global_load_lds_dwordx4 v[200:201], off
	v_lshl_add_u64 v[200:201], s[90:91], 0, v[134:135]
	s_add_i32 m0, s87, 0xe000
	s_nop 0
	global_load_lds_dwordx4 v[200:201], off
	s_waitcnt vmcnt(8)
	s_waitcnt lgkmcnt(0)
	s_barrier
	s_setprio 1
	s_waitcnt lgkmcnt(0)
	v_mfma_f32_16x16x32_bf16 v[126:129], v[136:139], v[174:177], v[126:129]
	v_mfma_f32_16x16x32_bf16 v[122:125], v[150:153], v[174:177], v[122:125]
	v_mfma_f32_16x16x32_bf16 v[110:113], v[136:139], v[182:185], v[110:113]
	v_mfma_f32_16x16x32_bf16 v[106:109], v[150:153], v[182:185], v[106:109]
	v_mfma_f32_16x16x32_bf16 v[94:97], v[136:139], v[190:193], v[94:97]
	v_mfma_f32_16x16x32_bf16 v[90:93], v[150:153], v[190:193], v[90:93]
	v_mfma_f32_16x16x32_bf16 v[78:81], v[136:139], v[206:209], v[78:81]
	v_mfma_f32_16x16x32_bf16 v[74:77], v[150:153], v[206:209], v[74:77]
	v_mfma_f32_16x16x32_bf16 v[126:129], v[146:149], v[178:181], v[126:129]
	v_mfma_f32_16x16x32_bf16 v[122:125], v[154:157], v[178:181], v[122:125]
	v_mfma_f32_16x16x32_bf16 v[110:113], v[146:149], v[186:189], v[110:113]
	v_mfma_f32_16x16x32_bf16 v[106:109], v[154:157], v[186:189], v[106:109]
	v_mfma_f32_16x16x32_bf16 v[94:97], v[146:149], v[202:205], v[94:97]
	v_mfma_f32_16x16x32_bf16 v[90:93], v[154:157], v[202:205], v[90:93]
	v_mfma_f32_16x16x32_bf16 v[78:81], v[146:149], v[210:213], v[78:81]
	v_mfma_f32_16x16x32_bf16 v[74:77], v[154:157], v[210:213], v[74:77]
	v_mfma_f32_16x16x32_bf16 v[118:121], v[158:161], v[174:177], v[118:121]
	v_mfma_f32_16x16x32_bf16 v[114:117], v[166:169], v[174:177], v[114:117]
	v_mfma_f32_16x16x32_bf16 v[102:105], v[158:161], v[182:185], v[102:105]
	v_mfma_f32_16x16x32_bf16 v[98:101], v[166:169], v[182:185], v[98:101]
	v_mfma_f32_16x16x32_bf16 v[86:89], v[158:161], v[190:193], v[86:89]
	v_mfma_f32_16x16x32_bf16 v[82:85], v[166:169], v[190:193], v[82:85]
	v_mfma_f32_16x16x32_bf16 v[70:73], v[158:161], v[206:209], v[70:73]
	v_mfma_f32_16x16x32_bf16 v[66:69], v[166:169], v[206:209], v[66:69]
	v_mfma_f32_16x16x32_bf16 v[118:121], v[162:165], v[178:181], v[118:121]
	v_mfma_f32_16x16x32_bf16 v[114:117], v[170:173], v[178:181], v[114:117]
	v_mfma_f32_16x16x32_bf16 v[102:105], v[162:165], v[186:189], v[102:105]
	v_mfma_f32_16x16x32_bf16 v[98:101], v[170:173], v[186:189], v[98:101]
	v_mfma_f32_16x16x32_bf16 v[86:89], v[162:165], v[202:205], v[86:89]
	v_mfma_f32_16x16x32_bf16 v[82:85], v[170:173], v[202:205], v[82:85]
	v_mfma_f32_16x16x32_bf16 v[70:73], v[162:165], v[210:213], v[70:73]
	v_mfma_f32_16x16x32_bf16 v[66:69], v[170:173], v[210:213], v[66:69]
	s_setprio 0
	s_barrier
	s_add_i32 s0, s24, s95
	v_lshl_add_u64 v[200:201], s[60:61], 0, v[0:1]
	s_mov_b32 m0, s0
	ds_read_b128 v[174:177], v145 offset:16384
	ds_read_b128 v[178:181], v145 offset:17408
	ds_read_b128 v[182:185], v145 offset:18432
	ds_read_b128 v[186:189], v145 offset:19456
	ds_read_b128 v[190:193], v145 offset:20480
	ds_read_b128 v[202:205], v145 offset:21504
	ds_read_b128 v[206:209], v145 offset:22528
	ds_read_b128 v[210:213], v145 offset:23552
	global_load_lds_dwordx4 v[200:201], off
	s_add_i32 m0, s0, 0x2000
	s_add_u32 s0, s60, 0x40000
	v_lshl_add_u64 v[214:215], s[60:61], 0, v[130:131]
	s_addc_u32 s1, s61, 0
	s_add_i32 s24, s58, s95
	global_load_lds_dwordx4 v[214:215], off
	v_lshl_add_u64 v[216:217], s[0:1], 0, v[0:1]
	s_mov_b32 m0, s24
	v_lshl_add_u64 v[218:219], s[62:63], 0, v[130:131]
	global_load_lds_dwordx4 v[216:217], off
	v_lshl_add_u64 v[216:217], s[0:1], 0, v[130:131]
	s_add_i32 m0, s24, 0x2000
	s_nop 0
	global_load_lds_dwordx4 v[216:217], off
	v_lshl_add_u64 v[216:217], s[62:63], 0, v[0:1]
	s_mov_b32 m0, s87
	s_nop 0
	global_load_lds_dwordx4 v[216:217], off
	s_mov_b32 m0, s89
	s_nop 0
	global_load_lds_dwordx4 v[218:219], off
	s_waitcnt vmcnt(8)
	s_waitcnt lgkmcnt(0)
	s_barrier
; #define PG8_STAGE(bufoff, gbase, voff) do { _Pragma("unroll") for (int _i = 0; _i < 2; ++_i) \
;         __builtin_amdgcn_global_load_lds((const unsigned*)((const char*)(gbase) + (voff)[_i]), (LAS unsigned*)(lds + (bufoff) + ldsw + _i * 8192), 16, 0, 0); } while (0)
; #define PG8_LDA(dst, b, h) do { _Pragma("unroll") for (int m = 0; m < 4; ++m) _Pragma("unroll") for (int k = 0; k < 2; ++k) dst[m][k] = *(const LAS bf16x8*)(lds + PG8_SA(b, h) + aoff + m * 2048 + k * 1024); } while (0)
; #define PG8_LDB(dst, b, h) do { _Pragma("unroll") for (int n = 0; n < 2; ++n) _Pragma("unroll") for (int k = 0; k < 2; ++k) dst[n][k] = *(const LAS bf16x8*)(lds + PG8_SB(b, h) + boff + n * 2048 + k * 1024); } while (0)
; #define PG8_MMA(ai, bj, At, Bt) do { __builtin_amdgcn_s_setprio(1); _Pragma("unroll") for (int m = 0; m < 4; ++m) _Pragma("unroll") for (int n = 0; n < 2; ++n) _Pragma("unroll") for (int k = 0; k < 2; ++k) \
;         acc[ai][bj][m][n] = __builtin_amdgcn_mfma_f32_16x16x32_bf16(Bt[n][k], At[m][k], acc[ai][bj][m][n], 0, 0, 0); __builtin_amdgcn_s_setprio(0); } while (0)
; #define PG8_WAIT_V(n) asm volatile("s_waitcnt vmcnt(" #n ")" ::: "memory")
; #define PG8_WAIT_L(n) asm volatile("s_waitcnt lgkmcnt(" #n ")" ::: "memory")
; #define PG8_BAR __builtin_amdgcn_s_barrier()
; #define PG8_SCHED __builtin_amdgcn_sched_barrier(0)
; template <class Epi, bool ALIGN_EPI, int M_, int N_, int K_, int LDA, int LDB>
; __device__ __forceinline__ void gemm_phase(LAS unsigned char* lds, const int tid_in, const int G_in, const int bx_in, const Gemm g, const Epi& E) {
;     ...
;             PG8_WAIT_V(8); PG8_WAIT_L(0); PG8_BAR; PG8_MMA(1, 0, At, B0); PG8_MMA(1, 1, At, B1); PG8_BAR; PG8_SCHED;
;             PG8_LDB(B0, 1, 0); PG8_LDB(B1, 1, 1); PG8_SCHED; PG8_LDA(At, 1, 0); PG8_STAGE(PG8_SA(0, 1), a2 + hstepA, voffA);
;             PG8_WAIT_V(8); PG8_WAIT_L(0); PG8_BAR; PG8_MMA(0, 0, At, B0); PG8_MMA(0, 1, At, B1); PG8_BAR; PG8_SCHED;
;             PG8_LDA(At, 1, 1); PG8_STAGE(PG8_SB(1, 0), b3, voffB); PG8_STAGE(PG8_SB(1, 1), b3 + hstepB, voffB); PG8_STAGE(PG8_SA(1, 0), a3, voffA);
;             PG8_WAIT_V(8); PG8_WAIT_L(0); PG8_BAR; PG8_MMA(1, 0, At, B0); PG8_MMA(1, 1, At, B1); PG8_BAR; PG8_SCHED;
	s_setprio 1
	s_waitcnt lgkmcnt(0)
	v_mfma_f32_16x16x32_bf16 v[62:65], v[136:139], v[174:177], v[62:65]
	v_mfma_f32_16x16x32_bf16 v[58:61], v[150:153], v[174:177], v[58:61]
	v_mfma_f32_16x16x32_bf16 v[46:49], v[136:139], v[182:185], v[46:49]
	v_mfma_f32_16x16x32_bf16 v[42:45], v[150:153], v[182:185], v[42:45]
	v_mfma_f32_16x16x32_bf16 v[30:33], v[136:139], v[190:193], v[30:33]
	v_mfma_f32_16x16x32_bf16 v[26:29], v[150:153], v[190:193], v[26:29]
	v_mfma_f32_16x16x32_bf16 v[14:17], v[136:139], v[206:209], v[14:17]
	v_mfma_f32_16x16x32_bf16 v[10:13], v[150:153], v[206:209], v[10:13]
	v_mfma_f32_16x16x32_bf16 v[62:65], v[146:149], v[178:181], v[62:65]
	v_mfma_f32_16x16x32_bf16 v[58:61], v[154:157], v[178:181], v[58:61]
	v_mfma_f32_16x16x32_bf16 v[46:49], v[146:149], v[186:189], v[46:49]
	v_mfma_f32_16x16x32_bf16 v[42:45], v[154:157], v[186:189], v[42:45]
	v_mfma_f32_16x16x32_bf16 v[30:33], v[146:149], v[202:205], v[30:33]
	v_mfma_f32_16x16x32_bf16 v[26:29], v[154:157], v[202:205], v[26:29]
	v_mfma_f32_16x16x32_bf16 v[14:17], v[146:149], v[210:213], v[14:17]
	v_mfma_f32_16x16x32_bf16 v[10:13], v[154:157], v[210:213], v[10:13]
	v_mfma_f32_16x16x32_bf16 v[54:57], v[158:161], v[174:177], v[54:57]
	v_mfma_f32_16x16x32_bf16 v[50:53], v[166:169], v[174:177], v[50:53]
	v_mfma_f32_16x16x32_bf16 v[38:41], v[158:161], v[182:185], v[38:41]
	v_mfma_f32_16x16x32_bf16 v[34:37], v[166:169], v[182:185], v[34:37]
	v_mfma_f32_16x16x32_bf16 v[22:25], v[158:161], v[190:193], v[22:25]
	v_mfma_f32_16x16x32_bf16 v[18:21], v[166:169], v[190:193], v[18:21]
	v_mfma_f32_16x16x32_bf16 v[6:9], v[158:161], v[206:209], v[6:9]
	v_mfma_f32_16x16x32_bf16 v[2:5], v[166:169], v[206:209], v[2:5]
	v_mfma_f32_16x16x32_bf16 v[54:57], v[162:165], v[178:181], v[54:57]
	v_mfma_f32_16x16x32_bf16 v[50:53], v[170:173], v[178:181], v[50:53]
	v_mfma_f32_16x16x32_bf16 v[38:41], v[162:165], v[186:189], v[38:41]
	v_mfma_f32_16x16x32_bf16 v[34:37], v[170:173], v[186:189], v[34:37]
	v_mfma_f32_16x16x32_bf16 v[22:25], v[162:165], v[202:205], v[22:25]
	v_mfma_f32_16x16x32_bf16 v[18:21], v[170:173], v[202:205], v[18:21]
	v_mfma_f32_16x16x32_bf16 v[6:9], v[162:165], v[210:213], v[6:9]
	v_mfma_f32_16x16x32_bf16 v[2:5], v[170:173], v[210:213], v[2:5]
	s_setprio 0
	s_barrier
	s_add_i32 s24, 0, 0x18000
	s_add_i32 s58, 0, 0x1c000
	v_add_u32_e32 v154, s24, v141
	v_add_u32_e32 v170, s58, v141
	ds_read_b128 v[136:139], v154
	ds_read_b128 v[146:149], v154 offset:1024
	ds_read_b128 v[150:153], v154 offset:2048
	ds_read_b128 v[154:157], v154 offset:3072
	ds_read_b128 v[158:161], v170
	ds_read_b128 v[162:165], v170 offset:1024
	ds_read_b128 v[166:169], v170 offset:2048
	ds_read_b128 v[170:173], v170 offset:3072
	s_add_u32 s0, s62, 0x40000
	s_addc_u32 s1, s63, 0
	s_mov_b32 m0, s96
	v_lshl_add_u64 v[220:221], s[0:1], 0, v[0:1]
	ds_read_b128 v[174:177], v145 offset:32768
	ds_read_b128 v[178:181], v145 offset:33792
	ds_read_b128 v[182:185], v145 offset:34816
	ds_read_b128 v[186:189], v145 offset:35840
	ds_read_b128 v[190:193], v145 offset:36864
	ds_read_b128 v[202:205], v145 offset:37888
	ds_read_b128 v[206:209], v145 offset:38912
	ds_read_b128 v[210:213], v145 offset:39936
	global_load_lds_dwordx4 v[220:221], off
	v_lshl_add_u64 v[220:221], s[0:1], 0, v[130:131]
	s_mov_b32 m0, s97
	s_nop 0
	global_load_lds_dwordx4 v[220:221], off
	s_waitcnt vmcnt(8)
	s_waitcnt lgkmcnt(0)
	s_barrier
	s_setprio 1
	s_waitcnt lgkmcnt(0)
	v_mfma_f32_16x16x32_bf16 v[126:129], v[136:139], v[174:177], v[126:129]
	v_mfma_f32_16x16x32_bf16 v[122:125], v[150:153], v[174:177], v[122:125]
	v_mfma_f32_16x16x32_bf16 v[110:113], v[136:139], v[182:185], v[110:113]
	v_mfma_f32_16x16x32_bf16 v[106:109], v[150:153], v[182:185], v[106:109]
	v_mfma_f32_16x16x32_bf16 v[94:97], v[136:139], v[190:193], v[94:97]
	v_mfma_f32_16x16x32_bf16 v[90:93], v[150:153], v[190:193], v[90:93]
	v_mfma_f32_16x16x32_bf16 v[78:81], v[136:139], v[206:209], v[78:81]
	v_mfma_f32_16x16x32_bf16 v[74:77], v[150:153], v[206:209], v[74:77]
	v_mfma_f32_16x16x32_bf16 v[126:129], v[146:149], v[178:181], v[126:129]
	v_mfma_f32_16x16x32_bf16 v[122:125], v[154:157], v[178:181], v[122:125]
	v_mfma_f32_16x16x32_bf16 v[110:113], v[146:149], v[186:189], v[110:113]
	v_mfma_f32_16x16x32_bf16 v[106:109], v[154:157], v[186:189], v[106:109]
	v_mfma_f32_16x16x32_bf16 v[94:97], v[146:149], v[202:205], v[94:97]
	v_mfma_f32_16x16x32_bf16 v[90:93], v[154:157], v[202:205], v[90:93]
	v_mfma_f32_16x16x32_bf16 v[78:81], v[146:149], v[210:213], v[78:81]
	v_mfma_f32_16x16x32_bf16 v[74:77], v[154:157], v[210:213], v[74:77]
	v_mfma_f32_16x16x32_bf16 v[118:121], v[158:161], v[174:177], v[118:121]
	v_mfma_f32_16x16x32_bf16 v[114:117], v[166:169], v[174:177], v[114:117]
	v_mfma_f32_16x16x32_bf16 v[102:105], v[158:161], v[182:185], v[102:105]
	v_mfma_f32_16x16x32_bf16 v[98:101], v[166:169], v[182:185], v[98:101]
	v_mfma_f32_16x16x32_bf16 v[86:89], v[158:161], v[190:193], v[86:89]
	v_mfma_f32_16x16x32_bf16 v[82:85], v[166:169], v[190:193], v[82:85]
	v_mfma_f32_16x16x32_bf16 v[70:73], v[158:161], v[206:209], v[70:73]
	v_mfma_f32_16x16x32_bf16 v[66:69], v[166:169], v[206:209], v[66:69]
	v_mfma_f32_16x16x32_bf16 v[118:121], v[162:165], v[178:181], v[118:121]
	v_mfma_f32_16x16x32_bf16 v[114:117], v[170:173], v[178:181], v[114:117]
	v_mfma_f32_16x16x32_bf16 v[102:105], v[162:165], v[186:189], v[102:105]
	v_mfma_f32_16x16x32_bf16 v[98:101], v[170:173], v[186:189], v[98:101]
	v_mfma_f32_16x16x32_bf16 v[86:89], v[162:165], v[202:205], v[86:89]
	v_mfma_f32_16x16x32_bf16 v[82:85], v[170:173], v[202:205], v[82:85]
	v_mfma_f32_16x16x32_bf16 v[70:73], v[162:165], v[210:213], v[70:73]
	v_mfma_f32_16x16x32_bf16 v[66:69], v[170:173], v[210:213], v[66:69]
	s_setprio 0
	s_barrier
; #define PG8_STAGE(bufoff, gbase, voff) do { _Pragma("unroll") for (int _i = 0; _i < 2; ++_i) \
;         __builtin_amdgcn_global_load_lds((const unsigned*)((const char*)(gbase) + (voff)[_i]), (LAS unsigned*)(lds + (bufoff) + ldsw + _i * 8192), 16, 0, 0); } while (0)
; #define PG8_LDA(dst, b, h) do { _Pragma("unroll") for (int m = 0; m < 4; ++m) _Pragma("unroll") for (int k = 0; k < 2; ++k) dst[m][k] = *(const LAS bf16x8*)(lds + PG8_SA(b, h) + aoff + m * 2048 + k * 1024); } while (0)
; #define PG8_MMA(ai, bj, At, Bt) do { __builtin_amdgcn_s_setprio(1); _Pragma("unroll") for (int m = 0; m < 4; ++m) _Pragma("unroll") for (int n = 0; n < 2; ++n) _Pragma("unroll") for (int k = 0; k < 2; ++k) \
;         acc[ai][bj][m][n] = __builtin_amdgcn_mfma_f32_16x16x32_bf16(Bt[n][k], At[m][k], acc[ai][bj][m][n], 0, 0, 0); __builtin_amdgcn_s_setprio(0); } while (0)
; #define PG8_WAIT_V(n) asm volatile("s_waitcnt vmcnt(" #n ")" ::: "memory")
; #define PG8_WAIT_L(n) asm volatile("s_waitcnt lgkmcnt(" #n ")" ::: "memory")
; #define PG8_BAR __builtin_amdgcn_s_barrier()
; #define PG8_SCHED __builtin_amdgcn_sched_barrier(0)
; template <class Epi, bool ALIGN_EPI, int M_, int N_, int K_, int LDA, int LDB>
; __device__ __forceinline__ void gemm_phase(LAS unsigned char* lds, const int tid_in, const int G_in, const int bx_in, const Gemm g, const Epi& E) {
;     ...
;             PG8_LDA(At, 1, 1); PG8_STAGE(PG8_SB(1, 0), b3, voffB); PG8_STAGE(PG8_SB(1, 1), b3 + hstepB, voffB); PG8_STAGE(PG8_SA(1, 0), a3, voffA);
;             PG8_WAIT_V(8); PG8_WAIT_L(0); PG8_BAR; PG8_MMA(1, 0, At, B0); PG8_MMA(1, 1, At, B1); PG8_BAR; PG8_SCHED;
;         }
;         if constexpr (ALIGN_EPI) { if (wr == 0) PG8_BAR; }
	s_add_i32 s0, s24, s95
	v_lshl_add_u64 v[200:201], v[200:201], 0, s[54:55]
	s_mov_b32 m0, s0
	ds_read_b128 v[174:177], v145 offset:49152
	ds_read_b128 v[178:181], v145 offset:50176
	ds_read_b128 v[182:185], v145 offset:51200
	ds_read_b128 v[186:189], v145 offset:52224
	ds_read_b128 v[190:193], v145 offset:53248
	ds_read_b128 v[202:205], v145 offset:54272
	ds_read_b128 v[206:209], v145 offset:55296
	ds_read_b128 v[210:213], v145 offset:56320
	global_load_lds_dwordx4 v[200:201], off
	s_add_i32 m0, s0, 0x2000
	s_add_u32 s0, s60, 0x40080
	v_lshl_add_u64 v[200:201], v[214:215], 0, s[54:55]
	s_addc_u32 s1, s61, 0
	s_add_i32 s24, s58, s95
	global_load_lds_dwordx4 v[200:201], off
	v_lshl_add_u64 v[200:201], s[0:1], 0, v[0:1]
	s_mov_b32 m0, s24
	s_nop 0
	global_load_lds_dwordx4 v[200:201], off
	v_lshl_add_u64 v[200:201], s[0:1], 0, v[130:131]
	s_add_i32 m0, s24, 0x2000
	s_nop 0
	global_load_lds_dwordx4 v[200:201], off
	v_lshl_add_u64 v[200:201], v[216:217], 0, s[54:55]
	s_mov_b32 m0, s12
	s_nop 0
	global_load_lds_dwordx4 v[200:201], off
	v_lshl_add_u64 v[200:201], v[218:219], 0, s[54:55]
	s_mov_b32 m0, s13
	s_nop 0
	global_load_lds_dwordx4 v[200:201], off
	s_waitcnt vmcnt(8)
	s_waitcnt lgkmcnt(0)
	s_barrier
	s_setprio 1
	s_waitcnt lgkmcnt(0)
	v_mfma_f32_16x16x32_bf16 v[62:65], v[136:139], v[174:177], v[62:65]
	v_mfma_f32_16x16x32_bf16 v[58:61], v[150:153], v[174:177], v[58:61]
	v_mfma_f32_16x16x32_bf16 v[46:49], v[136:139], v[182:185], v[46:49]
	v_mfma_f32_16x16x32_bf16 v[42:45], v[150:153], v[182:185], v[42:45]
	v_mfma_f32_16x16x32_bf16 v[30:33], v[136:139], v[190:193], v[30:33]
	v_mfma_f32_16x16x32_bf16 v[26:29], v[150:153], v[190:193], v[26:29]
	v_mfma_f32_16x16x32_bf16 v[14:17], v[136:139], v[206:209], v[14:17]
	v_mfma_f32_16x16x32_bf16 v[10:13], v[150:153], v[206:209], v[10:13]
	v_mfma_f32_16x16x32_bf16 v[62:65], v[146:149], v[178:181], v[62:65]
	v_mfma_f32_16x16x32_bf16 v[58:61], v[154:157], v[178:181], v[58:61]
	v_mfma_f32_16x16x32_bf16 v[46:49], v[146:149], v[186:189], v[46:49]
	v_mfma_f32_16x16x32_bf16 v[42:45], v[154:157], v[186:189], v[42:45]
	v_mfma_f32_16x16x32_bf16 v[30:33], v[146:149], v[202:205], v[30:33]
	v_mfma_f32_16x16x32_bf16 v[26:29], v[154:157], v[202:205], v[26:29]
	v_mfma_f32_16x16x32_bf16 v[14:17], v[146:149], v[210:213], v[14:17]
	v_mfma_f32_16x16x32_bf16 v[10:13], v[154:157], v[210:213], v[10:13]
	v_mfma_f32_16x16x32_bf16 v[54:57], v[158:161], v[174:177], v[54:57]
	v_mfma_f32_16x16x32_bf16 v[50:53], v[166:169], v[174:177], v[50:53]
	v_mfma_f32_16x16x32_bf16 v[38:41], v[158:161], v[182:185], v[38:41]
	v_mfma_f32_16x16x32_bf16 v[34:37], v[166:169], v[182:185], v[34:37]
	v_mfma_f32_16x16x32_bf16 v[22:25], v[158:161], v[190:193], v[22:25]
	v_mfma_f32_16x16x32_bf16 v[18:21], v[166:169], v[190:193], v[18:21]
	v_mfma_f32_16x16x32_bf16 v[6:9], v[158:161], v[206:209], v[6:9]
	v_mfma_f32_16x16x32_bf16 v[2:5], v[166:169], v[206:209], v[2:5]
	v_mfma_f32_16x16x32_bf16 v[54:57], v[162:165], v[178:181], v[54:57]
	v_mfma_f32_16x16x32_bf16 v[50:53], v[170:173], v[178:181], v[50:53]
	v_mfma_f32_16x16x32_bf16 v[38:41], v[162:165], v[186:189], v[38:41]
	v_mfma_f32_16x16x32_bf16 v[34:37], v[170:173], v[186:189], v[34:37]
	v_mfma_f32_16x16x32_bf16 v[22:25], v[162:165], v[202:205], v[22:25]
	v_mfma_f32_16x16x32_bf16 v[18:21], v[170:173], v[202:205], v[18:21]
	v_mfma_f32_16x16x32_bf16 v[6:9], v[162:165], v[210:213], v[6:9]
	v_mfma_f32_16x16x32_bf16 v[2:5], v[170:173], v[210:213], v[2:5]
	s_setprio 0
	s_barrier
	s_add_i32 s75, s75, 2
	s_add_u32 s90, s90, 0x100
	s_addc_u32 s91, s91, 0
	s_add_u32 s92, s92, 0x100
	s_addc_u32 s93, s93, 0
	s_cmp_gt_u32 s75, 13
	s_cbranch_scc0 .LBB0_95
	s_and_b64 vcc, exec, s[44:45]
	s_cbranch_vccz .LBB0_98
	s_barrier

; #define PG8_STAGE(bufoff, gbase, voff) do { _Pragma("unroll") for (int _i = 0; _i < 2; ++_i) \
;         __builtin_amdgcn_global_load_lds((const unsigned*)((const char*)(gbase) + (voff)[_i]), (LAS unsigned*)(lds + (bufoff) + ldsw + _i * 8192), 16, 0, 0); } while (0)
; #define PG8_LDA(dst, b, h) do { _Pragma("unroll") for (int m = 0; m < 4; ++m) _Pragma("unroll") for (int k = 0; k < 2; ++k) dst[m][k] = *(const LAS bf16x8*)(lds + PG8_SA(b, h) + aoff + m * 2048 + k * 1024); } while (0)
; #define PG8_LDB(dst, b, h) do { _Pragma("unroll") for (int n = 0; n < 2; ++n) _Pragma("unroll") for (int k = 0; k < 2; ++k) dst[n][k] = *(const LAS bf16x8*)(lds + PG8_SB(b, h) + boff + n * 2048 + k * 1024); } while (0)
; #define PG8_MMA(ai, bj, At, Bt) do { __builtin_amdgcn_s_setprio(1); _Pragma("unroll") for (int m = 0; m < 4; ++m) _Pragma("unroll") for (int n = 0; n < 2; ++n) _Pragma("unroll") for (int k = 0; k < 2; ++k) \
;         acc[ai][bj][m][n] = __builtin_amdgcn_mfma_f32_16x16x32_bf16(Bt[n][k], At[m][k], acc[ai][bj][m][n], 0, 0, 0); __builtin_amdgcn_s_setprio(0); } while (0)
; #define PG8_WAIT_V(n) asm volatile("s_waitcnt vmcnt(" #n ")" ::: "memory")
; #define PG8_WAIT_L(n) asm volatile("s_waitcnt lgkmcnt(" #n ")" ::: "memory")
; #define PG8_BAR __builtin_amdgcn_s_barrier()
; #define PG8_SCHED __builtin_amdgcn_sched_barrier(0)
; template <class Epi, bool ALIGN_EPI, int M_, int N_, int K_, int LDA, int LDB>
; __device__ __forceinline__ void gemm_phase(LAS unsigned char* lds, const int tid_in, const int G_in, const int bx_in, const Gemm g, const Epi& E) {
;     ...
;             const bool last = (t == nt - 2);
;             const char* a1 = cA + (size_t)(t + 1) * kstep;
;             const char* a2 = last ? nA : cA + (size_t)(t + 2) * kstep; const char* b2 = last ? nB : cB + (size_t)(t + 2) * kstep;
;             const char* a3 = a2 + kstep; const char* b3 = b2 + kstep;
;             PG8_LDB(B0, 0, 0); PG8_LDB(B1, 0, 1); PG8_SCHED; PG8_LDA(At, 0, 0); PG8_STAGE(PG8_SA(1, 1), a1 + hstepA, voffA);
;             PG8_WAIT_V(8); PG8_WAIT_L(0); PG8_BAR; PG8_MMA(0, 0, At, B0); PG8_MMA(0, 1, At, B1); PG8_BAR; PG8_SCHED;
;             PG8_LDA(At, 0, 1); PG8_STAGE(PG8_SB(0, 0), b2, voffB); PG8_STAGE(PG8_SB(0, 1), b2 + hstepB, voffB); PG8_STAGE(PG8_SA(0, 0), a2, voffA);
;             PG8_WAIT_V(8); PG8_WAIT_L(0); PG8_BAR; PG8_MMA(1, 0, At, B0); PG8_MMA(1, 1, At, B1); PG8_BAR; PG8_SCHED;
.LBB0_139:
	s_add_u32 s0, s50, 0xffe00080
	s_addc_u32 s1, s51, -1
	s_add_i32 s24, 0, 0x10000
	s_cmp_eq_u32 s96, 4
	s_cselect_b32 s63, s43, s1
	s_cselect_b32 s62, s94, s0
	s_cselect_b32 s61, s41, s87
	s_cselect_b32 s60, s95, s86
	s_add_i32 s66, 0, 0x14000
	v_add_u32_e32 v156, s24, v145
	v_add_u32_e32 v172, s66, v145
	ds_read_b128 v[140:143], v156
	ds_read_b128 v[148:151], v156 offset:1024
	ds_read_b128 v[152:155], v156 offset:2048
	ds_read_b128 v[156:159], v156 offset:3072
	ds_read_b128 v[160:163], v172
	ds_read_b128 v[164:167], v172 offset:1024
	ds_read_b128 v[168:171], v172 offset:2048
	ds_read_b128 v[172:175], v172 offset:3072
	v_lshl_add_u64 v[192:193], s[50:51], 0, v[136:137]
	s_add_i32 m0, s49, 0xc000
	ds_read_b128 v[176:179], v147
	ds_read_b128 v[180:183], v147 offset:1024
	ds_read_b128 v[184:187], v147 offset:2048
	ds_read_b128 v[188:191], v147 offset:3072
	ds_read_b128 v[202:205], v147 offset:4096
	ds_read_b128 v[206:209], v147 offset:5120
	ds_read_b128 v[210:213], v147 offset:6144
	ds_read_b128 v[214:217], v147 offset:7168
	global_load_lds_dwordx4 v[192:193], off
	v_lshl_add_u64 v[192:193], s[50:51], 0, v[138:139]
	s_add_i32 m0, s49, 0xe000
	s_nop 0
	global_load_lds_dwordx4 v[192:193], off
	s_waitcnt vmcnt(8)
	s_waitcnt lgkmcnt(0)
	s_barrier
	s_setprio 1
	s_waitcnt lgkmcnt(0)
	v_mfma_f32_16x16x32_bf16 v[126:129], v[140:143], v[176:179], v[126:129]
	v_mfma_f32_16x16x32_bf16 v[122:125], v[152:155], v[176:179], v[122:125]
	v_mfma_f32_16x16x32_bf16 v[114:117], v[140:143], v[184:187], v[114:117]
	v_mfma_f32_16x16x32_bf16 v[106:109], v[152:155], v[184:187], v[106:109]
	v_mfma_f32_16x16x32_bf16 v[98:101], v[140:143], v[202:205], v[98:101]
	v_mfma_f32_16x16x32_bf16 v[90:93], v[152:155], v[202:205], v[90:93]
	v_mfma_f32_16x16x32_bf16 v[82:85], v[140:143], v[210:213], v[82:85]
	v_mfma_f32_16x16x32_bf16 v[74:77], v[152:155], v[210:213], v[74:77]
	v_mfma_f32_16x16x32_bf16 v[126:129], v[148:151], v[180:183], v[126:129]
	v_mfma_f32_16x16x32_bf16 v[122:125], v[156:159], v[180:183], v[122:125]
	v_mfma_f32_16x16x32_bf16 v[114:117], v[148:151], v[188:191], v[114:117]
	v_mfma_f32_16x16x32_bf16 v[106:109], v[156:159], v[188:191], v[106:109]
	v_mfma_f32_16x16x32_bf16 v[98:101], v[148:151], v[206:209], v[98:101]
	v_mfma_f32_16x16x32_bf16 v[90:93], v[156:159], v[206:209], v[90:93]
	v_mfma_f32_16x16x32_bf16 v[82:85], v[148:151], v[214:217], v[82:85]
	v_mfma_f32_16x16x32_bf16 v[74:77], v[156:159], v[214:217], v[74:77]
	v_mfma_f32_16x16x32_bf16 v[118:121], v[160:163], v[176:179], v[118:121]
	v_mfma_f32_16x16x32_bf16 v[110:113], v[168:171], v[176:179], v[110:113]
	v_mfma_f32_16x16x32_bf16 v[102:105], v[160:163], v[184:187], v[102:105]
	v_mfma_f32_16x16x32_bf16 v[94:97], v[168:171], v[184:187], v[94:97]
	v_mfma_f32_16x16x32_bf16 v[86:89], v[160:163], v[202:205], v[86:89]
	v_mfma_f32_16x16x32_bf16 v[78:81], v[168:171], v[202:205], v[78:81]
	v_mfma_f32_16x16x32_bf16 v[70:73], v[160:163], v[210:213], v[70:73]
	v_mfma_f32_16x16x32_bf16 v[66:69], v[168:171], v[210:213], v[66:69]
	v_mfma_f32_16x16x32_bf16 v[118:121], v[164:167], v[180:183], v[118:121]
	v_mfma_f32_16x16x32_bf16 v[110:113], v[172:175], v[180:183], v[110:113]
	v_mfma_f32_16x16x32_bf16 v[102:105], v[164:167], v[188:191], v[102:105]
	v_mfma_f32_16x16x32_bf16 v[94:97], v[172:175], v[188:191], v[94:97]
	v_mfma_f32_16x16x32_bf16 v[86:89], v[164:167], v[206:209], v[86:89]
	v_mfma_f32_16x16x32_bf16 v[78:81], v[172:175], v[206:209], v[78:81]
	v_mfma_f32_16x16x32_bf16 v[70:73], v[164:167], v[214:217], v[70:73]
	v_mfma_f32_16x16x32_bf16 v[66:69], v[172:175], v[214:217], v[66:69]
	s_setprio 0
	s_barrier
	s_add_i32 s0, s24, s79
	v_lshl_add_u64 v[192:193], s[60:61], 0, v[0:1]
	s_mov_b32 m0, s0
	ds_read_b128 v[176:179], v147 offset:16384
	ds_read_b128 v[180:183], v147 offset:17408
	ds_read_b128 v[184:187], v147 offset:18432
	ds_read_b128 v[188:191], v147 offset:19456
	ds_read_b128 v[202:205], v147 offset:20480
	ds_read_b128 v[206:209], v147 offset:21504
	ds_read_b128 v[210:213], v147 offset:22528
	ds_read_b128 v[214:217], v147 offset:23552
	global_load_lds_dwordx4 v[192:193], off
	s_add_i32 m0, s0, 0x2000
	s_add_u32 s0, s60, 0x20000
	v_lshl_add_u64 v[200:201], s[60:61], 0, v[134:135]
	s_addc_u32 s1, s61, 0
	s_add_i32 s24, s66, s79
	global_load_lds_dwordx4 v[200:201], off
	v_lshl_add_u64 v[218:219], s[0:1], 0, v[0:1]
	s_mov_b32 m0, s24
	v_lshl_add_u64 v[220:221], s[62:63], 0, v[132:133]
	global_load_lds_dwordx4 v[218:219], off
	v_lshl_add_u64 v[218:219], s[0:1], 0, v[134:135]
	s_add_i32 m0, s24, 0x2000
	s_nop 0
	global_load_lds_dwordx4 v[218:219], off
	v_lshl_add_u64 v[218:219], s[62:63], 0, v[130:131]
	s_mov_b32 m0, s49
	s_nop 0
	global_load_lds_dwordx4 v[218:219], off
	s_mov_b32 m0, s84
	s_nop 0
	global_load_lds_dwordx4 v[220:221], off
	s_waitcnt vmcnt(8)
	s_waitcnt lgkmcnt(0)
	s_barrier
; #define PG8_STAGE(bufoff, gbase, voff) do { _Pragma("unroll") for (int _i = 0; _i < 2; ++_i) \
;         __builtin_amdgcn_global_load_lds((const unsigned*)((const char*)(gbase) + (voff)[_i]), (LAS unsigned*)(lds + (bufoff) + ldsw + _i * 8192), 16, 0, 0); } while (0)
; #define PG8_LDA(dst, b, h) do { _Pragma("unroll") for (int m = 0; m < 4; ++m) _Pragma("unroll") for (int k = 0; k < 2; ++k) dst[m][k] = *(const LAS bf16x8*)(lds + PG8_SA(b, h) + aoff + m * 2048 + k * 1024); } while (0)
; #define PG8_LDB(dst, b, h) do { _Pragma("unroll") for (int n = 0; n < 2; ++n) _Pragma("unroll") for (int k = 0; k < 2; ++k) dst[n][k] = *(const LAS bf16x8*)(lds + PG8_SB(b, h) + boff + n * 2048 + k * 1024); } while (0)
; #define PG8_MMA(ai, bj, At, Bt) do { __builtin_amdgcn_s_setprio(1); _Pragma("unroll") for (int m = 0; m < 4; ++m) _Pragma("unroll") for (int n = 0; n < 2; ++n) _Pragma("unroll") for (int k = 0; k < 2; ++k) \
;         acc[ai][bj][m][n] = __builtin_amdgcn_mfma_f32_16x16x32_bf16(Bt[n][k], At[m][k], acc[ai][bj][m][n], 0, 0, 0); __builtin_amdgcn_s_setprio(0); } while (0)
; #define PG8_WAIT_V(n) asm volatile("s_waitcnt vmcnt(" #n ")" ::: "memory")
; #define PG8_WAIT_L(n) asm volatile("s_waitcnt lgkmcnt(" #n ")" ::: "memory")
; #define PG8_BAR __builtin_amdgcn_s_barrier()
; #define PG8_SCHED __builtin_amdgcn_sched_barrier(0)
; template <class Epi, bool ALIGN_EPI, int M_, int N_, int K_, int LDA, int LDB>
; __device__ __forceinline__ void gemm_phase(LAS unsigned char* lds, const int tid_in, const int G_in, const int bx_in, const Gemm g, const Epi& E) {
;     ...
;             PG8_WAIT_V(8); PG8_WAIT_L(0); PG8_BAR; PG8_MMA(1, 0, At, B0); PG8_MMA(1, 1, At, B1); PG8_BAR; PG8_SCHED;
;             PG8_LDB(B0, 1, 0); PG8_LDB(B1, 1, 1); PG8_SCHED; PG8_LDA(At, 1, 0); PG8_STAGE(PG8_SA(0, 1), a2 + hstepA, voffA);
;             PG8_WAIT_V(8); PG8_WAIT_L(0); PG8_BAR; PG8_MMA(0, 0, At, B0); PG8_MMA(0, 1, At, B1); PG8_BAR; PG8_SCHED;
	s_setprio 1
	s_waitcnt lgkmcnt(0)
	v_mfma_f32_16x16x32_bf16 v[62:65], v[140:143], v[176:179], v[62:65]
	v_mfma_f32_16x16x32_bf16 v[58:61], v[152:155], v[176:179], v[58:61]
	v_mfma_f32_16x16x32_bf16 v[50:53], v[140:143], v[184:187], v[50:53]
	v_mfma_f32_16x16x32_bf16 v[42:45], v[152:155], v[184:187], v[42:45]
	v_mfma_f32_16x16x32_bf16 v[34:37], v[140:143], v[202:205], v[34:37]
	v_mfma_f32_16x16x32_bf16 v[26:29], v[152:155], v[202:205], v[26:29]
	v_mfma_f32_16x16x32_bf16 v[18:21], v[140:143], v[210:213], v[18:21]
	v_mfma_f32_16x16x32_bf16 v[10:13], v[152:155], v[210:213], v[10:13]
	v_mfma_f32_16x16x32_bf16 v[62:65], v[148:151], v[180:183], v[62:65]
	v_mfma_f32_16x16x32_bf16 v[58:61], v[156:159], v[180:183], v[58:61]
	v_mfma_f32_16x16x32_bf16 v[50:53], v[148:151], v[188:191], v[50:53]
	v_mfma_f32_16x16x32_bf16 v[42:45], v[156:159], v[188:191], v[42:45]
	v_mfma_f32_16x16x32_bf16 v[34:37], v[148:151], v[206:209], v[34:37]
	v_mfma_f32_16x16x32_bf16 v[26:29], v[156:159], v[206:209], v[26:29]
	v_mfma_f32_16x16x32_bf16 v[18:21], v[148:151], v[214:217], v[18:21]
	v_mfma_f32_16x16x32_bf16 v[10:13], v[156:159], v[214:217], v[10:13]
	v_mfma_f32_16x16x32_bf16 v[54:57], v[160:163], v[176:179], v[54:57]
	v_mfma_f32_16x16x32_bf16 v[46:49], v[168:171], v[176:179], v[46:49]
	v_mfma_f32_16x16x32_bf16 v[38:41], v[160:163], v[184:187], v[38:41]
	v_mfma_f32_16x16x32_bf16 v[30:33], v[168:171], v[184:187], v[30:33]
	v_mfma_f32_16x16x32_bf16 v[22:25], v[160:163], v[202:205], v[22:25]
	v_mfma_f32_16x16x32_bf16 v[14:17], v[168:171], v[202:205], v[14:17]
	v_mfma_f32_16x16x32_bf16 v[6:9], v[160:163], v[210:213], v[6:9]
	v_mfma_f32_16x16x32_bf16 v[2:5], v[168:171], v[210:213], v[2:5]
	v_mfma_f32_16x16x32_bf16 v[54:57], v[164:167], v[180:183], v[54:57]
	v_mfma_f32_16x16x32_bf16 v[46:49], v[172:175], v[180:183], v[46:49]
	v_mfma_f32_16x16x32_bf16 v[38:41], v[164:167], v[188:191], v[38:41]
	v_mfma_f32_16x16x32_bf16 v[30:33], v[172:175], v[188:191], v[30:33]
	v_mfma_f32_16x16x32_bf16 v[22:25], v[164:167], v[206:209], v[22:25]
	v_mfma_f32_16x16x32_bf16 v[14:17], v[172:175], v[206:209], v[14:17]
	v_mfma_f32_16x16x32_bf16 v[6:9], v[164:167], v[214:217], v[6:9]
	v_mfma_f32_16x16x32_bf16 v[2:5], v[172:175], v[214:217], v[2:5]
	s_setprio 0
	s_barrier
	s_add_i32 s24, 0, 0x18000
	s_add_i32 s66, 0, 0x1c000
	v_add_u32_e32 v156, s24, v145
	v_add_u32_e32 v172, s66, v145
	ds_read_b128 v[140:143], v156
	ds_read_b128 v[148:151], v156 offset:1024
	ds_read_b128 v[152:155], v156 offset:2048
	ds_read_b128 v[156:159], v156 offset:3072
	ds_read_b128 v[160:163], v172
	ds_read_b128 v[164:167], v172 offset:1024
	ds_read_b128 v[168:171], v172 offset:2048
	ds_read_b128 v[172:175], v172 offset:3072
	s_add_u32 s0, s62, 0x200000
	s_addc_u32 s1, s63, 0
	s_mov_b32 m0, s85
	v_lshl_add_u64 v[222:223], s[0:1], 0, v[130:131]
	ds_read_b128 v[176:179], v147 offset:32768
	ds_read_b128 v[180:183], v147 offset:33792
	ds_read_b128 v[184:187], v147 offset:34816
	ds_read_b128 v[188:191], v147 offset:35840
	ds_read_b128 v[202:205], v147 offset:36864
	ds_read_b128 v[206:209], v147 offset:37888
	ds_read_b128 v[210:213], v147 offset:38912
	ds_read_b128 v[214:217], v147 offset:39936
	global_load_lds_dwordx4 v[222:223], off
	v_lshl_add_u64 v[222:223], s[0:1], 0, v[132:133]
	s_mov_b32 m0, s88
	s_nop 0
	global_load_lds_dwordx4 v[222:223], off
	s_waitcnt vmcnt(8)
	s_waitcnt lgkmcnt(0)
	s_barrier
	s_setprio 1
	s_waitcnt lgkmcnt(0)
	v_mfma_f32_16x16x32_bf16 v[126:129], v[140:143], v[176:179], v[126:129]
	v_mfma_f32_16x16x32_bf16 v[122:125], v[152:155], v[176:179], v[122:125]
	v_mfma_f32_16x16x32_bf16 v[114:117], v[140:143], v[184:187], v[114:117]
	v_mfma_f32_16x16x32_bf16 v[106:109], v[152:155], v[184:187], v[106:109]
	v_mfma_f32_16x16x32_bf16 v[98:101], v[140:143], v[202:205], v[98:101]
	v_mfma_f32_16x16x32_bf16 v[90:93], v[152:155], v[202:205], v[90:93]
	v_mfma_f32_16x16x32_bf16 v[82:85], v[140:143], v[210:213], v[82:85]
	v_mfma_f32_16x16x32_bf16 v[74:77], v[152:155], v[210:213], v[74:77]
	v_mfma_f32_16x16x32_bf16 v[126:129], v[148:151], v[180:183], v[126:129]
	v_mfma_f32_16x16x32_bf16 v[122:125], v[156:159], v[180:183], v[122:125]
	v_mfma_f32_16x16x32_bf16 v[114:117], v[148:151], v[188:191], v[114:117]
	v_mfma_f32_16x16x32_bf16 v[106:109], v[156:159], v[188:191], v[106:109]
	v_mfma_f32_16x16x32_bf16 v[98:101], v[148:151], v[206:209], v[98:101]
	v_mfma_f32_16x16x32_bf16 v[90:93], v[156:159], v[206:209], v[90:93]
	v_mfma_f32_16x16x32_bf16 v[82:85], v[148:151], v[214:217], v[82:85]
	v_mfma_f32_16x16x32_bf16 v[74:77], v[156:159], v[214:217], v[74:77]
	v_mfma_f32_16x16x32_bf16 v[118:121], v[160:163], v[176:179], v[118:121]
	v_mfma_f32_16x16x32_bf16 v[110:113], v[168:171], v[176:179], v[110:113]
	v_mfma_f32_16x16x32_bf16 v[102:105], v[160:163], v[184:187], v[102:105]
	v_mfma_f32_16x16x32_bf16 v[94:97], v[168:171], v[184:187], v[94:97]
	v_mfma_f32_16x16x32_bf16 v[86:89], v[160:163], v[202:205], v[86:89]
	v_mfma_f32_16x16x32_bf16 v[78:81], v[168:171], v[202:205], v[78:81]
	v_mfma_f32_16x16x32_bf16 v[70:73], v[160:163], v[210:213], v[70:73]
	v_mfma_f32_16x16x32_bf16 v[66:69], v[168:171], v[210:213], v[66:69]
	v_mfma_f32_16x16x32_bf16 v[118:121], v[164:167], v[180:183], v[118:121]
	v_mfma_f32_16x16x32_bf16 v[110:113], v[172:175], v[180:183], v[110:113]
	v_mfma_f32_16x16x32_bf16 v[102:105], v[164:167], v[188:191], v[102:105]
	v_mfma_f32_16x16x32_bf16 v[94:97], v[172:175], v[188:191], v[94:97]
	v_mfma_f32_16x16x32_bf16 v[86:89], v[164:167], v[206:209], v[86:89]
	v_mfma_f32_16x16x32_bf16 v[78:81], v[172:175], v[206:209], v[78:81]
	v_mfma_f32_16x16x32_bf16 v[70:73], v[164:167], v[214:217], v[70:73]
	v_mfma_f32_16x16x32_bf16 v[66:69], v[172:175], v[214:217], v[66:69]
	s_setprio 0
	s_barrier
; #define PG8_STAGE(bufoff, gbase, voff) do { _Pragma("unroll") for (int _i = 0; _i < 2; ++_i) \
;         __builtin_amdgcn_global_load_lds((const unsigned*)((const char*)(gbase) + (voff)[_i]), (LAS unsigned*)(lds + (bufoff) + ldsw + _i * 8192), 16, 0, 0); } while (0)
; #define PG8_LDA(dst, b, h) do { _Pragma("unroll") for (int m = 0; m < 4; ++m) _Pragma("unroll") for (int k = 0; k < 2; ++k) dst[m][k] = *(const LAS bf16x8*)(lds + PG8_SA(b, h) + aoff + m * 2048 + k * 1024); } while (0)
; #define PG8_MMA(ai, bj, At, Bt) do { __builtin_amdgcn_s_setprio(1); _Pragma("unroll") for (int m = 0; m < 4; ++m) _Pragma("unroll") for (int n = 0; n < 2; ++n) _Pragma("unroll") for (int k = 0; k < 2; ++k) \
;         acc[ai][bj][m][n] = __builtin_amdgcn_mfma_f32_16x16x32_bf16(Bt[n][k], At[m][k], acc[ai][bj][m][n], 0, 0, 0); __builtin_amdgcn_s_setprio(0); } while (0)
; #define PG8_WAIT_V(n) asm volatile("s_waitcnt vmcnt(" #n ")" ::: "memory")
; #define PG8_WAIT_L(n) asm volatile("s_waitcnt lgkmcnt(" #n ")" ::: "memory")
; #define PG8_BAR __builtin_amdgcn_s_barrier()
; #define PG8_SCHED __builtin_amdgcn_sched_barrier(0)
; template <class Epi, bool ALIGN_EPI, int M_, int N_, int K_, int LDA, int LDB>
; __device__ __forceinline__ void gemm_phase(LAS unsigned char* lds, const int tid_in, const int G_in, const int bx_in, const Gemm g, const Epi& E) {
;     ...
;             PG8_LDA(At, 1, 1); PG8_STAGE(PG8_SB(1, 0), b3, voffB); PG8_STAGE(PG8_SB(1, 1), b3 + hstepB, voffB); PG8_STAGE(PG8_SA(1, 0), a3, voffA);
;             PG8_WAIT_V(8); PG8_WAIT_L(0); PG8_BAR; PG8_MMA(1, 0, At, B0); PG8_MMA(1, 1, At, B1); PG8_BAR; PG8_SCHED;
;         }
;         if constexpr (ALIGN_EPI) { if (wr == 0) PG8_BAR; }
	s_add_i32 s0, s24, s79
	v_lshl_add_u64 v[192:193], v[192:193], 0, s[54:55]
	s_mov_b32 m0, s0
	ds_read_b128 v[176:179], v147 offset:49152
	ds_read_b128 v[180:183], v147 offset:50176
	ds_read_b128 v[184:187], v147 offset:51200
	ds_read_b128 v[188:191], v147 offset:52224
	ds_read_b128 v[202:205], v147 offset:53248
	ds_read_b128 v[206:209], v147 offset:54272
	ds_read_b128 v[210:213], v147 offset:55296
	ds_read_b128 v[214:217], v147 offset:56320
	global_load_lds_dwordx4 v[192:193], off
	s_add_i32 m0, s0, 0x2000
	s_add_u32 s0, s60, 0x20080
	v_lshl_add_u64 v[192:193], v[200:201], 0, s[54:55]
	s_addc_u32 s1, s61, 0
	s_add_i32 s24, s66, s79
	global_load_lds_dwordx4 v[192:193], off
	v_lshl_add_u64 v[192:193], s[0:1], 0, v[0:1]
	s_mov_b32 m0, s24
	s_nop 0
	global_load_lds_dwordx4 v[192:193], off
	v_lshl_add_u64 v[192:193], s[0:1], 0, v[134:135]
	s_add_i32 m0, s24, 0x2000
	s_nop 0
	global_load_lds_dwordx4 v[192:193], off
	v_lshl_add_u64 v[192:193], v[218:219], 0, s[54:55]
	s_mov_b32 m0, s89
	s_nop 0
	global_load_lds_dwordx4 v[192:193], off
	v_lshl_add_u64 v[192:193], v[220:221], 0, s[54:55]
	s_mov_b32 m0, s90
	s_nop 0
	global_load_lds_dwordx4 v[192:193], off
	s_waitcnt vmcnt(8)
	s_waitcnt lgkmcnt(0)
	s_barrier
	s_setprio 1
	s_waitcnt lgkmcnt(0)
	v_mfma_f32_16x16x32_bf16 v[62:65], v[140:143], v[176:179], v[62:65]
	v_mfma_f32_16x16x32_bf16 v[58:61], v[152:155], v[176:179], v[58:61]
	v_mfma_f32_16x16x32_bf16 v[50:53], v[140:143], v[184:187], v[50:53]
	v_mfma_f32_16x16x32_bf16 v[42:45], v[152:155], v[184:187], v[42:45]
	v_mfma_f32_16x16x32_bf16 v[34:37], v[140:143], v[202:205], v[34:37]
	v_mfma_f32_16x16x32_bf16 v[26:29], v[152:155], v[202:205], v[26:29]
	v_mfma_f32_16x16x32_bf16 v[18:21], v[140:143], v[210:213], v[18:21]
	v_mfma_f32_16x16x32_bf16 v[10:13], v[152:155], v[210:213], v[10:13]
	v_mfma_f32_16x16x32_bf16 v[62:65], v[148:151], v[180:183], v[62:65]
	v_mfma_f32_16x16x32_bf16 v[58:61], v[156:159], v[180:183], v[58:61]
	v_mfma_f32_16x16x32_bf16 v[50:53], v[148:151], v[188:191], v[50:53]
	v_mfma_f32_16x16x32_bf16 v[42:45], v[156:159], v[188:191], v[42:45]
	v_mfma_f32_16x16x32_bf16 v[34:37], v[148:151], v[206:209], v[34:37]
	v_mfma_f32_16x16x32_bf16 v[26:29], v[156:159], v[206:209], v[26:29]
	v_mfma_f32_16x16x32_bf16 v[18:21], v[148:151], v[214:217], v[18:21]
	v_mfma_f32_16x16x32_bf16 v[10:13], v[156:159], v[214:217], v[10:13]
	v_mfma_f32_16x16x32_bf16 v[54:57], v[160:163], v[176:179], v[54:57]
	v_mfma_f32_16x16x32_bf16 v[46:49], v[168:171], v[176:179], v[46:49]
	v_mfma_f32_16x16x32_bf16 v[38:41], v[160:163], v[184:187], v[38:41]
	v_mfma_f32_16x16x32_bf16 v[30:33], v[168:171], v[184:187], v[30:33]
	v_mfma_f32_16x16x32_bf16 v[22:25], v[160:163], v[202:205], v[22:25]
	v_mfma_f32_16x16x32_bf16 v[14:17], v[168:171], v[202:205], v[14:17]
	v_mfma_f32_16x16x32_bf16 v[6:9], v[160:163], v[210:213], v[6:9]
	v_mfma_f32_16x16x32_bf16 v[2:5], v[168:171], v[210:213], v[2:5]
	v_mfma_f32_16x16x32_bf16 v[54:57], v[164:167], v[180:183], v[54:57]
	v_mfma_f32_16x16x32_bf16 v[46:49], v[172:175], v[180:183], v[46:49]
	v_mfma_f32_16x16x32_bf16 v[38:41], v[164:167], v[188:191], v[38:41]
	v_mfma_f32_16x16x32_bf16 v[30:33], v[172:175], v[188:191], v[30:33]
	v_mfma_f32_16x16x32_bf16 v[22:25], v[164:167], v[206:209], v[22:25]
	v_mfma_f32_16x16x32_bf16 v[14:17], v[172:175], v[206:209], v[14:17]
	v_mfma_f32_16x16x32_bf16 v[6:9], v[164:167], v[214:217], v[6:9]
	v_mfma_f32_16x16x32_bf16 v[2:5], v[172:175], v[214:217], v[2:5]
	s_setprio 0
	s_barrier
	s_add_i32 s96, s96, 2
	s_add_u32 s50, s50, 0x100
	s_addc_u32 s51, s51, 0
	s_add_u32 s86, s86, 0x100
	s_addc_u32 s87, s87, 0
	s_cmp_gt_u32 s96, 5
	s_cbranch_scc0 .LBB0_139
	v_readlane_b32 s96, v255, 14
	s_and_b64 vcc, exec, s[38:39]
	v_readlane_b32 s97, v255, 15
	v_readlane_b32 s95, v255, 16
	s_cbranch_vccz .LBB0_142
	s_barrier

; #define PG8_STAGE(bufoff, gbase, voff) do { _Pragma("unroll") for (int _i = 0; _i < 2; ++_i) \
;         __builtin_amdgcn_global_load_lds((const unsigned*)((const char*)(gbase) + (voff)[_i]), (LAS unsigned*)(lds + (bufoff) + ldsw + _i * 8192), 16, 0, 0); } while (0)
; #define PG8_LDA(dst, b, h) do { _Pragma("unroll") for (int m = 0; m < 4; ++m) _Pragma("unroll") for (int k = 0; k < 2; ++k) dst[m][k] = *(const LAS bf16x8*)(lds + PG8_SA(b, h) + aoff + m * 2048 + k * 1024); } while (0)
; #define PG8_LDB(dst, b, h) do { _Pragma("unroll") for (int n = 0; n < 2; ++n) _Pragma("unroll") for (int k = 0; k < 2; ++k) dst[n][k] = *(const LAS bf16x8*)(lds + PG8_SB(b, h) + boff + n * 2048 + k * 1024); } while (0)
; #define PG8_MMA(ai, bj, At, Bt) do { __builtin_amdgcn_s_setprio(1); _Pragma("unroll") for (int m = 0; m < 4; ++m) _Pragma("unroll") for (int n = 0; n < 2; ++n) _Pragma("unroll") for (int k = 0; k < 2; ++k) \
;         acc[ai][bj][m][n] = __builtin_amdgcn_mfma_f32_16x16x32_bf16(Bt[n][k], At[m][k], acc[ai][bj][m][n], 0, 0, 0); __builtin_amdgcn_s_setprio(0); } while (0)
; #define PG8_WAIT_V(n) asm volatile("s_waitcnt vmcnt(" #n ")" ::: "memory")
; #define PG8_WAIT_L(n) asm volatile("s_waitcnt lgkmcnt(" #n ")" ::: "memory")
; #define PG8_BAR __builtin_amdgcn_s_barrier()
; #define PG8_SCHED __builtin_amdgcn_sched_barrier(0)
; template <class Epi, bool ALIGN_EPI, int M_, int N_, int K_, int LDA, int LDB>
; __device__ __forceinline__ void gemm_phase(LAS unsigned char* lds, const int tid_in, const int G_in, const int bx_in, const Gemm g, const Epi& E) {
;     ...
;             const bool last = (t == nt - 2);
;             const char* a1 = cA + (size_t)(t + 1) * kstep;
;             const char* a2 = last ? nA : cA + (size_t)(t + 2) * kstep; const char* b2 = last ? nB : cB + (size_t)(t + 2) * kstep;
;             const char* a3 = a2 + kstep; const char* b3 = b2 + kstep;
;             PG8_LDB(B0, 0, 0); PG8_LDB(B1, 0, 1); PG8_SCHED; PG8_LDA(At, 0, 0); PG8_STAGE(PG8_SA(1, 1), a1 + hstepA, voffA);
;             PG8_WAIT_V(8); PG8_WAIT_L(0); PG8_BAR; PG8_MMA(0, 0, At, B0); PG8_MMA(0, 1, At, B1); PG8_BAR; PG8_SCHED;
;             PG8_LDA(At, 0, 1); PG8_STAGE(PG8_SB(0, 0), b2, voffB); PG8_STAGE(PG8_SB(0, 1), b2 + hstepB, voffB); PG8_STAGE(PG8_SA(0, 0), a2, voffA);
;             PG8_WAIT_V(8); PG8_WAIT_L(0); PG8_BAR; PG8_MMA(1, 0, At, B0); PG8_MMA(1, 1, At, B1); PG8_BAR; PG8_SCHED;
.LBB0_163:
	s_add_u32 s15, s88, s94
	s_addc_u32 s24, s89, s95
	s_add_u32 s40, s15, 0x100
	s_addc_u32 s41, s24, 0
	s_and_b64 s[0:1], s[92:93], exec
	s_cselect_b32 s97, s45, s41
	s_cselect_b32 s96, s85, s40
	s_add_u32 s0, s86, s94
	s_addc_u32 s1, s87, s95
	s_add_u32 s40, s0, 0x100
	s_addc_u32 s41, s1, 0
	s_add_i32 s66, 0, 0x10000
	s_and_b64 s[0:1], s[92:93], exec
	s_cselect_b32 vcc_hi, s43, s41
	s_cselect_b32 vcc_lo, s34, s40
	s_add_i32 s93, 0, 0x14000
	s_add_u32 s62, s15, 0x200080
	s_addc_u32 s63, s24, 0
	s_add_i32 s82, s66, s12
	s_add_i32 m0, s58, 0xc000
	s_add_i32 s13, s58, 0xe000
	s_add_i32 s24, s82, 0x2000
	s_add_u32 s60, vcc_lo, 0x10000
	v_add_u32_e32 v152, s66, v141
	v_add_u32_e32 v168, s93, v141
	s_addc_u32 s61, vcc_hi, 0
	s_add_i32 s1, s93, s12
	ds_read_b128 v[136:139], v152
	ds_read_b128 v[144:147], v152 offset:1024
	ds_read_b128 v[148:151], v152 offset:2048
	ds_read_b128 v[152:155], v152 offset:3072
	ds_read_b128 v[156:159], v168
	ds_read_b128 v[160:163], v168 offset:1024
	ds_read_b128 v[164:167], v168 offset:2048
	ds_read_b128 v[168:171], v168 offset:3072
	s_add_i32 s0, s1, 0x2000
	s_add_i32 s41, 0, 0x18000
	s_add_i32 s75, 0, 0x1c000
	s_add_u32 s94, s96, 0x200000
	s_addc_u32 s95, s97, 0
	s_add_i32 s40, s41, s12
	s_add_i32 s83, s40, 0x2000
	s_add_u32 s92, vcc_lo, 0x10080
	s_addc_u32 s93, vcc_hi, 0
	s_add_i32 s66, s75, s12
	s_add_i32 s15, s66, 0x2000
	v_lshl_add_u64 v[192:193], s[62:63], 0, v[130:131]
	ds_read_b128 v[172:175], v143
	ds_read_b128 v[176:179], v143 offset:1024
	ds_read_b128 v[180:183], v143 offset:2048
	ds_read_b128 v[184:187], v143 offset:3072
	ds_read_b128 v[188:191], v143 offset:4096
	ds_read_b128 v[202:205], v143 offset:5120
	ds_read_b128 v[206:209], v143 offset:6144
	ds_read_b128 v[210:213], v143 offset:7168
	global_load_lds_dwordx4 v[192:193], off
	v_lshl_add_u64 v[192:193], s[62:63], 0, v[132:133]
	s_mov_b32 m0, s13
	s_nop 0
	global_load_lds_dwordx4 v[192:193], off
	s_waitcnt vmcnt(8)
	s_waitcnt lgkmcnt(0)
	s_barrier
	s_setprio 1
	s_waitcnt lgkmcnt(0)
	v_mfma_f32_16x16x32_bf16 v[126:129], v[136:139], v[172:175], v[126:129]
	v_mfma_f32_16x16x32_bf16 v[122:125], v[148:151], v[172:175], v[122:125]
	v_mfma_f32_16x16x32_bf16 v[110:113], v[136:139], v[180:183], v[110:113]
	v_mfma_f32_16x16x32_bf16 v[106:109], v[148:151], v[180:183], v[106:109]
	v_mfma_f32_16x16x32_bf16 v[94:97], v[136:139], v[188:191], v[94:97]
	v_mfma_f32_16x16x32_bf16 v[90:93], v[148:151], v[188:191], v[90:93]
	v_mfma_f32_16x16x32_bf16 v[78:81], v[136:139], v[206:209], v[78:81]
	v_mfma_f32_16x16x32_bf16 v[74:77], v[148:151], v[206:209], v[74:77]
	v_mfma_f32_16x16x32_bf16 v[126:129], v[144:147], v[176:179], v[126:129]
	v_mfma_f32_16x16x32_bf16 v[122:125], v[152:155], v[176:179], v[122:125]
	v_mfma_f32_16x16x32_bf16 v[110:113], v[144:147], v[184:187], v[110:113]
	v_mfma_f32_16x16x32_bf16 v[106:109], v[152:155], v[184:187], v[106:109]
	v_mfma_f32_16x16x32_bf16 v[94:97], v[144:147], v[202:205], v[94:97]
	v_mfma_f32_16x16x32_bf16 v[90:93], v[152:155], v[202:205], v[90:93]
	v_mfma_f32_16x16x32_bf16 v[78:81], v[144:147], v[210:213], v[78:81]
	v_mfma_f32_16x16x32_bf16 v[74:77], v[152:155], v[210:213], v[74:77]
	v_mfma_f32_16x16x32_bf16 v[118:121], v[156:159], v[172:175], v[118:121]
	v_mfma_f32_16x16x32_bf16 v[114:117], v[164:167], v[172:175], v[114:117]
	v_mfma_f32_16x16x32_bf16 v[102:105], v[156:159], v[180:183], v[102:105]
	v_mfma_f32_16x16x32_bf16 v[98:101], v[164:167], v[180:183], v[98:101]
	v_mfma_f32_16x16x32_bf16 v[86:89], v[156:159], v[188:191], v[86:89]
	v_mfma_f32_16x16x32_bf16 v[82:85], v[164:167], v[188:191], v[82:85]
	v_mfma_f32_16x16x32_bf16 v[70:73], v[156:159], v[206:209], v[70:73]
	v_mfma_f32_16x16x32_bf16 v[66:69], v[164:167], v[206:209], v[66:69]
	v_mfma_f32_16x16x32_bf16 v[118:121], v[160:163], v[176:179], v[118:121]
	v_mfma_f32_16x16x32_bf16 v[114:117], v[168:171], v[176:179], v[114:117]
	v_mfma_f32_16x16x32_bf16 v[102:105], v[160:163], v[184:187], v[102:105]
	v_mfma_f32_16x16x32_bf16 v[98:101], v[168:171], v[184:187], v[98:101]
	v_mfma_f32_16x16x32_bf16 v[86:89], v[160:163], v[202:205], v[86:89]
	v_mfma_f32_16x16x32_bf16 v[82:85], v[168:171], v[202:205], v[82:85]
	v_mfma_f32_16x16x32_bf16 v[70:73], v[160:163], v[210:213], v[70:73]
	v_mfma_f32_16x16x32_bf16 v[66:69], v[168:171], v[210:213], v[66:69]
	s_setprio 0
	s_barrier
	s_mov_b32 m0, s82
	v_lshl_add_u64 v[192:193], vcc, 0, v[0:1]
	ds_read_b128 v[172:175], v143 offset:16384
	ds_read_b128 v[176:179], v143 offset:17408
	ds_read_b128 v[180:183], v143 offset:18432
	ds_read_b128 v[184:187], v143 offset:19456
	ds_read_b128 v[188:191], v143 offset:20480
	ds_read_b128 v[202:205], v143 offset:21504
	ds_read_b128 v[206:209], v143 offset:22528
	ds_read_b128 v[210:213], v143 offset:23552
	global_load_lds_dwordx4 v[192:193], off
	v_lshl_add_u64 v[200:201], vcc, 0, v[134:135]
	s_mov_b32 m0, s24
	v_lshl_add_u64 v[214:215], s[60:61], 0, v[0:1]
	global_load_lds_dwordx4 v[200:201], off
	s_mov_b32 m0, s1
	v_lshl_add_u64 v[216:217], s[96:97], 0, v[132:133]
	global_load_lds_dwordx4 v[214:215], off
	v_lshl_add_u64 v[214:215], s[60:61], 0, v[134:135]
	s_mov_b32 m0, s0
	s_nop 0
	global_load_lds_dwordx4 v[214:215], off
	v_lshl_add_u64 v[214:215], s[96:97], 0, v[130:131]
	s_mov_b32 m0, s58
	s_nop 0
	global_load_lds_dwordx4 v[214:215], off
	s_mov_b32 m0, s51
	s_nop 0
	global_load_lds_dwordx4 v[216:217], off
	s_waitcnt vmcnt(8)
	s_waitcnt lgkmcnt(0)
	s_barrier
; #define PG8_STAGE(bufoff, gbase, voff) do { _Pragma("unroll") for (int _i = 0; _i < 2; ++_i) \
;         __builtin_amdgcn_global_load_lds((const unsigned*)((const char*)(gbase) + (voff)[_i]), (LAS unsigned*)(lds + (bufoff) + ldsw + _i * 8192), 16, 0, 0); } while (0)
; #define PG8_LDA(dst, b, h) do { _Pragma("unroll") for (int m = 0; m < 4; ++m) _Pragma("unroll") for (int k = 0; k < 2; ++k) dst[m][k] = *(const LAS bf16x8*)(lds + PG8_SA(b, h) + aoff + m * 2048 + k * 1024); } while (0)
; #define PG8_LDB(dst, b, h) do { _Pragma("unroll") for (int n = 0; n < 2; ++n) _Pragma("unroll") for (int k = 0; k < 2; ++k) dst[n][k] = *(const LAS bf16x8*)(lds + PG8_SB(b, h) + boff + n * 2048 + k * 1024); } while (0)
; #define PG8_MMA(ai, bj, At, Bt) do { __builtin_amdgcn_s_setprio(1); _Pragma("unroll") for (int m = 0; m < 4; ++m) _Pragma("unroll") for (int n = 0; n < 2; ++n) _Pragma("unroll") for (int k = 0; k < 2; ++k) \
;         acc[ai][bj][m][n] = __builtin_amdgcn_mfma_f32_16x16x32_bf16(Bt[n][k], At[m][k], acc[ai][bj][m][n], 0, 0, 0); __builtin_amdgcn_s_setprio(0); } while (0)
; #define PG8_WAIT_V(n) asm volatile("s_waitcnt vmcnt(" #n ")" ::: "memory")
; #define PG8_WAIT_L(n) asm volatile("s_waitcnt lgkmcnt(" #n ")" ::: "memory")
; #define PG8_BAR __builtin_amdgcn_s_barrier()
; #define PG8_SCHED __builtin_amdgcn_sched_barrier(0)
; template <class Epi, bool ALIGN_EPI, int M_, int N_, int K_, int LDA, int LDB>
; __device__ __forceinline__ void gemm_phase(LAS unsigned char* lds, const int tid_in, const int G_in, const int bx_in, const Gemm g, const Epi& E) {
;     ...
;             PG8_WAIT_V(8); PG8_WAIT_L(0); PG8_BAR; PG8_MMA(1, 0, At, B0); PG8_MMA(1, 1, At, B1); PG8_BAR; PG8_SCHED;
;             PG8_LDB(B0, 1, 0); PG8_LDB(B1, 1, 1); PG8_SCHED; PG8_LDA(At, 1, 0); PG8_STAGE(PG8_SA(0, 1), a2 + hstepA, voffA);
;             PG8_WAIT_V(8); PG8_WAIT_L(0); PG8_BAR; PG8_MMA(0, 0, At, B0); PG8_MMA(0, 1, At, B1); PG8_BAR; PG8_SCHED;
	s_setprio 1
	s_waitcnt lgkmcnt(0)
	v_mfma_f32_16x16x32_bf16 v[62:65], v[136:139], v[172:175], v[62:65]
	v_mfma_f32_16x16x32_bf16 v[58:61], v[148:151], v[172:175], v[58:61]
	v_mfma_f32_16x16x32_bf16 v[46:49], v[136:139], v[180:183], v[46:49]
	v_mfma_f32_16x16x32_bf16 v[42:45], v[148:151], v[180:183], v[42:45]
	v_mfma_f32_16x16x32_bf16 v[30:33], v[136:139], v[188:191], v[30:33]
	v_mfma_f32_16x16x32_bf16 v[26:29], v[148:151], v[188:191], v[26:29]
	v_mfma_f32_16x16x32_bf16 v[14:17], v[136:139], v[206:209], v[14:17]
	v_mfma_f32_16x16x32_bf16 v[10:13], v[148:151], v[206:209], v[10:13]
	v_mfma_f32_16x16x32_bf16 v[62:65], v[144:147], v[176:179], v[62:65]
	v_mfma_f32_16x16x32_bf16 v[58:61], v[152:155], v[176:179], v[58:61]
	v_mfma_f32_16x16x32_bf16 v[46:49], v[144:147], v[184:187], v[46:49]
	v_mfma_f32_16x16x32_bf16 v[42:45], v[152:155], v[184:187], v[42:45]
	v_mfma_f32_16x16x32_bf16 v[30:33], v[144:147], v[202:205], v[30:33]
	v_mfma_f32_16x16x32_bf16 v[26:29], v[152:155], v[202:205], v[26:29]
	v_mfma_f32_16x16x32_bf16 v[14:17], v[144:147], v[210:213], v[14:17]
	v_mfma_f32_16x16x32_bf16 v[10:13], v[152:155], v[210:213], v[10:13]
	v_mfma_f32_16x16x32_bf16 v[54:57], v[156:159], v[172:175], v[54:57]
	v_mfma_f32_16x16x32_bf16 v[50:53], v[164:167], v[172:175], v[50:53]
	v_mfma_f32_16x16x32_bf16 v[38:41], v[156:159], v[180:183], v[38:41]
	v_mfma_f32_16x16x32_bf16 v[34:37], v[164:167], v[180:183], v[34:37]
	v_mfma_f32_16x16x32_bf16 v[22:25], v[156:159], v[188:191], v[22:25]
	v_mfma_f32_16x16x32_bf16 v[18:21], v[164:167], v[188:191], v[18:21]
	v_mfma_f32_16x16x32_bf16 v[6:9], v[156:159], v[206:209], v[6:9]
	v_mfma_f32_16x16x32_bf16 v[2:5], v[164:167], v[206:209], v[2:5]
	v_mfma_f32_16x16x32_bf16 v[54:57], v[160:163], v[176:179], v[54:57]
	v_mfma_f32_16x16x32_bf16 v[50:53], v[168:171], v[176:179], v[50:53]
	v_mfma_f32_16x16x32_bf16 v[38:41], v[160:163], v[184:187], v[38:41]
	v_mfma_f32_16x16x32_bf16 v[34:37], v[168:171], v[184:187], v[34:37]
	v_mfma_f32_16x16x32_bf16 v[22:25], v[160:163], v[202:205], v[22:25]
	v_mfma_f32_16x16x32_bf16 v[18:21], v[168:171], v[202:205], v[18:21]
	v_mfma_f32_16x16x32_bf16 v[6:9], v[160:163], v[210:213], v[6:9]
	v_mfma_f32_16x16x32_bf16 v[2:5], v[168:171], v[210:213], v[2:5]
	s_setprio 0
	s_barrier
	v_add_u32_e32 v152, s41, v141
	v_add_u32_e32 v168, s75, v141
	ds_read_b128 v[136:139], v152
	ds_read_b128 v[144:147], v152 offset:1024
	ds_read_b128 v[148:151], v152 offset:2048
	ds_read_b128 v[152:155], v152 offset:3072
	ds_read_b128 v[156:159], v168
	ds_read_b128 v[160:163], v168 offset:1024
	ds_read_b128 v[164:167], v168 offset:2048
	ds_read_b128 v[168:171], v168 offset:3072
	s_mov_b32 m0, s8
	v_lshl_add_u64 v[218:219], s[94:95], 0, v[130:131]
	ds_read_b128 v[172:175], v143 offset:32768
	ds_read_b128 v[176:179], v143 offset:33792
	ds_read_b128 v[180:183], v143 offset:34816
	ds_read_b128 v[184:187], v143 offset:35840
	ds_read_b128 v[188:191], v143 offset:36864
	ds_read_b128 v[202:205], v143 offset:37888
	ds_read_b128 v[206:209], v143 offset:38912
	ds_read_b128 v[210:213], v143 offset:39936
	global_load_lds_dwordx4 v[218:219], off
	v_lshl_add_u64 v[218:219], s[94:95], 0, v[132:133]
	s_mov_b32 m0, s9
	s_nop 0
	global_load_lds_dwordx4 v[218:219], off
	s_waitcnt vmcnt(8)
	s_waitcnt lgkmcnt(0)
	s_barrier
	s_setprio 1
	s_waitcnt lgkmcnt(0)
	v_mfma_f32_16x16x32_bf16 v[126:129], v[136:139], v[172:175], v[126:129]
	v_mfma_f32_16x16x32_bf16 v[122:125], v[148:151], v[172:175], v[122:125]
	v_mfma_f32_16x16x32_bf16 v[110:113], v[136:139], v[180:183], v[110:113]
	v_mfma_f32_16x16x32_bf16 v[106:109], v[148:151], v[180:183], v[106:109]
	v_mfma_f32_16x16x32_bf16 v[94:97], v[136:139], v[188:191], v[94:97]
	v_mfma_f32_16x16x32_bf16 v[90:93], v[148:151], v[188:191], v[90:93]
	v_mfma_f32_16x16x32_bf16 v[78:81], v[136:139], v[206:209], v[78:81]
	v_mfma_f32_16x16x32_bf16 v[74:77], v[148:151], v[206:209], v[74:77]
	v_mfma_f32_16x16x32_bf16 v[126:129], v[144:147], v[176:179], v[126:129]
	v_mfma_f32_16x16x32_bf16 v[122:125], v[152:155], v[176:179], v[122:125]
	v_mfma_f32_16x16x32_bf16 v[110:113], v[144:147], v[184:187], v[110:113]
	v_mfma_f32_16x16x32_bf16 v[106:109], v[152:155], v[184:187], v[106:109]
	v_mfma_f32_16x16x32_bf16 v[94:97], v[144:147], v[202:205], v[94:97]
	v_mfma_f32_16x16x32_bf16 v[90:93], v[152:155], v[202:205], v[90:93]
	v_mfma_f32_16x16x32_bf16 v[78:81], v[144:147], v[210:213], v[78:81]
	v_mfma_f32_16x16x32_bf16 v[74:77], v[152:155], v[210:213], v[74:77]
	v_mfma_f32_16x16x32_bf16 v[118:121], v[156:159], v[172:175], v[118:121]
	v_mfma_f32_16x16x32_bf16 v[114:117], v[164:167], v[172:175], v[114:117]
	v_mfma_f32_16x16x32_bf16 v[102:105], v[156:159], v[180:183], v[102:105]
	v_mfma_f32_16x16x32_bf16 v[98:101], v[164:167], v[180:183], v[98:101]
	v_mfma_f32_16x16x32_bf16 v[86:89], v[156:159], v[188:191], v[86:89]
	v_mfma_f32_16x16x32_bf16 v[82:85], v[164:167], v[188:191], v[82:85]
	v_mfma_f32_16x16x32_bf16 v[70:73], v[156:159], v[206:209], v[70:73]
	v_mfma_f32_16x16x32_bf16 v[66:69], v[164:167], v[206:209], v[66:69]
	v_mfma_f32_16x16x32_bf16 v[118:121], v[160:163], v[176:179], v[118:121]
	v_mfma_f32_16x16x32_bf16 v[114:117], v[168:171], v[176:179], v[114:117]
	v_mfma_f32_16x16x32_bf16 v[102:105], v[160:163], v[184:187], v[102:105]
	v_mfma_f32_16x16x32_bf16 v[98:101], v[168:171], v[184:187], v[98:101]
	v_mfma_f32_16x16x32_bf16 v[86:89], v[160:163], v[202:205], v[86:89]
	v_mfma_f32_16x16x32_bf16 v[82:85], v[168:171], v[202:205], v[82:85]
	v_mfma_f32_16x16x32_bf16 v[70:73], v[160:163], v[210:213], v[70:73]
	v_mfma_f32_16x16x32_bf16 v[66:69], v[168:171], v[210:213], v[66:69]
	s_setprio 0
	s_barrier
; #define PG8_STAGE(bufoff, gbase, voff) do { _Pragma("unroll") for (int _i = 0; _i < 2; ++_i) \
;         __builtin_amdgcn_global_load_lds((const unsigned*)((const char*)(gbase) + (voff)[_i]), (LAS unsigned*)(lds + (bufoff) + ldsw + _i * 8192), 16, 0, 0); } while (0)
; #define PG8_LDA(dst, b, h) do { _Pragma("unroll") for (int m = 0; m < 4; ++m) _Pragma("unroll") for (int k = 0; k < 2; ++k) dst[m][k] = *(const LAS bf16x8*)(lds + PG8_SA(b, h) + aoff + m * 2048 + k * 1024); } while (0)
; #define PG8_MMA(ai, bj, At, Bt) do { __builtin_amdgcn_s_setprio(1); _Pragma("unroll") for (int m = 0; m < 4; ++m) _Pragma("unroll") for (int n = 0; n < 2; ++n) _Pragma("unroll") for (int k = 0; k < 2; ++k) \
;         acc[ai][bj][m][n] = __builtin_amdgcn_mfma_f32_16x16x32_bf16(Bt[n][k], At[m][k], acc[ai][bj][m][n], 0, 0, 0); __builtin_amdgcn_s_setprio(0); } while (0)
; #define PG8_WAIT_V(n) asm volatile("s_waitcnt vmcnt(" #n ")" ::: "memory")
; #define PG8_WAIT_L(n) asm volatile("s_waitcnt lgkmcnt(" #n ")" ::: "memory")
; #define PG8_BAR __builtin_amdgcn_s_barrier()
; #define PG8_SCHED __builtin_amdgcn_sched_barrier(0)
; template <class Epi, bool ALIGN_EPI, int M_, int N_, int K_, int LDA, int LDB>
; __device__ __forceinline__ void gemm_phase(LAS unsigned char* lds, const int tid_in, const int G_in, const int bx_in, const Gemm g, const Epi& E) {
;     ...
;             PG8_LDA(At, 1, 1); PG8_STAGE(PG8_SB(1, 0), b3, voffB); PG8_STAGE(PG8_SB(1, 1), b3 + hstepB, voffB); PG8_STAGE(PG8_SA(1, 0), a3, voffA);
;             PG8_WAIT_V(8); PG8_WAIT_L(0); PG8_BAR; PG8_MMA(1, 0, At, B0); PG8_MMA(1, 1, At, B1); PG8_BAR; PG8_SCHED;
;         }
;         if constexpr (ALIGN_EPI) { if (wr == 0) PG8_BAR; }
	s_mov_b32 m0, s40
	v_lshl_add_u64 v[192:193], v[192:193], 0, s[54:55]
	ds_read_b128 v[172:175], v143 offset:49152
	ds_read_b128 v[176:179], v143 offset:50176
	ds_read_b128 v[180:183], v143 offset:51200
	ds_read_b128 v[184:187], v143 offset:52224
	ds_read_b128 v[188:191], v143 offset:53248
	ds_read_b128 v[202:205], v143 offset:54272
	ds_read_b128 v[206:209], v143 offset:55296
	ds_read_b128 v[210:213], v143 offset:56320
	global_load_lds_dwordx4 v[192:193], off
	v_lshl_add_u64 v[192:193], v[200:201], 0, s[54:55]
	s_mov_b32 m0, s83
	s_nop 0
	global_load_lds_dwordx4 v[192:193], off
	v_lshl_add_u64 v[192:193], s[92:93], 0, v[0:1]
	s_mov_b32 m0, s66
	s_nop 0
	global_load_lds_dwordx4 v[192:193], off
	v_lshl_add_u64 v[192:193], s[92:93], 0, v[134:135]
	s_mov_b32 m0, s15
	s_nop 0
	global_load_lds_dwordx4 v[192:193], off
	v_lshl_add_u64 v[192:193], v[214:215], 0, s[54:55]
	s_mov_b32 m0, s77
	s_nop 0
	global_load_lds_dwordx4 v[192:193], off
	v_lshl_add_u64 v[192:193], v[216:217], 0, s[54:55]
	s_mov_b32 m0, s78
	s_nop 0
	global_load_lds_dwordx4 v[192:193], off
	s_waitcnt vmcnt(8)
	s_waitcnt lgkmcnt(0)
	s_barrier
	s_setprio 1
	s_waitcnt lgkmcnt(0)
	v_mfma_f32_16x16x32_bf16 v[62:65], v[136:139], v[172:175], v[62:65]
	v_mfma_f32_16x16x32_bf16 v[58:61], v[148:151], v[172:175], v[58:61]
	v_mfma_f32_16x16x32_bf16 v[46:49], v[136:139], v[180:183], v[46:49]
	v_mfma_f32_16x16x32_bf16 v[42:45], v[148:151], v[180:183], v[42:45]
	v_mfma_f32_16x16x32_bf16 v[30:33], v[136:139], v[188:191], v[30:33]
	v_mfma_f32_16x16x32_bf16 v[26:29], v[148:151], v[188:191], v[26:29]
	v_mfma_f32_16x16x32_bf16 v[14:17], v[136:139], v[206:209], v[14:17]
	v_mfma_f32_16x16x32_bf16 v[10:13], v[148:151], v[206:209], v[10:13]
	v_mfma_f32_16x16x32_bf16 v[62:65], v[144:147], v[176:179], v[62:65]
	v_mfma_f32_16x16x32_bf16 v[58:61], v[152:155], v[176:179], v[58:61]
	v_mfma_f32_16x16x32_bf16 v[46:49], v[144:147], v[184:187], v[46:49]
	v_mfma_f32_16x16x32_bf16 v[42:45], v[152:155], v[184:187], v[42:45]
	v_mfma_f32_16x16x32_bf16 v[30:33], v[144:147], v[202:205], v[30:33]
	v_mfma_f32_16x16x32_bf16 v[26:29], v[152:155], v[202:205], v[26:29]
	v_mfma_f32_16x16x32_bf16 v[14:17], v[144:147], v[210:213], v[14:17]
	v_mfma_f32_16x16x32_bf16 v[10:13], v[152:155], v[210:213], v[10:13]
	v_mfma_f32_16x16x32_bf16 v[54:57], v[156:159], v[172:175], v[54:57]
	v_mfma_f32_16x16x32_bf16 v[50:53], v[164:167], v[172:175], v[50:53]
	v_mfma_f32_16x16x32_bf16 v[38:41], v[156:159], v[180:183], v[38:41]
	v_mfma_f32_16x16x32_bf16 v[34:37], v[164:167], v[180:183], v[34:37]
	v_mfma_f32_16x16x32_bf16 v[22:25], v[156:159], v[188:191], v[22:25]
	v_mfma_f32_16x16x32_bf16 v[18:21], v[164:167], v[188:191], v[18:21]
	v_mfma_f32_16x16x32_bf16 v[6:9], v[156:159], v[206:209], v[6:9]
	v_mfma_f32_16x16x32_bf16 v[2:5], v[164:167], v[206:209], v[2:5]
	v_mfma_f32_16x16x32_bf16 v[54:57], v[160:163], v[176:179], v[54:57]
	v_mfma_f32_16x16x32_bf16 v[50:53], v[168:171], v[176:179], v[50:53]
	v_mfma_f32_16x16x32_bf16 v[38:41], v[160:163], v[184:187], v[38:41]
	v_mfma_f32_16x16x32_bf16 v[34:37], v[168:171], v[184:187], v[34:37]
	v_mfma_f32_16x16x32_bf16 v[22:25], v[160:163], v[202:205], v[22:25]
	v_mfma_f32_16x16x32_bf16 v[18:21], v[168:171], v[202:205], v[18:21]
	v_mfma_f32_16x16x32_bf16 v[6:9], v[160:163], v[210:213], v[6:9]
	v_mfma_f32_16x16x32_bf16 v[2:5], v[168:171], v[210:213], v[2:5]
	s_setprio 0
	s_barrier
	s_andn2_b64 vcc, exec, s[90:91]
	s_mov_b64 s[92:93], -1
	s_mov_b64 s[90:91], 0
	s_mov_b64 s[94:95], 0x100
	s_cbranch_vccz .LBB0_163
	v_readlane_b32 s0, v255, 40
	v_readlane_b32 s1, v255, 41
	s_and_b64 vcc, exec, s[0:1]
	v_readlane_b32 s95, v255, 16
	s_cbranch_vccz .LBB0_166
	s_barrier

; #define PG8_STAGE(bufoff, gbase, voff) do { _Pragma("unroll") for (int _i = 0; _i < 2; ++_i) \
;         __builtin_amdgcn_global_load_lds((const unsigned*)((const char*)(gbase) + (voff)[_i]), (LAS unsigned*)(lds + (bufoff) + ldsw + _i * 8192), 16, 0, 0); } while (0)
; #define PG8_LDA(dst, b, h) do { _Pragma("unroll") for (int m = 0; m < 4; ++m) _Pragma("unroll") for (int k = 0; k < 2; ++k) dst[m][k] = *(const LAS bf16x8*)(lds + PG8_SA(b, h) + aoff + m * 2048 + k * 1024); } while (0)
; #define PG8_LDB(dst, b, h) do { _Pragma("unroll") for (int n = 0; n < 2; ++n) _Pragma("unroll") for (int k = 0; k < 2; ++k) dst[n][k] = *(const LAS bf16x8*)(lds + PG8_SB(b, h) + boff + n * 2048 + k * 1024); } while (0)
; #define PG8_MMA(ai, bj, At, Bt) do { __builtin_amdgcn_s_setprio(1); _Pragma("unroll") for (int m = 0; m < 4; ++m) _Pragma("unroll") for (int n = 0; n < 2; ++n) _Pragma("unroll") for (int k = 0; k < 2; ++k) \
;         acc[ai][bj][m][n] = __builtin_amdgcn_mfma_f32_16x16x32_bf16(Bt[n][k], At[m][k], acc[ai][bj][m][n], 0, 0, 0); __builtin_amdgcn_s_setprio(0); } while (0)
; #define PG8_WAIT_V(n) asm volatile("s_waitcnt vmcnt(" #n ")" ::: "memory")
; #define PG8_WAIT_L(n) asm volatile("s_waitcnt lgkmcnt(" #n ")" ::: "memory")
; #define PG8_BAR __builtin_amdgcn_s_barrier()
; #define PG8_SCHED __builtin_amdgcn_sched_barrier(0)
; template <class Epi, bool ALIGN_EPI, int M_, int N_, int K_, int LDA, int LDB>
; __device__ __forceinline__ void gemm_phase(LAS unsigned char* lds, const int tid_in, const int G_in, const int bx_in, const Gemm g, const Epi& E) {
;     ...
;             const bool last = (t == nt - 2);
;             const char* a1 = cA + (size_t)(t + 1) * kstep;
;             const char* a2 = last ? nA : cA + (size_t)(t + 2) * kstep; const char* b2 = last ? nB : cB + (size_t)(t + 2) * kstep;
;             const char* a3 = a2 + kstep; const char* b3 = b2 + kstep;
;             PG8_LDB(B0, 0, 0); PG8_LDB(B1, 0, 1); PG8_SCHED; PG8_LDA(At, 0, 0); PG8_STAGE(PG8_SA(1, 1), a1 + hstepA, voffA);
;             PG8_WAIT_V(8); PG8_WAIT_L(0); PG8_BAR; PG8_MMA(0, 0, At, B0); PG8_MMA(0, 1, At, B1); PG8_BAR; PG8_SCHED;
;             PG8_LDA(At, 0, 1); PG8_STAGE(PG8_SB(0, 0), b2, voffB); PG8_STAGE(PG8_SB(0, 1), b2 + hstepB, voffB); PG8_STAGE(PG8_SA(0, 0), a2, voffA);
;             PG8_WAIT_V(8); PG8_WAIT_L(0); PG8_BAR; PG8_MMA(1, 0, At, B0); PG8_MMA(1, 1, At, B1); PG8_BAR; PG8_SCHED;
.LBB0_189:
	s_add_u32 s8, s50, 0x100
	s_addc_u32 s9, s51, 0
	s_add_i32 s0, 0, 0x10000
	s_cmp_eq_u32 vcc_lo, 4
	s_cselect_b32 s63, s47, s9
	s_cselect_b32 s62, s46, s8
	s_cselect_b32 s61, s45, s87
	s_cselect_b32 s60, s97, s86
	s_add_i32 s24, 0, 0x14000
	v_add_u32_e32 v156, s0, v145
	v_add_u32_e32 v172, s24, v145
	ds_read_b128 v[140:143], v156
	ds_read_b128 v[148:151], v156 offset:1024
	ds_read_b128 v[152:155], v156 offset:2048
	ds_read_b128 v[156:159], v156 offset:3072
	ds_read_b128 v[160:163], v172
	ds_read_b128 v[164:167], v172 offset:1024
	ds_read_b128 v[168:171], v172 offset:2048
	ds_read_b128 v[172:175], v172 offset:3072
	v_lshl_add_u64 v[192:193], s[50:51], 0, v[136:137]
	s_add_i32 m0, s84, 0xc000
	ds_read_b128 v[176:179], v147
	ds_read_b128 v[180:183], v147 offset:1024
	ds_read_b128 v[184:187], v147 offset:2048
	ds_read_b128 v[188:191], v147 offset:3072
	ds_read_b128 v[202:205], v147 offset:4096
	ds_read_b128 v[206:209], v147 offset:5120
	ds_read_b128 v[210:213], v147 offset:6144
	ds_read_b128 v[214:217], v147 offset:7168
	global_load_lds_dwordx4 v[192:193], off
	v_lshl_add_u64 v[192:193], s[50:51], 0, v[138:139]
	s_add_i32 m0, s84, 0xe000
	s_nop 0
	global_load_lds_dwordx4 v[192:193], off
	s_waitcnt vmcnt(8)
	s_waitcnt lgkmcnt(0)
	s_barrier
	s_setprio 1
	s_waitcnt lgkmcnt(0)
	v_mfma_f32_16x16x32_bf16 v[126:129], v[140:143], v[176:179], v[126:129]
	v_mfma_f32_16x16x32_bf16 v[122:125], v[152:155], v[176:179], v[122:125]
	v_mfma_f32_16x16x32_bf16 v[110:113], v[140:143], v[184:187], v[110:113]
	v_mfma_f32_16x16x32_bf16 v[106:109], v[152:155], v[184:187], v[106:109]
	v_mfma_f32_16x16x32_bf16 v[94:97], v[140:143], v[202:205], v[94:97]
	v_mfma_f32_16x16x32_bf16 v[90:93], v[152:155], v[202:205], v[90:93]
	v_mfma_f32_16x16x32_bf16 v[78:81], v[140:143], v[210:213], v[78:81]
	v_mfma_f32_16x16x32_bf16 v[74:77], v[152:155], v[210:213], v[74:77]
	v_mfma_f32_16x16x32_bf16 v[126:129], v[148:151], v[180:183], v[126:129]
	v_mfma_f32_16x16x32_bf16 v[122:125], v[156:159], v[180:183], v[122:125]
	v_mfma_f32_16x16x32_bf16 v[110:113], v[148:151], v[188:191], v[110:113]
	v_mfma_f32_16x16x32_bf16 v[106:109], v[156:159], v[188:191], v[106:109]
	v_mfma_f32_16x16x32_bf16 v[94:97], v[148:151], v[206:209], v[94:97]
	v_mfma_f32_16x16x32_bf16 v[90:93], v[156:159], v[206:209], v[90:93]
	v_mfma_f32_16x16x32_bf16 v[78:81], v[148:151], v[214:217], v[78:81]
	v_mfma_f32_16x16x32_bf16 v[74:77], v[156:159], v[214:217], v[74:77]
	v_mfma_f32_16x16x32_bf16 v[118:121], v[160:163], v[176:179], v[118:121]
	v_mfma_f32_16x16x32_bf16 v[114:117], v[168:171], v[176:179], v[114:117]
	v_mfma_f32_16x16x32_bf16 v[102:105], v[160:163], v[184:187], v[102:105]
	v_mfma_f32_16x16x32_bf16 v[98:101], v[168:171], v[184:187], v[98:101]
	v_mfma_f32_16x16x32_bf16 v[86:89], v[160:163], v[202:205], v[86:89]
	v_mfma_f32_16x16x32_bf16 v[82:85], v[168:171], v[202:205], v[82:85]
	v_mfma_f32_16x16x32_bf16 v[70:73], v[160:163], v[210:213], v[70:73]
	v_mfma_f32_16x16x32_bf16 v[66:69], v[168:171], v[210:213], v[66:69]
	v_mfma_f32_16x16x32_bf16 v[118:121], v[164:167], v[180:183], v[118:121]
	v_mfma_f32_16x16x32_bf16 v[114:117], v[172:175], v[180:183], v[114:117]
	v_mfma_f32_16x16x32_bf16 v[102:105], v[164:167], v[188:191], v[102:105]
	v_mfma_f32_16x16x32_bf16 v[98:101], v[172:175], v[188:191], v[98:101]
	v_mfma_f32_16x16x32_bf16 v[86:89], v[164:167], v[206:209], v[86:89]
	v_mfma_f32_16x16x32_bf16 v[82:85], v[172:175], v[206:209], v[82:85]
	v_mfma_f32_16x16x32_bf16 v[70:73], v[164:167], v[214:217], v[70:73]
	v_mfma_f32_16x16x32_bf16 v[66:69], v[172:175], v[214:217], v[66:69]
	s_setprio 0
	s_barrier
	s_add_i32 s0, s0, s89
	v_lshl_add_u64 v[192:193], s[60:61], 0, v[0:1]
	s_mov_b32 m0, s0
	ds_read_b128 v[176:179], v147 offset:16384
	ds_read_b128 v[180:183], v147 offset:17408
	ds_read_b128 v[184:187], v147 offset:18432
	ds_read_b128 v[188:191], v147 offset:19456
	ds_read_b128 v[202:205], v147 offset:20480
	ds_read_b128 v[206:209], v147 offset:21504
	ds_read_b128 v[210:213], v147 offset:22528
	ds_read_b128 v[214:217], v147 offset:23552
	global_load_lds_dwordx4 v[192:193], off
	s_add_i32 m0, s0, 0x2000
	s_add_u32 s0, s60, 0x20000
	v_lshl_add_u64 v[200:201], s[60:61], 0, v[134:135]
	s_addc_u32 s1, s61, 0
	s_add_i32 s24, s24, s89
	global_load_lds_dwordx4 v[200:201], off
	v_lshl_add_u64 v[218:219], s[0:1], 0, v[0:1]
	s_mov_b32 m0, s24
	v_lshl_add_u64 v[220:221], s[62:63], 0, v[132:133]
	global_load_lds_dwordx4 v[218:219], off
	v_lshl_add_u64 v[218:219], s[0:1], 0, v[134:135]
	s_add_i32 m0, s24, 0x2000
	s_nop 0
	global_load_lds_dwordx4 v[218:219], off
	v_lshl_add_u64 v[218:219], s[62:63], 0, v[130:131]
	s_mov_b32 m0, s84
	s_nop 0
	global_load_lds_dwordx4 v[218:219], off
	s_mov_b32 m0, s85
	s_nop 0
	global_load_lds_dwordx4 v[220:221], off
	s_waitcnt vmcnt(8)
	s_waitcnt lgkmcnt(0)
	s_barrier
; #define PG8_STAGE(bufoff, gbase, voff) do { _Pragma("unroll") for (int _i = 0; _i < 2; ++_i) \
;         __builtin_amdgcn_global_load_lds((const unsigned*)((const char*)(gbase) + (voff)[_i]), (LAS unsigned*)(lds + (bufoff) + ldsw + _i * 8192), 16, 0, 0); } while (0)
; #define PG8_LDA(dst, b, h) do { _Pragma("unroll") for (int m = 0; m < 4; ++m) _Pragma("unroll") for (int k = 0; k < 2; ++k) dst[m][k] = *(const LAS bf16x8*)(lds + PG8_SA(b, h) + aoff + m * 2048 + k * 1024); } while (0)
; #define PG8_LDB(dst, b, h) do { _Pragma("unroll") for (int n = 0; n < 2; ++n) _Pragma("unroll") for (int k = 0; k < 2; ++k) dst[n][k] = *(const LAS bf16x8*)(lds + PG8_SB(b, h) + boff + n * 2048 + k * 1024); } while (0)
; #define PG8_MMA(ai, bj, At, Bt) do { __builtin_amdgcn_s_setprio(1); _Pragma("unroll") for (int m = 0; m < 4; ++m) _Pragma("unroll") for (int n = 0; n < 2; ++n) _Pragma("unroll") for (int k = 0; k < 2; ++k) \
;         acc[ai][bj][m][n] = __builtin_amdgcn_mfma_f32_16x16x32_bf16(Bt[n][k], At[m][k], acc[ai][bj][m][n], 0, 0, 0); __builtin_amdgcn_s_setprio(0); } while (0)
; #define PG8_WAIT_V(n) asm volatile("s_waitcnt vmcnt(" #n ")" ::: "memory")
; #define PG8_WAIT_L(n) asm volatile("s_waitcnt lgkmcnt(" #n ")" ::: "memory")
; #define PG8_BAR __builtin_amdgcn_s_barrier()
; #define PG8_SCHED __builtin_amdgcn_sched_barrier(0)
; template <class Epi, bool ALIGN_EPI, int M_, int N_, int K_, int LDA, int LDB>
; __device__ __forceinline__ void gemm_phase(LAS unsigned char* lds, const int tid_in, const int G_in, const int bx_in, const Gemm g, const Epi& E) {
;     ...
;             PG8_WAIT_V(8); PG8_WAIT_L(0); PG8_BAR; PG8_MMA(1, 0, At, B0); PG8_MMA(1, 1, At, B1); PG8_BAR; PG8_SCHED;
;             PG8_LDB(B0, 1, 0); PG8_LDB(B1, 1, 1); PG8_SCHED; PG8_LDA(At, 1, 0); PG8_STAGE(PG8_SA(0, 1), a2 + hstepA, voffA);
;             PG8_WAIT_V(8); PG8_WAIT_L(0); PG8_BAR; PG8_MMA(0, 0, At, B0); PG8_MMA(0, 1, At, B1); PG8_BAR; PG8_SCHED;
	s_setprio 1
	s_waitcnt lgkmcnt(0)
	v_mfma_f32_16x16x32_bf16 v[62:65], v[140:143], v[176:179], v[62:65]
	v_mfma_f32_16x16x32_bf16 v[58:61], v[152:155], v[176:179], v[58:61]
	v_mfma_f32_16x16x32_bf16 v[46:49], v[140:143], v[184:187], v[46:49]
	v_mfma_f32_16x16x32_bf16 v[42:45], v[152:155], v[184:187], v[42:45]
	v_mfma_f32_16x16x32_bf16 v[30:33], v[140:143], v[202:205], v[30:33]
	v_mfma_f32_16x16x32_bf16 v[26:29], v[152:155], v[202:205], v[26:29]
	v_mfma_f32_16x16x32_bf16 v[14:17], v[140:143], v[210:213], v[14:17]
	v_mfma_f32_16x16x32_bf16 v[10:13], v[152:155], v[210:213], v[10:13]
	v_mfma_f32_16x16x32_bf16 v[62:65], v[148:151], v[180:183], v[62:65]
	v_mfma_f32_16x16x32_bf16 v[58:61], v[156:159], v[180:183], v[58:61]
	v_mfma_f32_16x16x32_bf16 v[46:49], v[148:151], v[188:191], v[46:49]
	v_mfma_f32_16x16x32_bf16 v[42:45], v[156:159], v[188:191], v[42:45]
	v_mfma_f32_16x16x32_bf16 v[30:33], v[148:151], v[206:209], v[30:33]
	v_mfma_f32_16x16x32_bf16 v[26:29], v[156:159], v[206:209], v[26:29]
	v_mfma_f32_16x16x32_bf16 v[14:17], v[148:151], v[214:217], v[14:17]
	v_mfma_f32_16x16x32_bf16 v[10:13], v[156:159], v[214:217], v[10:13]
	v_mfma_f32_16x16x32_bf16 v[54:57], v[160:163], v[176:179], v[54:57]
	v_mfma_f32_16x16x32_bf16 v[50:53], v[168:171], v[176:179], v[50:53]
	v_mfma_f32_16x16x32_bf16 v[38:41], v[160:163], v[184:187], v[38:41]
	v_mfma_f32_16x16x32_bf16 v[34:37], v[168:171], v[184:187], v[34:37]
	v_mfma_f32_16x16x32_bf16 v[22:25], v[160:163], v[202:205], v[22:25]
	v_mfma_f32_16x16x32_bf16 v[18:21], v[168:171], v[202:205], v[18:21]
	v_mfma_f32_16x16x32_bf16 v[6:9], v[160:163], v[210:213], v[6:9]
	v_mfma_f32_16x16x32_bf16 v[2:5], v[168:171], v[210:213], v[2:5]
	v_mfma_f32_16x16x32_bf16 v[54:57], v[164:167], v[180:183], v[54:57]
	v_mfma_f32_16x16x32_bf16 v[50:53], v[172:175], v[180:183], v[50:53]
	v_mfma_f32_16x16x32_bf16 v[38:41], v[164:167], v[188:191], v[38:41]
	v_mfma_f32_16x16x32_bf16 v[34:37], v[172:175], v[188:191], v[34:37]
	v_mfma_f32_16x16x32_bf16 v[22:25], v[164:167], v[206:209], v[22:25]
	v_mfma_f32_16x16x32_bf16 v[18:21], v[172:175], v[206:209], v[18:21]
	v_mfma_f32_16x16x32_bf16 v[6:9], v[164:167], v[214:217], v[6:9]
	v_mfma_f32_16x16x32_bf16 v[2:5], v[172:175], v[214:217], v[2:5]
	s_setprio 0
	s_barrier
	s_add_i32 s24, 0, 0x18000
	s_add_i32 s50, 0, 0x1c000
	v_add_u32_e32 v156, s24, v145
	v_add_u32_e32 v172, s50, v145
	ds_read_b128 v[140:143], v156
	ds_read_b128 v[148:151], v156 offset:1024
	ds_read_b128 v[152:155], v156 offset:2048
	ds_read_b128 v[156:159], v156 offset:3072
	ds_read_b128 v[160:163], v172
	ds_read_b128 v[164:167], v172 offset:1024
	ds_read_b128 v[168:171], v172 offset:2048
	ds_read_b128 v[172:175], v172 offset:3072
	s_add_u32 s0, s62, 0x30000
	s_addc_u32 s1, s63, 0
	s_mov_b32 m0, s90
	v_lshl_add_u64 v[222:223], s[0:1], 0, v[130:131]
	ds_read_b128 v[176:179], v147 offset:32768
	ds_read_b128 v[180:183], v147 offset:33792
	ds_read_b128 v[184:187], v147 offset:34816
	ds_read_b128 v[188:191], v147 offset:35840
	ds_read_b128 v[202:205], v147 offset:36864
	ds_read_b128 v[206:209], v147 offset:37888
	ds_read_b128 v[210:213], v147 offset:38912
	ds_read_b128 v[214:217], v147 offset:39936
	global_load_lds_dwordx4 v[222:223], off
	v_lshl_add_u64 v[222:223], s[0:1], 0, v[132:133]
	s_mov_b32 m0, s91
	s_nop 0
	global_load_lds_dwordx4 v[222:223], off
	s_waitcnt vmcnt(8)
	s_waitcnt lgkmcnt(0)
	s_barrier
	s_setprio 1
	s_waitcnt lgkmcnt(0)
	v_mfma_f32_16x16x32_bf16 v[126:129], v[140:143], v[176:179], v[126:129]
	v_mfma_f32_16x16x32_bf16 v[122:125], v[152:155], v[176:179], v[122:125]
	v_mfma_f32_16x16x32_bf16 v[110:113], v[140:143], v[184:187], v[110:113]
	v_mfma_f32_16x16x32_bf16 v[106:109], v[152:155], v[184:187], v[106:109]
	v_mfma_f32_16x16x32_bf16 v[94:97], v[140:143], v[202:205], v[94:97]
	v_mfma_f32_16x16x32_bf16 v[90:93], v[152:155], v[202:205], v[90:93]
	v_mfma_f32_16x16x32_bf16 v[78:81], v[140:143], v[210:213], v[78:81]
	v_mfma_f32_16x16x32_bf16 v[74:77], v[152:155], v[210:213], v[74:77]
	v_mfma_f32_16x16x32_bf16 v[126:129], v[148:151], v[180:183], v[126:129]
	v_mfma_f32_16x16x32_bf16 v[122:125], v[156:159], v[180:183], v[122:125]
	v_mfma_f32_16x16x32_bf16 v[110:113], v[148:151], v[188:191], v[110:113]
	v_mfma_f32_16x16x32_bf16 v[106:109], v[156:159], v[188:191], v[106:109]
	v_mfma_f32_16x16x32_bf16 v[94:97], v[148:151], v[206:209], v[94:97]
	v_mfma_f32_16x16x32_bf16 v[90:93], v[156:159], v[206:209], v[90:93]
	v_mfma_f32_16x16x32_bf16 v[78:81], v[148:151], v[214:217], v[78:81]
	v_mfma_f32_16x16x32_bf16 v[74:77], v[156:159], v[214:217], v[74:77]
	v_mfma_f32_16x16x32_bf16 v[118:121], v[160:163], v[176:179], v[118:121]
	v_mfma_f32_16x16x32_bf16 v[114:117], v[168:171], v[176:179], v[114:117]
	v_mfma_f32_16x16x32_bf16 v[102:105], v[160:163], v[184:187], v[102:105]
	v_mfma_f32_16x16x32_bf16 v[98:101], v[168:171], v[184:187], v[98:101]
	v_mfma_f32_16x16x32_bf16 v[86:89], v[160:163], v[202:205], v[86:89]
	v_mfma_f32_16x16x32_bf16 v[82:85], v[168:171], v[202:205], v[82:85]
	v_mfma_f32_16x16x32_bf16 v[70:73], v[160:163], v[210:213], v[70:73]
	v_mfma_f32_16x16x32_bf16 v[66:69], v[168:171], v[210:213], v[66:69]
	v_mfma_f32_16x16x32_bf16 v[118:121], v[164:167], v[180:183], v[118:121]
	v_mfma_f32_16x16x32_bf16 v[114:117], v[172:175], v[180:183], v[114:117]
	v_mfma_f32_16x16x32_bf16 v[102:105], v[164:167], v[188:191], v[102:105]
	v_mfma_f32_16x16x32_bf16 v[98:101], v[172:175], v[188:191], v[98:101]
	v_mfma_f32_16x16x32_bf16 v[86:89], v[164:167], v[206:209], v[86:89]
	v_mfma_f32_16x16x32_bf16 v[82:85], v[172:175], v[206:209], v[82:85]
	v_mfma_f32_16x16x32_bf16 v[70:73], v[164:167], v[214:217], v[70:73]
	v_mfma_f32_16x16x32_bf16 v[66:69], v[172:175], v[214:217], v[66:69]
	s_setprio 0
	s_barrier
; #define PG8_STAGE(bufoff, gbase, voff) do { _Pragma("unroll") for (int _i = 0; _i < 2; ++_i) \
;         __builtin_amdgcn_global_load_lds((const unsigned*)((const char*)(gbase) + (voff)[_i]), (LAS unsigned*)(lds + (bufoff) + ldsw + _i * 8192), 16, 0, 0); } while (0)
; #define PG8_LDA(dst, b, h) do { _Pragma("unroll") for (int m = 0; m < 4; ++m) _Pragma("unroll") for (int k = 0; k < 2; ++k) dst[m][k] = *(const LAS bf16x8*)(lds + PG8_SA(b, h) + aoff + m * 2048 + k * 1024); } while (0)
; #define PG8_MMA(ai, bj, At, Bt) do { __builtin_amdgcn_s_setprio(1); _Pragma("unroll") for (int m = 0; m < 4; ++m) _Pragma("unroll") for (int n = 0; n < 2; ++n) _Pragma("unroll") for (int k = 0; k < 2; ++k) \
;         acc[ai][bj][m][n] = __builtin_amdgcn_mfma_f32_16x16x32_bf16(Bt[n][k], At[m][k], acc[ai][bj][m][n], 0, 0, 0); __builtin_amdgcn_s_setprio(0); } while (0)
; #define PG8_WAIT_V(n) asm volatile("s_waitcnt vmcnt(" #n ")" ::: "memory")
; #define PG8_WAIT_L(n) asm volatile("s_waitcnt lgkmcnt(" #n ")" ::: "memory")
; #define PG8_BAR __builtin_amdgcn_s_barrier()
; #define PG8_SCHED __builtin_amdgcn_sched_barrier(0)
; template <class Epi, bool ALIGN_EPI, int M_, int N_, int K_, int LDA, int LDB>
; __device__ __forceinline__ void gemm_phase(LAS unsigned char* lds, const int tid_in, const int G_in, const int bx_in, const Gemm g, const Epi& E) {
;     ...
;             PG8_LDA(At, 1, 1); PG8_STAGE(PG8_SB(1, 0), b3, voffB); PG8_STAGE(PG8_SB(1, 1), b3 + hstepB, voffB); PG8_STAGE(PG8_SA(1, 0), a3, voffA);
;             PG8_WAIT_V(8); PG8_WAIT_L(0); PG8_BAR; PG8_MMA(1, 0, At, B0); PG8_MMA(1, 1, At, B1); PG8_BAR; PG8_SCHED;
;         }
;         if constexpr (ALIGN_EPI) { if (wr == 0) PG8_BAR; }
	s_add_i32 s0, s24, s89
	v_lshl_add_u64 v[192:193], v[192:193], 0, s[54:55]
	s_mov_b32 m0, s0
	ds_read_b128 v[176:179], v147 offset:49152
	ds_read_b128 v[180:183], v147 offset:50176
	ds_read_b128 v[184:187], v147 offset:51200
	ds_read_b128 v[188:191], v147 offset:52224
	ds_read_b128 v[202:205], v147 offset:53248
	ds_read_b128 v[206:209], v147 offset:54272
	ds_read_b128 v[210:213], v147 offset:55296
	ds_read_b128 v[214:217], v147 offset:56320
	global_load_lds_dwordx4 v[192:193], off
	s_add_i32 m0, s0, 0x2000
	s_add_u32 s0, s60, 0x20080
	v_lshl_add_u64 v[192:193], v[200:201], 0, s[54:55]
	s_addc_u32 s1, s61, 0
	s_add_i32 s24, s50, s89
	global_load_lds_dwordx4 v[192:193], off
	v_lshl_add_u64 v[192:193], s[0:1], 0, v[0:1]
	s_mov_b32 m0, s24
	s_nop 0
	global_load_lds_dwordx4 v[192:193], off
	v_lshl_add_u64 v[192:193], s[0:1], 0, v[134:135]
	s_add_i32 m0, s24, 0x2000
	s_nop 0
	global_load_lds_dwordx4 v[192:193], off
	v_lshl_add_u64 v[192:193], v[218:219], 0, s[54:55]
	s_mov_b32 m0, s12
	s_nop 0
	global_load_lds_dwordx4 v[192:193], off
	v_lshl_add_u64 v[192:193], v[220:221], 0, s[54:55]
	s_mov_b32 m0, s13
	s_nop 0
	global_load_lds_dwordx4 v[192:193], off
	s_waitcnt vmcnt(8)
	s_waitcnt lgkmcnt(0)
	s_barrier
	s_setprio 1
	s_waitcnt lgkmcnt(0)
	v_mfma_f32_16x16x32_bf16 v[62:65], v[140:143], v[176:179], v[62:65]
	v_mfma_f32_16x16x32_bf16 v[58:61], v[152:155], v[176:179], v[58:61]
	v_mfma_f32_16x16x32_bf16 v[46:49], v[140:143], v[184:187], v[46:49]
	v_mfma_f32_16x16x32_bf16 v[42:45], v[152:155], v[184:187], v[42:45]
	v_mfma_f32_16x16x32_bf16 v[30:33], v[140:143], v[202:205], v[30:33]
	v_mfma_f32_16x16x32_bf16 v[26:29], v[152:155], v[202:205], v[26:29]
	v_mfma_f32_16x16x32_bf16 v[14:17], v[140:143], v[210:213], v[14:17]
	v_mfma_f32_16x16x32_bf16 v[10:13], v[152:155], v[210:213], v[10:13]
	v_mfma_f32_16x16x32_bf16 v[62:65], v[148:151], v[180:183], v[62:65]
	v_mfma_f32_16x16x32_bf16 v[58:61], v[156:159], v[180:183], v[58:61]
	v_mfma_f32_16x16x32_bf16 v[46:49], v[148:151], v[188:191], v[46:49]
	v_mfma_f32_16x16x32_bf16 v[42:45], v[156:159], v[188:191], v[42:45]
	v_mfma_f32_16x16x32_bf16 v[30:33], v[148:151], v[206:209], v[30:33]
	v_mfma_f32_16x16x32_bf16 v[26:29], v[156:159], v[206:209], v[26:29]
	v_mfma_f32_16x16x32_bf16 v[14:17], v[148:151], v[214:217], v[14:17]
	v_mfma_f32_16x16x32_bf16 v[10:13], v[156:159], v[214:217], v[10:13]
	v_mfma_f32_16x16x32_bf16 v[54:57], v[160:163], v[176:179], v[54:57]
	v_mfma_f32_16x16x32_bf16 v[50:53], v[168:171], v[176:179], v[50:53]
	v_mfma_f32_16x16x32_bf16 v[38:41], v[160:163], v[184:187], v[38:41]
	v_mfma_f32_16x16x32_bf16 v[34:37], v[168:171], v[184:187], v[34:37]
	v_mfma_f32_16x16x32_bf16 v[22:25], v[160:163], v[202:205], v[22:25]
	v_mfma_f32_16x16x32_bf16 v[18:21], v[168:171], v[202:205], v[18:21]
	v_mfma_f32_16x16x32_bf16 v[6:9], v[160:163], v[210:213], v[6:9]
	v_mfma_f32_16x16x32_bf16 v[2:5], v[168:171], v[210:213], v[2:5]
	v_mfma_f32_16x16x32_bf16 v[54:57], v[164:167], v[180:183], v[54:57]
	v_mfma_f32_16x16x32_bf16 v[50:53], v[172:175], v[180:183], v[50:53]
	v_mfma_f32_16x16x32_bf16 v[38:41], v[164:167], v[188:191], v[38:41]
	v_mfma_f32_16x16x32_bf16 v[34:37], v[172:175], v[188:191], v[34:37]
	v_mfma_f32_16x16x32_bf16 v[22:25], v[164:167], v[206:209], v[22:25]
	v_mfma_f32_16x16x32_bf16 v[18:21], v[172:175], v[206:209], v[18:21]
	v_mfma_f32_16x16x32_bf16 v[6:9], v[164:167], v[214:217], v[6:9]
	v_mfma_f32_16x16x32_bf16 v[2:5], v[172:175], v[214:217], v[2:5]
	s_setprio 0
	s_barrier
	s_add_i32 vcc_lo, vcc_lo, 2
	s_add_u32 s86, s86, 0x100
	s_addc_u32 s87, s87, 0
	s_cmp_gt_u32 vcc_lo, 5
	s_mov_b64 s[50:51], s[8:9]
	s_cbranch_scc0 .LBB0_189
	s_and_b64 vcc, exec, s[42:43]
	s_cbranch_vccz .LBB0_192
	s_barrier

; #define PG8_STAGE(bufoff, gbase, voff) do { _Pragma("unroll") for (int _i = 0; _i < 2; ++_i) \
;         __builtin_amdgcn_global_load_lds((const unsigned*)((const char*)(gbase) + (voff)[_i]), (LAS unsigned*)(lds + (bufoff) + ldsw + _i * 8192), 16, 0, 0); } while (0)
; #define PG8_LDA(dst, b, h) do { _Pragma("unroll") for (int m = 0; m < 4; ++m) _Pragma("unroll") for (int k = 0; k < 2; ++k) dst[m][k] = *(const LAS bf16x8*)(lds + PG8_SA(b, h) + aoff + m * 2048 + k * 1024); } while (0)
; #define PG8_LDB(dst, b, h) do { _Pragma("unroll") for (int n = 0; n < 2; ++n) _Pragma("unroll") for (int k = 0; k < 2; ++k) dst[n][k] = *(const LAS bf16x8*)(lds + PG8_SB(b, h) + boff + n * 2048 + k * 1024); } while (0)
; #define PG8_MMA(ai, bj, At, Bt) do { __builtin_amdgcn_s_setprio(1); _Pragma("unroll") for (int m = 0; m < 4; ++m) _Pragma("unroll") for (int n = 0; n < 2; ++n) _Pragma("unroll") for (int k = 0; k < 2; ++k) \
;         acc[ai][bj][m][n] = __builtin_amdgcn_mfma_f32_16x16x32_bf16(Bt[n][k], At[m][k], acc[ai][bj][m][n], 0, 0, 0); __builtin_amdgcn_s_setprio(0); } while (0)
; #define PG8_WAIT_V(n) asm volatile("s_waitcnt vmcnt(" #n ")" ::: "memory")
; #define PG8_WAIT_L(n) asm volatile("s_waitcnt lgkmcnt(" #n ")" ::: "memory")
; #define PG8_BAR __builtin_amdgcn_s_barrier()
; #define PG8_SCHED __builtin_amdgcn_sched_barrier(0)
; template <class Epi, bool ALIGN_EPI, int M_, int N_, int K_, int LDA, int LDB>
; __device__ __forceinline__ void gemm_phase(LAS unsigned char* lds, const int tid_in, const int G_in, const int bx_in, const Gemm g, const Epi& E) {
;     ...
;             const bool last = (t == nt - 2);
;             const char* a1 = cA + (size_t)(t + 1) * kstep;
;             const char* a2 = last ? nA : cA + (size_t)(t + 2) * kstep; const char* b2 = last ? nB : cB + (size_t)(t + 2) * kstep;
;             const char* a3 = a2 + kstep; const char* b3 = b2 + kstep;
;             PG8_LDB(B0, 0, 0); PG8_LDB(B1, 0, 1); PG8_SCHED; PG8_LDA(At, 0, 0); PG8_STAGE(PG8_SA(1, 1), a1 + hstepA, voffA);
;             PG8_WAIT_V(8); PG8_WAIT_L(0); PG8_BAR; PG8_MMA(0, 0, At, B0); PG8_MMA(0, 1, At, B1); PG8_BAR; PG8_SCHED;
;             PG8_LDA(At, 0, 1); PG8_STAGE(PG8_SB(0, 0), b2, voffB); PG8_STAGE(PG8_SB(0, 1), b2 + hstepB, voffB); PG8_STAGE(PG8_SA(0, 0), a2, voffA);
;             PG8_WAIT_V(8); PG8_WAIT_L(0); PG8_BAR; PG8_MMA(1, 0, At, B0); PG8_MMA(1, 1, At, B1); PG8_BAR; PG8_SCHED;
.LBB0_483:
	s_add_u32 s0, s8, 0xffe00080
	s_addc_u32 s1, s9, -1
	s_add_i32 s24, 0, 0x10000
	s_cmp_eq_u32 s91, 8
	s_cselect_b32 s49, s11, s1
	s_cselect_b32 s48, s41, s0
	v_add_u32_e32 v0, s24, v167
	s_cselect_b32 s47, s43, s90
	s_cselect_b32 s46, s42, s89
	s_add_i32 s66, 0, 0x14000
	ds_read_b128 v[130:133], v0
	ds_read_b128 v[134:137], v0 offset:1024
	ds_read_b128 v[138:141], v0 offset:2048
	ds_read_b128 v[160:163], v0 offset:3072
	v_add_u32_e32 v0, s66, v167
	ds_read_b128 v[170:173], v0
	ds_read_b128 v[174:177], v0 offset:1024
	ds_read_b128 v[178:181], v0 offset:2048
	ds_read_b128 v[182:185], v0 offset:3072
	v_lshl_add_u64 v[142:143], s[8:9], 0, v[156:157]
	s_add_i32 m0, s63, 0xc000
	ds_read_b128 v[186:189], v169
	ds_read_b128 v[202:205], v169 offset:1024
	ds_read_b128 v[206:209], v169 offset:2048
	ds_read_b128 v[210:213], v169 offset:3072
	ds_read_b128 v[214:217], v169 offset:4096
	ds_read_b128 v[218:221], v169 offset:5120
	ds_read_b128 v[222:225], v169 offset:6144
	ds_read_b128 v[226:229], v169 offset:7168
	global_load_lds_dwordx4 v[142:143], off
	v_lshl_add_u64 v[142:143], s[8:9], 0, v[158:159]
	s_add_i32 m0, s63, 0xe000
	s_nop 0
	global_load_lds_dwordx4 v[142:143], off
	s_waitcnt vmcnt(8)
	s_waitcnt lgkmcnt(0)
	s_barrier
	s_setprio 1
	s_waitcnt lgkmcnt(0)
	v_mfma_f32_16x16x32_bf16 v[126:129], v[130:133], v[186:189], v[126:129]
	v_mfma_f32_16x16x32_bf16 v[122:125], v[138:141], v[186:189], v[122:125]
	v_mfma_f32_16x16x32_bf16 v[110:113], v[130:133], v[206:209], v[110:113]
	v_mfma_f32_16x16x32_bf16 v[106:109], v[138:141], v[206:209], v[106:109]
	v_mfma_f32_16x16x32_bf16 v[94:97], v[130:133], v[214:217], v[94:97]
	v_mfma_f32_16x16x32_bf16 v[90:93], v[138:141], v[214:217], v[90:93]
	v_mfma_f32_16x16x32_bf16 v[78:81], v[130:133], v[222:225], v[78:81]
	v_mfma_f32_16x16x32_bf16 v[74:77], v[138:141], v[222:225], v[74:77]
	v_mfma_f32_16x16x32_bf16 v[126:129], v[134:137], v[202:205], v[126:129]
	v_mfma_f32_16x16x32_bf16 v[122:125], v[160:163], v[202:205], v[122:125]
	v_mfma_f32_16x16x32_bf16 v[110:113], v[134:137], v[210:213], v[110:113]
	v_mfma_f32_16x16x32_bf16 v[106:109], v[160:163], v[210:213], v[106:109]
	v_mfma_f32_16x16x32_bf16 v[94:97], v[134:137], v[218:221], v[94:97]
	v_mfma_f32_16x16x32_bf16 v[90:93], v[160:163], v[218:221], v[90:93]
	v_mfma_f32_16x16x32_bf16 v[78:81], v[134:137], v[226:229], v[78:81]
	v_mfma_f32_16x16x32_bf16 v[74:77], v[160:163], v[226:229], v[74:77]
	v_mfma_f32_16x16x32_bf16 v[118:121], v[170:173], v[186:189], v[118:121]
	v_mfma_f32_16x16x32_bf16 v[114:117], v[178:181], v[186:189], v[114:117]
	v_mfma_f32_16x16x32_bf16 v[102:105], v[170:173], v[206:209], v[102:105]
	v_mfma_f32_16x16x32_bf16 v[98:101], v[178:181], v[206:209], v[98:101]
	v_mfma_f32_16x16x32_bf16 v[86:89], v[170:173], v[214:217], v[86:89]
	v_mfma_f32_16x16x32_bf16 v[82:85], v[178:181], v[214:217], v[82:85]
	v_mfma_f32_16x16x32_bf16 v[70:73], v[170:173], v[222:225], v[70:73]
	v_mfma_f32_16x16x32_bf16 v[66:69], v[178:181], v[222:225], v[66:69]
	v_mfma_f32_16x16x32_bf16 v[118:121], v[174:177], v[202:205], v[118:121]
	v_mfma_f32_16x16x32_bf16 v[114:117], v[182:185], v[202:205], v[114:117]
	v_mfma_f32_16x16x32_bf16 v[102:105], v[174:177], v[210:213], v[102:105]
	v_mfma_f32_16x16x32_bf16 v[98:101], v[182:185], v[210:213], v[98:101]
	v_mfma_f32_16x16x32_bf16 v[86:89], v[174:177], v[218:221], v[86:89]
	v_mfma_f32_16x16x32_bf16 v[82:85], v[182:185], v[218:221], v[82:85]
	v_mfma_f32_16x16x32_bf16 v[70:73], v[174:177], v[226:229], v[70:73]
	v_mfma_f32_16x16x32_bf16 v[66:69], v[182:185], v[226:229], v[66:69]
	s_setprio 0
	s_barrier
	s_add_i32 s0, s24, s62
	v_lshl_add_u64 v[142:143], s[46:47], 0, v[146:147]
	s_mov_b32 m0, s0
	ds_read_b128 v[186:189], v169 offset:16384
	ds_read_b128 v[202:205], v169 offset:17408
	ds_read_b128 v[206:209], v169 offset:18432
	ds_read_b128 v[210:213], v169 offset:19456
	ds_read_b128 v[214:217], v169 offset:20480
	ds_read_b128 v[218:221], v169 offset:21504
	ds_read_b128 v[222:225], v169 offset:22528
	ds_read_b128 v[226:229], v169 offset:23552
	global_load_lds_dwordx4 v[142:143], off
	s_add_i32 m0, s0, 0x2000
	s_add_u32 s0, s46, 0x30000
	v_lshl_add_u64 v[164:165], s[46:47], 0, v[150:151]
	s_addc_u32 s1, s47, 0
	s_add_i32 s24, s66, s62
	global_load_lds_dwordx4 v[164:165], off
	v_lshl_add_u64 v[190:191], s[0:1], 0, v[146:147]
	s_mov_b32 m0, s24
	v_lshl_add_u64 v[192:193], s[48:49], 0, v[148:149]
	global_load_lds_dwordx4 v[190:191], off
	v_lshl_add_u64 v[190:191], s[0:1], 0, v[150:151]
	s_add_i32 m0, s24, 0x2000
	s_nop 0
	global_load_lds_dwordx4 v[190:191], off
	v_lshl_add_u64 v[190:191], s[48:49], 0, v[144:145]
	s_mov_b32 m0, s63
	s_nop 0
	global_load_lds_dwordx4 v[190:191], off
	s_mov_b32 m0, s75
	s_nop 0
	global_load_lds_dwordx4 v[192:193], off
	s_waitcnt vmcnt(8)
	s_waitcnt lgkmcnt(0)
	s_barrier
; #define PG8_STAGE(bufoff, gbase, voff) do { _Pragma("unroll") for (int _i = 0; _i < 2; ++_i) \
;         __builtin_amdgcn_global_load_lds((const unsigned*)((const char*)(gbase) + (voff)[_i]), (LAS unsigned*)(lds + (bufoff) + ldsw + _i * 8192), 16, 0, 0); } while (0)
; #define PG8_LDA(dst, b, h) do { _Pragma("unroll") for (int m = 0; m < 4; ++m) _Pragma("unroll") for (int k = 0; k < 2; ++k) dst[m][k] = *(const LAS bf16x8*)(lds + PG8_SA(b, h) + aoff + m * 2048 + k * 1024); } while (0)
; #define PG8_LDB(dst, b, h) do { _Pragma("unroll") for (int n = 0; n < 2; ++n) _Pragma("unroll") for (int k = 0; k < 2; ++k) dst[n][k] = *(const LAS bf16x8*)(lds + PG8_SB(b, h) + boff + n * 2048 + k * 1024); } while (0)
; #define PG8_MMA(ai, bj, At, Bt) do { __builtin_amdgcn_s_setprio(1); _Pragma("unroll") for (int m = 0; m < 4; ++m) _Pragma("unroll") for (int n = 0; n < 2; ++n) _Pragma("unroll") for (int k = 0; k < 2; ++k) \
;         acc[ai][bj][m][n] = __builtin_amdgcn_mfma_f32_16x16x32_bf16(Bt[n][k], At[m][k], acc[ai][bj][m][n], 0, 0, 0); __builtin_amdgcn_s_setprio(0); } while (0)
; #define PG8_WAIT_V(n) asm volatile("s_waitcnt vmcnt(" #n ")" ::: "memory")
; #define PG8_WAIT_L(n) asm volatile("s_waitcnt lgkmcnt(" #n ")" ::: "memory")
; #define PG8_BAR __builtin_amdgcn_s_barrier()
; #define PG8_SCHED __builtin_amdgcn_sched_barrier(0)
; template <class Epi, bool ALIGN_EPI, int M_, int N_, int K_, int LDA, int LDB>
; __device__ __forceinline__ void gemm_phase(LAS unsigned char* lds, const int tid_in, const int G_in, const int bx_in, const Gemm g, const Epi& E) {
;     ...
;             PG8_WAIT_V(8); PG8_WAIT_L(0); PG8_BAR; PG8_MMA(1, 0, At, B0); PG8_MMA(1, 1, At, B1); PG8_BAR; PG8_SCHED;
;             PG8_LDB(B0, 1, 0); PG8_LDB(B1, 1, 1); PG8_SCHED; PG8_LDA(At, 1, 0); PG8_STAGE(PG8_SA(0, 1), a2 + hstepA, voffA);
;             PG8_WAIT_V(8); PG8_WAIT_L(0); PG8_BAR; PG8_MMA(0, 0, At, B0); PG8_MMA(0, 1, At, B1); PG8_BAR; PG8_SCHED;
	s_setprio 1
	s_waitcnt lgkmcnt(0)
	v_mfma_f32_16x16x32_bf16 v[62:65], v[130:133], v[186:189], v[62:65]
	v_mfma_f32_16x16x32_bf16 v[58:61], v[138:141], v[186:189], v[58:61]
	v_mfma_f32_16x16x32_bf16 v[46:49], v[130:133], v[206:209], v[46:49]
	v_mfma_f32_16x16x32_bf16 v[42:45], v[138:141], v[206:209], v[42:45]
	v_mfma_f32_16x16x32_bf16 v[30:33], v[130:133], v[214:217], v[30:33]
	v_mfma_f32_16x16x32_bf16 v[26:29], v[138:141], v[214:217], v[26:29]
	v_mfma_f32_16x16x32_bf16 v[14:17], v[130:133], v[222:225], v[14:17]
	v_mfma_f32_16x16x32_bf16 v[10:13], v[138:141], v[222:225], v[10:13]
	v_mfma_f32_16x16x32_bf16 v[62:65], v[134:137], v[202:205], v[62:65]
	v_mfma_f32_16x16x32_bf16 v[58:61], v[160:163], v[202:205], v[58:61]
	v_mfma_f32_16x16x32_bf16 v[46:49], v[134:137], v[210:213], v[46:49]
	v_mfma_f32_16x16x32_bf16 v[42:45], v[160:163], v[210:213], v[42:45]
	v_mfma_f32_16x16x32_bf16 v[30:33], v[134:137], v[218:221], v[30:33]
	v_mfma_f32_16x16x32_bf16 v[26:29], v[160:163], v[218:221], v[26:29]
	v_mfma_f32_16x16x32_bf16 v[14:17], v[134:137], v[226:229], v[14:17]
	v_mfma_f32_16x16x32_bf16 v[10:13], v[160:163], v[226:229], v[10:13]
	v_mfma_f32_16x16x32_bf16 v[54:57], v[170:173], v[186:189], v[54:57]
	v_mfma_f32_16x16x32_bf16 v[50:53], v[178:181], v[186:189], v[50:53]
	v_mfma_f32_16x16x32_bf16 v[38:41], v[170:173], v[206:209], v[38:41]
	v_mfma_f32_16x16x32_bf16 v[34:37], v[178:181], v[206:209], v[34:37]
	v_mfma_f32_16x16x32_bf16 v[22:25], v[170:173], v[214:217], v[22:25]
	v_mfma_f32_16x16x32_bf16 v[18:21], v[178:181], v[214:217], v[18:21]
	v_mfma_f32_16x16x32_bf16 v[6:9], v[170:173], v[222:225], v[6:9]
	v_mfma_f32_16x16x32_bf16 v[2:5], v[178:181], v[222:225], v[2:5]
	v_mfma_f32_16x16x32_bf16 v[54:57], v[174:177], v[202:205], v[54:57]
	v_mfma_f32_16x16x32_bf16 v[50:53], v[182:185], v[202:205], v[50:53]
	v_mfma_f32_16x16x32_bf16 v[38:41], v[174:177], v[210:213], v[38:41]
	v_mfma_f32_16x16x32_bf16 v[34:37], v[182:185], v[210:213], v[34:37]
	v_mfma_f32_16x16x32_bf16 v[22:25], v[174:177], v[218:221], v[22:25]
	v_mfma_f32_16x16x32_bf16 v[18:21], v[182:185], v[218:221], v[18:21]
	v_mfma_f32_16x16x32_bf16 v[6:9], v[174:177], v[226:229], v[6:9]
	v_mfma_f32_16x16x32_bf16 v[2:5], v[182:185], v[226:229], v[2:5]
	s_setprio 0
	s_barrier
	s_add_i32 s24, 0, 0x18000
	v_add_u32_e32 v0, s24, v167
	s_add_i32 s66, 0, 0x1c000
	ds_read_b128 v[130:133], v0
	ds_read_b128 v[134:137], v0 offset:1024
	ds_read_b128 v[138:141], v0 offset:2048
	ds_read_b128 v[160:163], v0 offset:3072
	v_add_u32_e32 v0, s66, v167
	ds_read_b128 v[170:173], v0
	ds_read_b128 v[174:177], v0 offset:1024
	ds_read_b128 v[178:181], v0 offset:2048
	ds_read_b128 v[182:185], v0 offset:3072
	s_add_u32 s0, s48, 0x200000
	s_addc_u32 s1, s49, 0
	s_mov_b32 m0, s77
	v_lshl_add_u64 v[200:201], s[0:1], 0, v[144:145]
	ds_read_b128 v[186:189], v169 offset:32768
	ds_read_b128 v[202:205], v169 offset:33792
	ds_read_b128 v[206:209], v169 offset:34816
	ds_read_b128 v[210:213], v169 offset:35840
	ds_read_b128 v[214:217], v169 offset:36864
	ds_read_b128 v[218:221], v169 offset:37888
	ds_read_b128 v[222:225], v169 offset:38912
	ds_read_b128 v[226:229], v169 offset:39936
	global_load_lds_dwordx4 v[200:201], off
	v_lshl_add_u64 v[200:201], s[0:1], 0, v[148:149]
	s_mov_b32 m0, s78
	s_nop 0
	global_load_lds_dwordx4 v[200:201], off
	s_waitcnt vmcnt(8)
	s_waitcnt lgkmcnt(0)
	s_barrier
	s_setprio 1
	s_waitcnt lgkmcnt(0)
	v_mfma_f32_16x16x32_bf16 v[126:129], v[130:133], v[186:189], v[126:129]
	v_mfma_f32_16x16x32_bf16 v[122:125], v[138:141], v[186:189], v[122:125]
	v_mfma_f32_16x16x32_bf16 v[110:113], v[130:133], v[206:209], v[110:113]
	v_mfma_f32_16x16x32_bf16 v[106:109], v[138:141], v[206:209], v[106:109]
	v_mfma_f32_16x16x32_bf16 v[94:97], v[130:133], v[214:217], v[94:97]
	v_mfma_f32_16x16x32_bf16 v[90:93], v[138:141], v[214:217], v[90:93]
	v_mfma_f32_16x16x32_bf16 v[78:81], v[130:133], v[222:225], v[78:81]
	v_mfma_f32_16x16x32_bf16 v[74:77], v[138:141], v[222:225], v[74:77]
	v_mfma_f32_16x16x32_bf16 v[126:129], v[134:137], v[202:205], v[126:129]
	v_mfma_f32_16x16x32_bf16 v[122:125], v[160:163], v[202:205], v[122:125]
	v_mfma_f32_16x16x32_bf16 v[110:113], v[134:137], v[210:213], v[110:113]
	v_mfma_f32_16x16x32_bf16 v[106:109], v[160:163], v[210:213], v[106:109]
	v_mfma_f32_16x16x32_bf16 v[94:97], v[134:137], v[218:221], v[94:97]
	v_mfma_f32_16x16x32_bf16 v[90:93], v[160:163], v[218:221], v[90:93]
	v_mfma_f32_16x16x32_bf16 v[78:81], v[134:137], v[226:229], v[78:81]
	v_mfma_f32_16x16x32_bf16 v[74:77], v[160:163], v[226:229], v[74:77]
	v_mfma_f32_16x16x32_bf16 v[118:121], v[170:173], v[186:189], v[118:121]
	v_mfma_f32_16x16x32_bf16 v[114:117], v[178:181], v[186:189], v[114:117]
	v_mfma_f32_16x16x32_bf16 v[102:105], v[170:173], v[206:209], v[102:105]
	v_mfma_f32_16x16x32_bf16 v[98:101], v[178:181], v[206:209], v[98:101]
	v_mfma_f32_16x16x32_bf16 v[86:89], v[170:173], v[214:217], v[86:89]
	v_mfma_f32_16x16x32_bf16 v[82:85], v[178:181], v[214:217], v[82:85]
	v_mfma_f32_16x16x32_bf16 v[70:73], v[170:173], v[222:225], v[70:73]
	v_mfma_f32_16x16x32_bf16 v[66:69], v[178:181], v[222:225], v[66:69]
	v_mfma_f32_16x16x32_bf16 v[118:121], v[174:177], v[202:205], v[118:121]
	v_mfma_f32_16x16x32_bf16 v[114:117], v[182:185], v[202:205], v[114:117]
	v_mfma_f32_16x16x32_bf16 v[102:105], v[174:177], v[210:213], v[102:105]
	v_mfma_f32_16x16x32_bf16 v[98:101], v[182:185], v[210:213], v[98:101]
	v_mfma_f32_16x16x32_bf16 v[86:89], v[174:177], v[218:221], v[86:89]
	v_mfma_f32_16x16x32_bf16 v[82:85], v[182:185], v[218:221], v[82:85]
	v_mfma_f32_16x16x32_bf16 v[70:73], v[174:177], v[226:229], v[70:73]
	v_mfma_f32_16x16x32_bf16 v[66:69], v[182:185], v[226:229], v[66:69]
	s_setprio 0
	s_barrier
; #define PG8_STAGE(bufoff, gbase, voff) do { _Pragma("unroll") for (int _i = 0; _i < 2; ++_i) \
;         __builtin_amdgcn_global_load_lds((const unsigned*)((const char*)(gbase) + (voff)[_i]), (LAS unsigned*)(lds + (bufoff) + ldsw + _i * 8192), 16, 0, 0); } while (0)
; #define PG8_LDA(dst, b, h) do { _Pragma("unroll") for (int m = 0; m < 4; ++m) _Pragma("unroll") for (int k = 0; k < 2; ++k) dst[m][k] = *(const LAS bf16x8*)(lds + PG8_SA(b, h) + aoff + m * 2048 + k * 1024); } while (0)
; #define PG8_MMA(ai, bj, At, Bt) do { __builtin_amdgcn_s_setprio(1); _Pragma("unroll") for (int m = 0; m < 4; ++m) _Pragma("unroll") for (int n = 0; n < 2; ++n) _Pragma("unroll") for (int k = 0; k < 2; ++k) \
;         acc[ai][bj][m][n] = __builtin_amdgcn_mfma_f32_16x16x32_bf16(Bt[n][k], At[m][k], acc[ai][bj][m][n], 0, 0, 0); __builtin_amdgcn_s_setprio(0); } while (0)
; #define PG8_WAIT_V(n) asm volatile("s_waitcnt vmcnt(" #n ")" ::: "memory")
; #define PG8_WAIT_L(n) asm volatile("s_waitcnt lgkmcnt(" #n ")" ::: "memory")
; #define PG8_BAR __builtin_amdgcn_s_barrier()
; #define PG8_SCHED __builtin_amdgcn_sched_barrier(0)
; template <class Epi, bool ALIGN_EPI, int M_, int N_, int K_, int LDA, int LDB>
; __device__ __forceinline__ void gemm_phase(LAS unsigned char* lds, const int tid_in, const int G_in, const int bx_in, const Gemm g, const Epi& E) {
;     ...
;             PG8_LDA(At, 1, 1); PG8_STAGE(PG8_SB(1, 0), b3, voffB); PG8_STAGE(PG8_SB(1, 1), b3 + hstepB, voffB); PG8_STAGE(PG8_SA(1, 0), a3, voffA);
;             PG8_WAIT_V(8); PG8_WAIT_L(0); PG8_BAR; PG8_MMA(1, 0, At, B0); PG8_MMA(1, 1, At, B1); PG8_BAR; PG8_SCHED;
;         }
;         if constexpr (ALIGN_EPI) { if (wr == 0) PG8_BAR; }
	s_add_i32 s0, s24, s62
	v_lshl_add_u64 v[142:143], v[142:143], 0, s[54:55]
	s_mov_b32 m0, s0
	ds_read_b128 v[186:189], v169 offset:49152
	ds_read_b128 v[202:205], v169 offset:50176
	ds_read_b128 v[206:209], v169 offset:51200
	ds_read_b128 v[210:213], v169 offset:52224
	ds_read_b128 v[214:217], v169 offset:53248
	ds_read_b128 v[218:221], v169 offset:54272
	ds_read_b128 v[222:225], v169 offset:55296
	ds_read_b128 v[226:229], v169 offset:56320
	global_load_lds_dwordx4 v[142:143], off
	s_add_i32 m0, s0, 0x2000
	s_add_u32 s0, s46, 0x30080
	v_lshl_add_u64 v[142:143], v[164:165], 0, s[54:55]
	s_addc_u32 s1, s47, 0
	s_add_i32 s24, s66, s62
	global_load_lds_dwordx4 v[142:143], off
	v_lshl_add_u64 v[142:143], s[0:1], 0, v[146:147]
	s_mov_b32 m0, s24
	s_nop 0
	global_load_lds_dwordx4 v[142:143], off
	v_lshl_add_u64 v[142:143], s[0:1], 0, v[150:151]
	s_add_i32 m0, s24, 0x2000
	s_nop 0
	global_load_lds_dwordx4 v[142:143], off
	v_lshl_add_u64 v[142:143], v[190:191], 0, s[54:55]
	s_mov_b32 m0, s79
	s_nop 0
	global_load_lds_dwordx4 v[142:143], off
	v_lshl_add_u64 v[142:143], v[192:193], 0, s[54:55]
	s_mov_b32 m0, s84
	s_nop 0
	global_load_lds_dwordx4 v[142:143], off
	s_waitcnt vmcnt(8)
	s_waitcnt lgkmcnt(0)
	s_barrier
	s_setprio 1
	s_waitcnt lgkmcnt(0)
	v_mfma_f32_16x16x32_bf16 v[62:65], v[130:133], v[186:189], v[62:65]
	v_mfma_f32_16x16x32_bf16 v[58:61], v[138:141], v[186:189], v[58:61]
	v_mfma_f32_16x16x32_bf16 v[46:49], v[130:133], v[206:209], v[46:49]
	v_mfma_f32_16x16x32_bf16 v[42:45], v[138:141], v[206:209], v[42:45]
	v_mfma_f32_16x16x32_bf16 v[30:33], v[130:133], v[214:217], v[30:33]
	v_mfma_f32_16x16x32_bf16 v[26:29], v[138:141], v[214:217], v[26:29]
	v_mfma_f32_16x16x32_bf16 v[14:17], v[130:133], v[222:225], v[14:17]
	v_mfma_f32_16x16x32_bf16 v[10:13], v[138:141], v[222:225], v[10:13]
	v_mfma_f32_16x16x32_bf16 v[62:65], v[134:137], v[202:205], v[62:65]
	v_mfma_f32_16x16x32_bf16 v[58:61], v[160:163], v[202:205], v[58:61]
	v_mfma_f32_16x16x32_bf16 v[46:49], v[134:137], v[210:213], v[46:49]
	v_mfma_f32_16x16x32_bf16 v[42:45], v[160:163], v[210:213], v[42:45]
	v_mfma_f32_16x16x32_bf16 v[30:33], v[134:137], v[218:221], v[30:33]
	v_mfma_f32_16x16x32_bf16 v[26:29], v[160:163], v[218:221], v[26:29]
	v_mfma_f32_16x16x32_bf16 v[14:17], v[134:137], v[226:229], v[14:17]
	v_mfma_f32_16x16x32_bf16 v[10:13], v[160:163], v[226:229], v[10:13]
	v_mfma_f32_16x16x32_bf16 v[54:57], v[170:173], v[186:189], v[54:57]
	v_mfma_f32_16x16x32_bf16 v[50:53], v[178:181], v[186:189], v[50:53]
	v_mfma_f32_16x16x32_bf16 v[38:41], v[170:173], v[206:209], v[38:41]
	v_mfma_f32_16x16x32_bf16 v[34:37], v[178:181], v[206:209], v[34:37]
	v_mfma_f32_16x16x32_bf16 v[22:25], v[170:173], v[214:217], v[22:25]
	v_mfma_f32_16x16x32_bf16 v[18:21], v[178:181], v[214:217], v[18:21]
	v_mfma_f32_16x16x32_bf16 v[6:9], v[170:173], v[222:225], v[6:9]
	v_mfma_f32_16x16x32_bf16 v[2:5], v[178:181], v[222:225], v[2:5]
	v_mfma_f32_16x16x32_bf16 v[54:57], v[174:177], v[202:205], v[54:57]
	v_mfma_f32_16x16x32_bf16 v[50:53], v[182:185], v[202:205], v[50:53]
	v_mfma_f32_16x16x32_bf16 v[38:41], v[174:177], v[210:213], v[38:41]
	v_mfma_f32_16x16x32_bf16 v[34:37], v[182:185], v[210:213], v[34:37]
	v_mfma_f32_16x16x32_bf16 v[22:25], v[174:177], v[218:221], v[22:25]
	v_mfma_f32_16x16x32_bf16 v[18:21], v[182:185], v[218:221], v[18:21]
	v_mfma_f32_16x16x32_bf16 v[6:9], v[174:177], v[226:229], v[6:9]
	v_mfma_f32_16x16x32_bf16 v[2:5], v[182:185], v[226:229], v[2:5]
	s_setprio 0
	s_barrier
	s_add_i32 s91, s91, 2
	s_add_u32 s8, s8, 0x100
	s_addc_u32 s9, s9, 0
	s_add_u32 s89, s89, 0x100
	s_addc_u32 s90, s90, 0
	s_cmp_gt_u32 s91, 9
	s_cbranch_scc0 .LBB0_483
	s_and_b64 vcc, exec, s[38:39]
	s_cbranch_vccz .LBB0_486
	s_barrier

; #define PG8_STAGE(bufoff, gbase, voff) do { _Pragma("unroll") for (int _i = 0; _i < 2; ++_i) \
;         __builtin_amdgcn_global_load_lds((const unsigned*)((const char*)(gbase) + (voff)[_i]), (LAS unsigned*)(lds + (bufoff) + ldsw + _i * 8192), 16, 0, 0); } while (0)
; #define PG8_LDA(dst, b, h) do { _Pragma("unroll") for (int m = 0; m < 4; ++m) _Pragma("unroll") for (int k = 0; k < 2; ++k) dst[m][k] = *(const LAS bf16x8*)(lds + PG8_SA(b, h) + aoff + m * 2048 + k * 1024); } while (0)
; #define PG8_LDB(dst, b, h) do { _Pragma("unroll") for (int n = 0; n < 2; ++n) _Pragma("unroll") for (int k = 0; k < 2; ++k) dst[n][k] = *(const LAS bf16x8*)(lds + PG8_SB(b, h) + boff + n * 2048 + k * 1024); } while (0)
; #define PG8_MMA(ai, bj, At, Bt) do { __builtin_amdgcn_s_setprio(1); _Pragma("unroll") for (int m = 0; m < 4; ++m) _Pragma("unroll") for (int n = 0; n < 2; ++n) _Pragma("unroll") for (int k = 0; k < 2; ++k) \
;         acc[ai][bj][m][n] = __builtin_amdgcn_mfma_f32_16x16x32_bf16(Bt[n][k], At[m][k], acc[ai][bj][m][n], 0, 0, 0); __builtin_amdgcn_s_setprio(0); } while (0)
; #define PG8_WAIT_V(n) asm volatile("s_waitcnt vmcnt(" #n ")" ::: "memory")
; #define PG8_WAIT_L(n) asm volatile("s_waitcnt lgkmcnt(" #n ")" ::: "memory")
; #define PG8_BAR __builtin_amdgcn_s_barrier()
; #define PG8_SCHED __builtin_amdgcn_sched_barrier(0)
; template <class Epi, bool ALIGN_EPI, int M_, int N_, int K_, int LDA, int LDB>
; __device__ __forceinline__ void gemm_phase(LAS unsigned char* lds, const int tid_in, const int G_in, const int bx_in, const Gemm g, const Epi& E) {
;     ...
;             const bool last = (t == nt - 2);
;             const char* a1 = cA + (size_t)(t + 1) * kstep;
;             const char* a2 = last ? nA : cA + (size_t)(t + 2) * kstep; const char* b2 = last ? nB : cB + (size_t)(t + 2) * kstep;
;             const char* a3 = a2 + kstep; const char* b3 = b2 + kstep;
;             PG8_LDB(B0, 0, 0); PG8_LDB(B1, 0, 1); PG8_SCHED; PG8_LDA(At, 0, 0); PG8_STAGE(PG8_SA(1, 1), a1 + hstepA, voffA);
;             PG8_WAIT_V(8); PG8_WAIT_L(0); PG8_BAR; PG8_MMA(0, 0, At, B0); PG8_MMA(0, 1, At, B1); PG8_BAR; PG8_SCHED;
;             PG8_LDA(At, 0, 1); PG8_STAGE(PG8_SB(0, 0), b2, voffB); PG8_STAGE(PG8_SB(0, 1), b2 + hstepB, voffB); PG8_STAGE(PG8_SA(0, 0), a2, voffA);
;             PG8_WAIT_V(8); PG8_WAIT_L(0); PG8_BAR; PG8_MMA(1, 0, At, B0); PG8_MMA(1, 1, At, B1); PG8_BAR; PG8_SCHED;
.LBB0_527:
	s_add_u32 s0, s46, 0xfff00080
	s_addc_u32 s1, s47, -1
	s_add_i32 s24, 0, 0x10000
	s_cmp_eq_u32 s92, 60
	s_cselect_b32 s51, s39, s1
	s_cselect_b32 s50, s88, s0
	v_add_u32_e32 v140, s24, v143
	s_cselect_b32 s49, s37, s91
	s_cselect_b32 s48, s89, s90
	s_add_i32 s58, 0, 0x14000
	ds_read_b128 v[136:139], v140
	ds_read_b128 v[146:149], v140 offset:1024
	ds_read_b128 v[150:153], v140 offset:2048
	ds_read_b128 v[154:157], v140 offset:3072
	v_add_u32_e32 v140, s58, v143
	ds_read_b128 v[158:161], v140
	ds_read_b128 v[162:165], v140 offset:1024
	ds_read_b128 v[166:169], v140 offset:2048
	ds_read_b128 v[170:173], v140 offset:3072
	v_lshl_add_u64 v[140:141], s[46:47], 0, v[132:133]
	s_add_i32 m0, s77, 0xc000
	ds_read_b128 v[174:177], v145
	ds_read_b128 v[178:181], v145 offset:1024
	ds_read_b128 v[182:185], v145 offset:2048
	ds_read_b128 v[186:189], v145 offset:3072
	ds_read_b128 v[190:193], v145 offset:4096
	ds_read_b128 v[202:205], v145 offset:5120
	ds_read_b128 v[206:209], v145 offset:6144
	ds_read_b128 v[210:213], v145 offset:7168
	global_load_lds_dwordx4 v[140:141], off
	v_lshl_add_u64 v[140:141], s[46:47], 0, v[134:135]
	s_add_i32 m0, s77, 0xe000
	s_nop 0
	global_load_lds_dwordx4 v[140:141], off
	s_waitcnt vmcnt(8)
	s_waitcnt lgkmcnt(0)
	s_barrier
	s_setprio 1
	s_waitcnt lgkmcnt(0)
	v_mfma_f32_16x16x32_bf16 v[126:129], v[136:139], v[174:177], v[126:129]
	v_mfma_f32_16x16x32_bf16 v[122:125], v[150:153], v[174:177], v[122:125]
	v_mfma_f32_16x16x32_bf16 v[110:113], v[136:139], v[182:185], v[110:113]
	v_mfma_f32_16x16x32_bf16 v[106:109], v[150:153], v[182:185], v[106:109]
	v_mfma_f32_16x16x32_bf16 v[94:97], v[136:139], v[190:193], v[94:97]
	v_mfma_f32_16x16x32_bf16 v[90:93], v[150:153], v[190:193], v[90:93]
	v_mfma_f32_16x16x32_bf16 v[78:81], v[136:139], v[206:209], v[78:81]
	v_mfma_f32_16x16x32_bf16 v[74:77], v[150:153], v[206:209], v[74:77]
	v_mfma_f32_16x16x32_bf16 v[126:129], v[146:149], v[178:181], v[126:129]
	v_mfma_f32_16x16x32_bf16 v[122:125], v[154:157], v[178:181], v[122:125]
	v_mfma_f32_16x16x32_bf16 v[110:113], v[146:149], v[186:189], v[110:113]
	v_mfma_f32_16x16x32_bf16 v[106:109], v[154:157], v[186:189], v[106:109]
	v_mfma_f32_16x16x32_bf16 v[94:97], v[146:149], v[202:205], v[94:97]
	v_mfma_f32_16x16x32_bf16 v[90:93], v[154:157], v[202:205], v[90:93]
	v_mfma_f32_16x16x32_bf16 v[78:81], v[146:149], v[210:213], v[78:81]
	v_mfma_f32_16x16x32_bf16 v[74:77], v[154:157], v[210:213], v[74:77]
	v_mfma_f32_16x16x32_bf16 v[118:121], v[158:161], v[174:177], v[118:121]
	v_mfma_f32_16x16x32_bf16 v[114:117], v[166:169], v[174:177], v[114:117]
	v_mfma_f32_16x16x32_bf16 v[102:105], v[158:161], v[182:185], v[102:105]
	v_mfma_f32_16x16x32_bf16 v[98:101], v[166:169], v[182:185], v[98:101]
	v_mfma_f32_16x16x32_bf16 v[86:89], v[158:161], v[190:193], v[86:89]
	v_mfma_f32_16x16x32_bf16 v[82:85], v[166:169], v[190:193], v[82:85]
	v_mfma_f32_16x16x32_bf16 v[70:73], v[158:161], v[206:209], v[70:73]
	v_mfma_f32_16x16x32_bf16 v[66:69], v[166:169], v[206:209], v[66:69]
	v_mfma_f32_16x16x32_bf16 v[118:121], v[162:165], v[178:181], v[118:121]
	v_mfma_f32_16x16x32_bf16 v[114:117], v[170:173], v[178:181], v[114:117]
	v_mfma_f32_16x16x32_bf16 v[102:105], v[162:165], v[186:189], v[102:105]
	v_mfma_f32_16x16x32_bf16 v[98:101], v[170:173], v[186:189], v[98:101]
	v_mfma_f32_16x16x32_bf16 v[86:89], v[162:165], v[202:205], v[86:89]
	v_mfma_f32_16x16x32_bf16 v[82:85], v[170:173], v[202:205], v[82:85]
	v_mfma_f32_16x16x32_bf16 v[70:73], v[162:165], v[210:213], v[70:73]
	v_mfma_f32_16x16x32_bf16 v[66:69], v[170:173], v[210:213], v[66:69]
	s_setprio 0
	s_barrier
	s_add_i32 s0, s24, s63
	v_lshl_add_u64 v[140:141], s[48:49], 0, v[0:1]
	s_mov_b32 m0, s0
	ds_read_b128 v[174:177], v145 offset:16384
	ds_read_b128 v[178:181], v145 offset:17408
	ds_read_b128 v[182:185], v145 offset:18432
	ds_read_b128 v[186:189], v145 offset:19456
	ds_read_b128 v[190:193], v145 offset:20480
	ds_read_b128 v[202:205], v145 offset:21504
	ds_read_b128 v[206:209], v145 offset:22528
	ds_read_b128 v[210:213], v145 offset:23552
	global_load_lds_dwordx4 v[140:141], off
	s_add_i32 m0, s0, 0x2000
	s_add_u32 s0, s48, 0x100000
	v_lshl_add_u64 v[200:201], s[48:49], 0, v[130:131]
	s_addc_u32 s1, s49, 0
	s_add_i32 s24, s58, s63
	global_load_lds_dwordx4 v[200:201], off
	v_lshl_add_u64 v[214:215], s[0:1], 0, v[0:1]
	s_mov_b32 m0, s24
	v_lshl_add_u64 v[216:217], s[50:51], 0, v[130:131]
	global_load_lds_dwordx4 v[214:215], off
	v_lshl_add_u64 v[214:215], s[0:1], 0, v[130:131]
	s_add_i32 m0, s24, 0x2000
	s_nop 0
	global_load_lds_dwordx4 v[214:215], off
	v_lshl_add_u64 v[214:215], s[50:51], 0, v[0:1]
	s_mov_b32 m0, s77
	s_nop 0
	global_load_lds_dwordx4 v[214:215], off
	s_mov_b32 m0, s78
	s_nop 0
	global_load_lds_dwordx4 v[216:217], off
	s_waitcnt vmcnt(8)
	s_waitcnt lgkmcnt(0)
	s_barrier
; #define PG8_STAGE(bufoff, gbase, voff) do { _Pragma("unroll") for (int _i = 0; _i < 2; ++_i) \
;         __builtin_amdgcn_global_load_lds((const unsigned*)((const char*)(gbase) + (voff)[_i]), (LAS unsigned*)(lds + (bufoff) + ldsw + _i * 8192), 16, 0, 0); } while (0)
; #define PG8_LDA(dst, b, h) do { _Pragma("unroll") for (int m = 0; m < 4; ++m) _Pragma("unroll") for (int k = 0; k < 2; ++k) dst[m][k] = *(const LAS bf16x8*)(lds + PG8_SA(b, h) + aoff + m * 2048 + k * 1024); } while (0)
; #define PG8_LDB(dst, b, h) do { _Pragma("unroll") for (int n = 0; n < 2; ++n) _Pragma("unroll") for (int k = 0; k < 2; ++k) dst[n][k] = *(const LAS bf16x8*)(lds + PG8_SB(b, h) + boff + n * 2048 + k * 1024); } while (0)
; #define PG8_MMA(ai, bj, At, Bt) do { __builtin_amdgcn_s_setprio(1); _Pragma("unroll") for (int m = 0; m < 4; ++m) _Pragma("unroll") for (int n = 0; n < 2; ++n) _Pragma("unroll") for (int k = 0; k < 2; ++k) \
;         acc[ai][bj][m][n] = __builtin_amdgcn_mfma_f32_16x16x32_bf16(Bt[n][k], At[m][k], acc[ai][bj][m][n], 0, 0, 0); __builtin_amdgcn_s_setprio(0); } while (0)
; #define PG8_WAIT_V(n) asm volatile("s_waitcnt vmcnt(" #n ")" ::: "memory")
; #define PG8_WAIT_L(n) asm volatile("s_waitcnt lgkmcnt(" #n ")" ::: "memory")
; #define PG8_BAR __builtin_amdgcn_s_barrier()
; #define PG8_SCHED __builtin_amdgcn_sched_barrier(0)
; template <class Epi, bool ALIGN_EPI, int M_, int N_, int K_, int LDA, int LDB>
; __device__ __forceinline__ void gemm_phase(LAS unsigned char* lds, const int tid_in, const int G_in, const int bx_in, const Gemm g, const Epi& E) {
;     ...
;             PG8_WAIT_V(8); PG8_WAIT_L(0); PG8_BAR; PG8_MMA(1, 0, At, B0); PG8_MMA(1, 1, At, B1); PG8_BAR; PG8_SCHED;
;             PG8_LDB(B0, 1, 0); PG8_LDB(B1, 1, 1); PG8_SCHED; PG8_LDA(At, 1, 0); PG8_STAGE(PG8_SA(0, 1), a2 + hstepA, voffA);
;             PG8_WAIT_V(8); PG8_WAIT_L(0); PG8_BAR; PG8_MMA(0, 0, At, B0); PG8_MMA(0, 1, At, B1); PG8_BAR; PG8_SCHED;
	s_setprio 1
	s_waitcnt lgkmcnt(0)
	v_mfma_f32_16x16x32_bf16 v[62:65], v[136:139], v[174:177], v[62:65]
	v_mfma_f32_16x16x32_bf16 v[58:61], v[150:153], v[174:177], v[58:61]
	v_mfma_f32_16x16x32_bf16 v[46:49], v[136:139], v[182:185], v[46:49]
	v_mfma_f32_16x16x32_bf16 v[42:45], v[150:153], v[182:185], v[42:45]
	v_mfma_f32_16x16x32_bf16 v[30:33], v[136:139], v[190:193], v[30:33]
	v_mfma_f32_16x16x32_bf16 v[26:29], v[150:153], v[190:193], v[26:29]
	v_mfma_f32_16x16x32_bf16 v[14:17], v[136:139], v[206:209], v[14:17]
	v_mfma_f32_16x16x32_bf16 v[10:13], v[150:153], v[206:209], v[10:13]
	v_mfma_f32_16x16x32_bf16 v[62:65], v[146:149], v[178:181], v[62:65]
	v_mfma_f32_16x16x32_bf16 v[58:61], v[154:157], v[178:181], v[58:61]
	v_mfma_f32_16x16x32_bf16 v[46:49], v[146:149], v[186:189], v[46:49]
	v_mfma_f32_16x16x32_bf16 v[42:45], v[154:157], v[186:189], v[42:45]
	v_mfma_f32_16x16x32_bf16 v[30:33], v[146:149], v[202:205], v[30:33]
	v_mfma_f32_16x16x32_bf16 v[26:29], v[154:157], v[202:205], v[26:29]
	v_mfma_f32_16x16x32_bf16 v[14:17], v[146:149], v[210:213], v[14:17]
	v_mfma_f32_16x16x32_bf16 v[10:13], v[154:157], v[210:213], v[10:13]
	v_mfma_f32_16x16x32_bf16 v[54:57], v[158:161], v[174:177], v[54:57]
	v_mfma_f32_16x16x32_bf16 v[50:53], v[166:169], v[174:177], v[50:53]
	v_mfma_f32_16x16x32_bf16 v[38:41], v[158:161], v[182:185], v[38:41]
	v_mfma_f32_16x16x32_bf16 v[34:37], v[166:169], v[182:185], v[34:37]
	v_mfma_f32_16x16x32_bf16 v[22:25], v[158:161], v[190:193], v[22:25]
	v_mfma_f32_16x16x32_bf16 v[18:21], v[166:169], v[190:193], v[18:21]
	v_mfma_f32_16x16x32_bf16 v[6:9], v[158:161], v[206:209], v[6:9]
	v_mfma_f32_16x16x32_bf16 v[2:5], v[166:169], v[206:209], v[2:5]
	v_mfma_f32_16x16x32_bf16 v[54:57], v[162:165], v[178:181], v[54:57]
	v_mfma_f32_16x16x32_bf16 v[50:53], v[170:173], v[178:181], v[50:53]
	v_mfma_f32_16x16x32_bf16 v[38:41], v[162:165], v[186:189], v[38:41]
	v_mfma_f32_16x16x32_bf16 v[34:37], v[170:173], v[186:189], v[34:37]
	v_mfma_f32_16x16x32_bf16 v[22:25], v[162:165], v[202:205], v[22:25]
	v_mfma_f32_16x16x32_bf16 v[18:21], v[170:173], v[202:205], v[18:21]
	v_mfma_f32_16x16x32_bf16 v[6:9], v[162:165], v[210:213], v[6:9]
	v_mfma_f32_16x16x32_bf16 v[2:5], v[170:173], v[210:213], v[2:5]
	s_setprio 0
	s_barrier
	s_add_i32 s24, 0, 0x18000
	s_add_i32 s58, 0, 0x1c000
	v_add_u32_e32 v154, s24, v143
	v_add_u32_e32 v170, s58, v143
	ds_read_b128 v[136:139], v154
	ds_read_b128 v[146:149], v154 offset:1024
	ds_read_b128 v[150:153], v154 offset:2048
	ds_read_b128 v[154:157], v154 offset:3072
	ds_read_b128 v[158:161], v170
	ds_read_b128 v[162:165], v170 offset:1024
	ds_read_b128 v[166:169], v170 offset:2048
	ds_read_b128 v[170:173], v170 offset:3072
	s_add_u32 s0, s50, 0x100000
	s_addc_u32 s1, s51, 0
	s_mov_b32 m0, s79
	v_lshl_add_u64 v[218:219], s[0:1], 0, v[0:1]
	ds_read_b128 v[174:177], v145 offset:32768
	ds_read_b128 v[178:181], v145 offset:33792
	ds_read_b128 v[182:185], v145 offset:34816
	ds_read_b128 v[186:189], v145 offset:35840
	ds_read_b128 v[190:193], v145 offset:36864
	ds_read_b128 v[202:205], v145 offset:37888
	ds_read_b128 v[206:209], v145 offset:38912
	ds_read_b128 v[210:213], v145 offset:39936
	global_load_lds_dwordx4 v[218:219], off
	v_lshl_add_u64 v[218:219], s[0:1], 0, v[130:131]
	s_mov_b32 m0, s83
	s_nop 0
	global_load_lds_dwordx4 v[218:219], off
	s_waitcnt vmcnt(8)
	s_waitcnt lgkmcnt(0)
	s_barrier
	s_setprio 1
	s_waitcnt lgkmcnt(0)
	v_mfma_f32_16x16x32_bf16 v[126:129], v[136:139], v[174:177], v[126:129]
	v_mfma_f32_16x16x32_bf16 v[122:125], v[150:153], v[174:177], v[122:125]
	v_mfma_f32_16x16x32_bf16 v[110:113], v[136:139], v[182:185], v[110:113]
	v_mfma_f32_16x16x32_bf16 v[106:109], v[150:153], v[182:185], v[106:109]
	v_mfma_f32_16x16x32_bf16 v[94:97], v[136:139], v[190:193], v[94:97]
	v_mfma_f32_16x16x32_bf16 v[90:93], v[150:153], v[190:193], v[90:93]
	v_mfma_f32_16x16x32_bf16 v[78:81], v[136:139], v[206:209], v[78:81]
	v_mfma_f32_16x16x32_bf16 v[74:77], v[150:153], v[206:209], v[74:77]
	v_mfma_f32_16x16x32_bf16 v[126:129], v[146:149], v[178:181], v[126:129]
	v_mfma_f32_16x16x32_bf16 v[122:125], v[154:157], v[178:181], v[122:125]
	v_mfma_f32_16x16x32_bf16 v[110:113], v[146:149], v[186:189], v[110:113]
	v_mfma_f32_16x16x32_bf16 v[106:109], v[154:157], v[186:189], v[106:109]
	v_mfma_f32_16x16x32_bf16 v[94:97], v[146:149], v[202:205], v[94:97]
	v_mfma_f32_16x16x32_bf16 v[90:93], v[154:157], v[202:205], v[90:93]
	v_mfma_f32_16x16x32_bf16 v[78:81], v[146:149], v[210:213], v[78:81]
	v_mfma_f32_16x16x32_bf16 v[74:77], v[154:157], v[210:213], v[74:77]
	v_mfma_f32_16x16x32_bf16 v[118:121], v[158:161], v[174:177], v[118:121]
	v_mfma_f32_16x16x32_bf16 v[114:117], v[166:169], v[174:177], v[114:117]
	v_mfma_f32_16x16x32_bf16 v[102:105], v[158:161], v[182:185], v[102:105]
	v_mfma_f32_16x16x32_bf16 v[98:101], v[166:169], v[182:185], v[98:101]
	v_mfma_f32_16x16x32_bf16 v[86:89], v[158:161], v[190:193], v[86:89]
	v_mfma_f32_16x16x32_bf16 v[82:85], v[166:169], v[190:193], v[82:85]
	v_mfma_f32_16x16x32_bf16 v[70:73], v[158:161], v[206:209], v[70:73]
	v_mfma_f32_16x16x32_bf16 v[66:69], v[166:169], v[206:209], v[66:69]
	v_mfma_f32_16x16x32_bf16 v[118:121], v[162:165], v[178:181], v[118:121]
	v_mfma_f32_16x16x32_bf16 v[114:117], v[170:173], v[178:181], v[114:117]
	v_mfma_f32_16x16x32_bf16 v[102:105], v[162:165], v[186:189], v[102:105]
	v_mfma_f32_16x16x32_bf16 v[98:101], v[170:173], v[186:189], v[98:101]
	v_mfma_f32_16x16x32_bf16 v[86:89], v[162:165], v[202:205], v[86:89]
	v_mfma_f32_16x16x32_bf16 v[82:85], v[170:173], v[202:205], v[82:85]
	v_mfma_f32_16x16x32_bf16 v[70:73], v[162:165], v[210:213], v[70:73]
	v_mfma_f32_16x16x32_bf16 v[66:69], v[170:173], v[210:213], v[66:69]
	s_setprio 0
	s_barrier
; #define PG8_STAGE(bufoff, gbase, voff) do { _Pragma("unroll") for (int _i = 0; _i < 2; ++_i) \
;         __builtin_amdgcn_global_load_lds((const unsigned*)((const char*)(gbase) + (voff)[_i]), (LAS unsigned*)(lds + (bufoff) + ldsw + _i * 8192), 16, 0, 0); } while (0)
; #define PG8_LDA(dst, b, h) do { _Pragma("unroll") for (int m = 0; m < 4; ++m) _Pragma("unroll") for (int k = 0; k < 2; ++k) dst[m][k] = *(const LAS bf16x8*)(lds + PG8_SA(b, h) + aoff + m * 2048 + k * 1024); } while (0)
; #define PG8_MMA(ai, bj, At, Bt) do { __builtin_amdgcn_s_setprio(1); _Pragma("unroll") for (int m = 0; m < 4; ++m) _Pragma("unroll") for (int n = 0; n < 2; ++n) _Pragma("unroll") for (int k = 0; k < 2; ++k) \
;         acc[ai][bj][m][n] = __builtin_amdgcn_mfma_f32_16x16x32_bf16(Bt[n][k], At[m][k], acc[ai][bj][m][n], 0, 0, 0); __builtin_amdgcn_s_setprio(0); } while (0)
; #define PG8_WAIT_V(n) asm volatile("s_waitcnt vmcnt(" #n ")" ::: "memory")
; #define PG8_WAIT_L(n) asm volatile("s_waitcnt lgkmcnt(" #n ")" ::: "memory")
; #define PG8_BAR __builtin_amdgcn_s_barrier()
; #define PG8_SCHED __builtin_amdgcn_sched_barrier(0)
; template <class Epi, bool ALIGN_EPI, int M_, int N_, int K_, int LDA, int LDB>
; __device__ __forceinline__ void gemm_phase(LAS unsigned char* lds, const int tid_in, const int G_in, const int bx_in, const Gemm g, const Epi& E) {
;     ...
;             PG8_LDA(At, 1, 1); PG8_STAGE(PG8_SB(1, 0), b3, voffB); PG8_STAGE(PG8_SB(1, 1), b3 + hstepB, voffB); PG8_STAGE(PG8_SA(1, 0), a3, voffA);
;             PG8_WAIT_V(8); PG8_WAIT_L(0); PG8_BAR; PG8_MMA(1, 0, At, B0); PG8_MMA(1, 1, At, B1); PG8_BAR; PG8_SCHED;
;         }
;         if constexpr (ALIGN_EPI) { if (wr == 0) PG8_BAR; }
	s_add_i32 s0, s24, s63
	v_lshl_add_u64 v[140:141], v[140:141], 0, s[54:55]
	s_mov_b32 m0, s0
	ds_read_b128 v[174:177], v145 offset:49152
	ds_read_b128 v[178:181], v145 offset:50176
	ds_read_b128 v[182:185], v145 offset:51200
	ds_read_b128 v[186:189], v145 offset:52224
	ds_read_b128 v[190:193], v145 offset:53248
	ds_read_b128 v[202:205], v145 offset:54272
	ds_read_b128 v[206:209], v145 offset:55296
	ds_read_b128 v[210:213], v145 offset:56320
	global_load_lds_dwordx4 v[140:141], off
	s_add_i32 m0, s0, 0x2000
	s_add_u32 s0, s48, 0x100080
	v_lshl_add_u64 v[140:141], v[200:201], 0, s[54:55]
	s_addc_u32 s1, s49, 0
	s_add_i32 s24, s58, s63
	global_load_lds_dwordx4 v[140:141], off
	v_lshl_add_u64 v[140:141], s[0:1], 0, v[0:1]
	s_mov_b32 m0, s24
	s_nop 0
	global_load_lds_dwordx4 v[140:141], off
	v_lshl_add_u64 v[140:141], s[0:1], 0, v[130:131]
	s_add_i32 m0, s24, 0x2000
	s_nop 0
	global_load_lds_dwordx4 v[140:141], off
	v_lshl_add_u64 v[140:141], v[214:215], 0, s[54:55]
	s_mov_b32 m0, s84
	s_nop 0
	global_load_lds_dwordx4 v[140:141], off
	v_lshl_add_u64 v[140:141], v[216:217], 0, s[54:55]
	s_mov_b32 m0, s85
	s_nop 0
	global_load_lds_dwordx4 v[140:141], off
	s_waitcnt vmcnt(8)
	s_waitcnt lgkmcnt(0)
	s_barrier
	s_setprio 1
	s_waitcnt lgkmcnt(0)
	v_mfma_f32_16x16x32_bf16 v[62:65], v[136:139], v[174:177], v[62:65]
	v_mfma_f32_16x16x32_bf16 v[58:61], v[150:153], v[174:177], v[58:61]
	v_mfma_f32_16x16x32_bf16 v[46:49], v[136:139], v[182:185], v[46:49]
	v_mfma_f32_16x16x32_bf16 v[42:45], v[150:153], v[182:185], v[42:45]
	v_mfma_f32_16x16x32_bf16 v[30:33], v[136:139], v[190:193], v[30:33]
	v_mfma_f32_16x16x32_bf16 v[26:29], v[150:153], v[190:193], v[26:29]
	v_mfma_f32_16x16x32_bf16 v[14:17], v[136:139], v[206:209], v[14:17]
	v_mfma_f32_16x16x32_bf16 v[10:13], v[150:153], v[206:209], v[10:13]
	v_mfma_f32_16x16x32_bf16 v[62:65], v[146:149], v[178:181], v[62:65]
	v_mfma_f32_16x16x32_bf16 v[58:61], v[154:157], v[178:181], v[58:61]
	v_mfma_f32_16x16x32_bf16 v[46:49], v[146:149], v[186:189], v[46:49]
	v_mfma_f32_16x16x32_bf16 v[42:45], v[154:157], v[186:189], v[42:45]
	v_mfma_f32_16x16x32_bf16 v[30:33], v[146:149], v[202:205], v[30:33]
	v_mfma_f32_16x16x32_bf16 v[26:29], v[154:157], v[202:205], v[26:29]
	v_mfma_f32_16x16x32_bf16 v[14:17], v[146:149], v[210:213], v[14:17]
	v_mfma_f32_16x16x32_bf16 v[10:13], v[154:157], v[210:213], v[10:13]
	v_mfma_f32_16x16x32_bf16 v[54:57], v[158:161], v[174:177], v[54:57]
	v_mfma_f32_16x16x32_bf16 v[50:53], v[166:169], v[174:177], v[50:53]
	v_mfma_f32_16x16x32_bf16 v[38:41], v[158:161], v[182:185], v[38:41]
	v_mfma_f32_16x16x32_bf16 v[34:37], v[166:169], v[182:185], v[34:37]
	v_mfma_f32_16x16x32_bf16 v[22:25], v[158:161], v[190:193], v[22:25]
	v_mfma_f32_16x16x32_bf16 v[18:21], v[166:169], v[190:193], v[18:21]
	v_mfma_f32_16x16x32_bf16 v[6:9], v[158:161], v[206:209], v[6:9]
	v_mfma_f32_16x16x32_bf16 v[2:5], v[166:169], v[206:209], v[2:5]
	v_mfma_f32_16x16x32_bf16 v[54:57], v[162:165], v[178:181], v[54:57]
	v_mfma_f32_16x16x32_bf16 v[50:53], v[170:173], v[178:181], v[50:53]
	v_mfma_f32_16x16x32_bf16 v[38:41], v[162:165], v[186:189], v[38:41]
	v_mfma_f32_16x16x32_bf16 v[34:37], v[170:173], v[186:189], v[34:37]
	v_mfma_f32_16x16x32_bf16 v[22:25], v[162:165], v[202:205], v[22:25]
	v_mfma_f32_16x16x32_bf16 v[18:21], v[170:173], v[202:205], v[18:21]
	v_mfma_f32_16x16x32_bf16 v[6:9], v[162:165], v[210:213], v[6:9]
	v_mfma_f32_16x16x32_bf16 v[2:5], v[170:173], v[210:213], v[2:5]
	s_setprio 0
	s_barrier
	s_add_i32 s92, s92, 2
	s_add_u32 s46, s46, 0x100
	s_addc_u32 s47, s47, 0
	s_add_u32 s90, s90, 0x100
	s_addc_u32 s91, s91, 0
	s_cmp_gt_u32 s92, 61
	s_cbranch_scc0 .LBB0_527
	s_and_b64 vcc, exec, s[12:13]
	s_cbranch_vccz .LBB0_530
	s_barrier

; #define PG8_STAGE(bufoff, gbase, voff) do { _Pragma("unroll") for (int _i = 0; _i < 2; ++_i) \
;         __builtin_amdgcn_global_load_lds((const unsigned*)((const char*)(gbase) + (voff)[_i]), (LAS unsigned*)(lds + (bufoff) + ldsw + _i * 8192), 16, 0, 0); } while (0)
; #define PG8_LDA(dst, b, h) do { _Pragma("unroll") for (int m = 0; m < 4; ++m) _Pragma("unroll") for (int k = 0; k < 2; ++k) dst[m][k] = *(const LAS bf16x8*)(lds + PG8_SA(b, h) + aoff + m * 2048 + k * 1024); } while (0)
; #define PG8_LDB(dst, b, h) do { _Pragma("unroll") for (int n = 0; n < 2; ++n) _Pragma("unroll") for (int k = 0; k < 2; ++k) dst[n][k] = *(const LAS bf16x8*)(lds + PG8_SB(b, h) + boff + n * 2048 + k * 1024); } while (0)
; #define PG8_MMA(ai, bj, At, Bt) do { __builtin_amdgcn_s_setprio(1); _Pragma("unroll") for (int m = 0; m < 4; ++m) _Pragma("unroll") for (int n = 0; n < 2; ++n) _Pragma("unroll") for (int k = 0; k < 2; ++k) \
;         acc[ai][bj][m][n] = __builtin_amdgcn_mfma_f32_16x16x32_bf16(Bt[n][k], At[m][k], acc[ai][bj][m][n], 0, 0, 0); __builtin_amdgcn_s_setprio(0); } while (0)
; #define PG8_WAIT_V(n) asm volatile("s_waitcnt vmcnt(" #n ")" ::: "memory")
; #define PG8_WAIT_L(n) asm volatile("s_waitcnt lgkmcnt(" #n ")" ::: "memory")
; #define PG8_BAR __builtin_amdgcn_s_barrier()
; #define PG8_SCHED __builtin_amdgcn_sched_barrier(0)
; template <class Epi, bool ALIGN_EPI, int M_, int N_, int K_, int LDA, int LDB>
; __device__ __forceinline__ void gemm_phase(LAS unsigned char* lds, const int tid_in, const int G_in, const int bx_in, const Gemm g, const Epi& E) {
;     ...
;             const bool last = (t == nt - 2);
;             const char* a1 = cA + (size_t)(t + 1) * kstep;
;             const char* a2 = last ? nA : cA + (size_t)(t + 2) * kstep; const char* b2 = last ? nB : cB + (size_t)(t + 2) * kstep;
;             const char* a3 = a2 + kstep; const char* b3 = b2 + kstep;
;             PG8_LDB(B0, 0, 0); PG8_LDB(B1, 0, 1); PG8_SCHED; PG8_LDA(At, 0, 0); PG8_STAGE(PG8_SA(1, 1), a1 + hstepA, voffA);
;             PG8_WAIT_V(8); PG8_WAIT_L(0); PG8_BAR; PG8_MMA(0, 0, At, B0); PG8_MMA(0, 1, At, B1); PG8_BAR; PG8_SCHED;
;             PG8_LDA(At, 0, 1); PG8_STAGE(PG8_SB(0, 0), b2, voffB); PG8_STAGE(PG8_SB(0, 1), b2 + hstepB, voffB); PG8_STAGE(PG8_SA(0, 0), a2, voffA);
;             PG8_WAIT_V(8); PG8_WAIT_L(0); PG8_BAR; PG8_MMA(1, 0, At, B0); PG8_MMA(1, 1, At, B1); PG8_BAR; PG8_SCHED;
.LBB0_555:
	s_add_u32 s0, s86, 0xfff00080
	s_addc_u32 s1, s87, -1
	s_add_i32 s24, 0, 0x10000
	s_cmp_eq_u32 vcc_lo, 60
	s_cselect_b32 s63, s45, s1
	s_cselect_b32 s62, s51, s0
	s_cselect_b32 s61, s43, s89
	s_cselect_b32 s60, s97, s88
	s_add_i32 s58, 0, 0x14000
	v_add_u32_e32 v154, s24, v141
	v_add_u32_e32 v170, s58, v141
	ds_read_b128 v[136:139], v154
	ds_read_b128 v[146:149], v154 offset:1024
	ds_read_b128 v[150:153], v154 offset:2048
	ds_read_b128 v[154:157], v154 offset:3072
	ds_read_b128 v[158:161], v170
	ds_read_b128 v[162:165], v170 offset:1024
	ds_read_b128 v[166:169], v170 offset:2048
	ds_read_b128 v[170:173], v170 offset:3072
	v_lshl_add_u64 v[200:201], s[86:87], 0, v[132:133]
	s_add_i32 m0, s85, 0xc000
	ds_read_b128 v[174:177], v145
	ds_read_b128 v[178:181], v145 offset:1024
	ds_read_b128 v[182:185], v145 offset:2048
	ds_read_b128 v[186:189], v145 offset:3072
	ds_read_b128 v[190:193], v145 offset:4096
	ds_read_b128 v[202:205], v145 offset:5120
	ds_read_b128 v[206:209], v145 offset:6144
	ds_read_b128 v[210:213], v145 offset:7168
	global_load_lds_dwordx4 v[200:201], off
	v_lshl_add_u64 v[200:201], s[86:87], 0, v[134:135]
	s_add_i32 m0, s85, 0xe000
	s_nop 0
	global_load_lds_dwordx4 v[200:201], off
	s_waitcnt vmcnt(8)
	s_waitcnt lgkmcnt(0)
	s_barrier
	s_setprio 1
	s_waitcnt lgkmcnt(0)
	v_mfma_f32_16x16x32_bf16 v[126:129], v[136:139], v[174:177], v[126:129]
	v_mfma_f32_16x16x32_bf16 v[122:125], v[150:153], v[174:177], v[122:125]
	v_mfma_f32_16x16x32_bf16 v[110:113], v[136:139], v[182:185], v[110:113]
	v_mfma_f32_16x16x32_bf16 v[106:109], v[150:153], v[182:185], v[106:109]
	v_mfma_f32_16x16x32_bf16 v[94:97], v[136:139], v[190:193], v[94:97]
	v_mfma_f32_16x16x32_bf16 v[90:93], v[150:153], v[190:193], v[90:93]
	v_mfma_f32_16x16x32_bf16 v[78:81], v[136:139], v[206:209], v[78:81]
	v_mfma_f32_16x16x32_bf16 v[74:77], v[150:153], v[206:209], v[74:77]
	v_mfma_f32_16x16x32_bf16 v[126:129], v[146:149], v[178:181], v[126:129]
	v_mfma_f32_16x16x32_bf16 v[122:125], v[154:157], v[178:181], v[122:125]
	v_mfma_f32_16x16x32_bf16 v[110:113], v[146:149], v[186:189], v[110:113]
	v_mfma_f32_16x16x32_bf16 v[106:109], v[154:157], v[186:189], v[106:109]
	v_mfma_f32_16x16x32_bf16 v[94:97], v[146:149], v[202:205], v[94:97]
	v_mfma_f32_16x16x32_bf16 v[90:93], v[154:157], v[202:205], v[90:93]
	v_mfma_f32_16x16x32_bf16 v[78:81], v[146:149], v[210:213], v[78:81]
	v_mfma_f32_16x16x32_bf16 v[74:77], v[154:157], v[210:213], v[74:77]
	v_mfma_f32_16x16x32_bf16 v[118:121], v[158:161], v[174:177], v[118:121]
	v_mfma_f32_16x16x32_bf16 v[114:117], v[166:169], v[174:177], v[114:117]
	v_mfma_f32_16x16x32_bf16 v[102:105], v[158:161], v[182:185], v[102:105]
	v_mfma_f32_16x16x32_bf16 v[98:101], v[166:169], v[182:185], v[98:101]
	v_mfma_f32_16x16x32_bf16 v[86:89], v[158:161], v[190:193], v[86:89]
	v_mfma_f32_16x16x32_bf16 v[82:85], v[166:169], v[190:193], v[82:85]
	v_mfma_f32_16x16x32_bf16 v[70:73], v[158:161], v[206:209], v[70:73]
	v_mfma_f32_16x16x32_bf16 v[66:69], v[166:169], v[206:209], v[66:69]
	v_mfma_f32_16x16x32_bf16 v[118:121], v[162:165], v[178:181], v[118:121]
	v_mfma_f32_16x16x32_bf16 v[114:117], v[170:173], v[178:181], v[114:117]
	v_mfma_f32_16x16x32_bf16 v[102:105], v[162:165], v[186:189], v[102:105]
	v_mfma_f32_16x16x32_bf16 v[98:101], v[170:173], v[186:189], v[98:101]
	v_mfma_f32_16x16x32_bf16 v[86:89], v[162:165], v[202:205], v[86:89]
	v_mfma_f32_16x16x32_bf16 v[82:85], v[170:173], v[202:205], v[82:85]
	v_mfma_f32_16x16x32_bf16 v[70:73], v[162:165], v[210:213], v[70:73]
	v_mfma_f32_16x16x32_bf16 v[66:69], v[170:173], v[210:213], v[66:69]
	s_setprio 0
	s_barrier
	s_add_i32 s0, s24, s83
	v_lshl_add_u64 v[200:201], s[60:61], 0, v[0:1]
	s_mov_b32 m0, s0
	ds_read_b128 v[174:177], v145 offset:16384
	ds_read_b128 v[178:181], v145 offset:17408
	ds_read_b128 v[182:185], v145 offset:18432
	ds_read_b128 v[186:189], v145 offset:19456
	ds_read_b128 v[190:193], v145 offset:20480
	ds_read_b128 v[202:205], v145 offset:21504
	ds_read_b128 v[206:209], v145 offset:22528
	ds_read_b128 v[210:213], v145 offset:23552
	global_load_lds_dwordx4 v[200:201], off
	s_add_i32 m0, s0, 0x2000
	s_add_u32 s0, s60, 0x100000
	v_lshl_add_u64 v[214:215], s[60:61], 0, v[130:131]
	s_addc_u32 s1, s61, 0
	s_add_i32 s24, s58, s83
	global_load_lds_dwordx4 v[214:215], off
	v_lshl_add_u64 v[216:217], s[0:1], 0, v[0:1]
	s_mov_b32 m0, s24
	v_lshl_add_u64 v[218:219], s[62:63], 0, v[130:131]
	global_load_lds_dwordx4 v[216:217], off
	v_lshl_add_u64 v[216:217], s[0:1], 0, v[130:131]
	s_add_i32 m0, s24, 0x2000
	s_nop 0
	global_load_lds_dwordx4 v[216:217], off
	v_lshl_add_u64 v[216:217], s[62:63], 0, v[0:1]
	s_mov_b32 m0, s85
	s_nop 0
	global_load_lds_dwordx4 v[216:217], off
	s_mov_b32 m0, s90
	s_nop 0
	global_load_lds_dwordx4 v[218:219], off
	s_waitcnt vmcnt(8)
	s_waitcnt lgkmcnt(0)
	s_barrier
; #define PG8_STAGE(bufoff, gbase, voff) do { _Pragma("unroll") for (int _i = 0; _i < 2; ++_i) \
;         __builtin_amdgcn_global_load_lds((const unsigned*)((const char*)(gbase) + (voff)[_i]), (LAS unsigned*)(lds + (bufoff) + ldsw + _i * 8192), 16, 0, 0); } while (0)
; #define PG8_LDA(dst, b, h) do { _Pragma("unroll") for (int m = 0; m < 4; ++m) _Pragma("unroll") for (int k = 0; k < 2; ++k) dst[m][k] = *(const LAS bf16x8*)(lds + PG8_SA(b, h) + aoff + m * 2048 + k * 1024); } while (0)
; #define PG8_LDB(dst, b, h) do { _Pragma("unroll") for (int n = 0; n < 2; ++n) _Pragma("unroll") for (int k = 0; k < 2; ++k) dst[n][k] = *(const LAS bf16x8*)(lds + PG8_SB(b, h) + boff + n * 2048 + k * 1024); } while (0)
; #define PG8_MMA(ai, bj, At, Bt) do { __builtin_amdgcn_s_setprio(1); _Pragma("unroll") for (int m = 0; m < 4; ++m) _Pragma("unroll") for (int n = 0; n < 2; ++n) _Pragma("unroll") for (int k = 0; k < 2; ++k) \
;         acc[ai][bj][m][n] = __builtin_amdgcn_mfma_f32_16x16x32_bf16(Bt[n][k], At[m][k], acc[ai][bj][m][n], 0, 0, 0); __builtin_amdgcn_s_setprio(0); } while (0)
; #define PG8_WAIT_V(n) asm volatile("s_waitcnt vmcnt(" #n ")" ::: "memory")
; #define PG8_WAIT_L(n) asm volatile("s_waitcnt lgkmcnt(" #n ")" ::: "memory")
; #define PG8_BAR __builtin_amdgcn_s_barrier()
; #define PG8_SCHED __builtin_amdgcn_sched_barrier(0)
; template <class Epi, bool ALIGN_EPI, int M_, int N_, int K_, int LDA, int LDB>
; __device__ __forceinline__ void gemm_phase(LAS unsigned char* lds, const int tid_in, const int G_in, const int bx_in, const Gemm g, const Epi& E) {
;     ...
;             PG8_WAIT_V(8); PG8_WAIT_L(0); PG8_BAR; PG8_MMA(1, 0, At, B0); PG8_MMA(1, 1, At, B1); PG8_BAR; PG8_SCHED;
;             PG8_LDB(B0, 1, 0); PG8_LDB(B1, 1, 1); PG8_SCHED; PG8_LDA(At, 1, 0); PG8_STAGE(PG8_SA(0, 1), a2 + hstepA, voffA);
;             PG8_WAIT_V(8); PG8_WAIT_L(0); PG8_BAR; PG8_MMA(0, 0, At, B0); PG8_MMA(0, 1, At, B1); PG8_BAR; PG8_SCHED;
	s_setprio 1
	s_waitcnt lgkmcnt(0)
	v_mfma_f32_16x16x32_bf16 v[62:65], v[136:139], v[174:177], v[62:65]
	v_mfma_f32_16x16x32_bf16 v[58:61], v[150:153], v[174:177], v[58:61]
	v_mfma_f32_16x16x32_bf16 v[46:49], v[136:139], v[182:185], v[46:49]
	v_mfma_f32_16x16x32_bf16 v[42:45], v[150:153], v[182:185], v[42:45]
	v_mfma_f32_16x16x32_bf16 v[30:33], v[136:139], v[190:193], v[30:33]
	v_mfma_f32_16x16x32_bf16 v[26:29], v[150:153], v[190:193], v[26:29]
	v_mfma_f32_16x16x32_bf16 v[14:17], v[136:139], v[206:209], v[14:17]
	v_mfma_f32_16x16x32_bf16 v[10:13], v[150:153], v[206:209], v[10:13]
	v_mfma_f32_16x16x32_bf16 v[62:65], v[146:149], v[178:181], v[62:65]
	v_mfma_f32_16x16x32_bf16 v[58:61], v[154:157], v[178:181], v[58:61]
	v_mfma_f32_16x16x32_bf16 v[46:49], v[146:149], v[186:189], v[46:49]
	v_mfma_f32_16x16x32_bf16 v[42:45], v[154:157], v[186:189], v[42:45]
	v_mfma_f32_16x16x32_bf16 v[30:33], v[146:149], v[202:205], v[30:33]
	v_mfma_f32_16x16x32_bf16 v[26:29], v[154:157], v[202:205], v[26:29]
	v_mfma_f32_16x16x32_bf16 v[14:17], v[146:149], v[210:213], v[14:17]
	v_mfma_f32_16x16x32_bf16 v[10:13], v[154:157], v[210:213], v[10:13]
	v_mfma_f32_16x16x32_bf16 v[54:57], v[158:161], v[174:177], v[54:57]
	v_mfma_f32_16x16x32_bf16 v[50:53], v[166:169], v[174:177], v[50:53]
	v_mfma_f32_16x16x32_bf16 v[38:41], v[158:161], v[182:185], v[38:41]
	v_mfma_f32_16x16x32_bf16 v[34:37], v[166:169], v[182:185], v[34:37]
	v_mfma_f32_16x16x32_bf16 v[22:25], v[158:161], v[190:193], v[22:25]
	v_mfma_f32_16x16x32_bf16 v[18:21], v[166:169], v[190:193], v[18:21]
	v_mfma_f32_16x16x32_bf16 v[6:9], v[158:161], v[206:209], v[6:9]
	v_mfma_f32_16x16x32_bf16 v[2:5], v[166:169], v[206:209], v[2:5]
	v_mfma_f32_16x16x32_bf16 v[54:57], v[162:165], v[178:181], v[54:57]
	v_mfma_f32_16x16x32_bf16 v[50:53], v[170:173], v[178:181], v[50:53]
	v_mfma_f32_16x16x32_bf16 v[38:41], v[162:165], v[186:189], v[38:41]
	v_mfma_f32_16x16x32_bf16 v[34:37], v[170:173], v[186:189], v[34:37]
	v_mfma_f32_16x16x32_bf16 v[22:25], v[162:165], v[202:205], v[22:25]
	v_mfma_f32_16x16x32_bf16 v[18:21], v[170:173], v[202:205], v[18:21]
	v_mfma_f32_16x16x32_bf16 v[6:9], v[162:165], v[210:213], v[6:9]
	v_mfma_f32_16x16x32_bf16 v[2:5], v[170:173], v[210:213], v[2:5]
	s_setprio 0
	s_barrier
	s_add_i32 s24, 0, 0x18000
	s_add_i32 s58, 0, 0x1c000
	v_add_u32_e32 v154, s24, v141
	v_add_u32_e32 v170, s58, v141
	ds_read_b128 v[136:139], v154
	ds_read_b128 v[146:149], v154 offset:1024
	ds_read_b128 v[150:153], v154 offset:2048
	ds_read_b128 v[154:157], v154 offset:3072
	ds_read_b128 v[158:161], v170
	ds_read_b128 v[162:165], v170 offset:1024
	ds_read_b128 v[166:169], v170 offset:2048
	ds_read_b128 v[170:173], v170 offset:3072
	s_add_u32 s0, s62, 0x100000
	s_addc_u32 s1, s63, 0
	s_mov_b32 m0, s91
	v_lshl_add_u64 v[220:221], s[0:1], 0, v[0:1]
	ds_read_b128 v[174:177], v145 offset:32768
	ds_read_b128 v[178:181], v145 offset:33792
	ds_read_b128 v[182:185], v145 offset:34816
	ds_read_b128 v[186:189], v145 offset:35840
	ds_read_b128 v[190:193], v145 offset:36864
	ds_read_b128 v[202:205], v145 offset:37888
	ds_read_b128 v[206:209], v145 offset:38912
	ds_read_b128 v[210:213], v145 offset:39936
	global_load_lds_dwordx4 v[220:221], off
	v_lshl_add_u64 v[220:221], s[0:1], 0, v[130:131]
	s_mov_b32 m0, s92
	s_nop 0
	global_load_lds_dwordx4 v[220:221], off
	s_waitcnt vmcnt(8)
	s_waitcnt lgkmcnt(0)
	s_barrier
	s_setprio 1
	s_waitcnt lgkmcnt(0)
	v_mfma_f32_16x16x32_bf16 v[126:129], v[136:139], v[174:177], v[126:129]
	v_mfma_f32_16x16x32_bf16 v[122:125], v[150:153], v[174:177], v[122:125]
	v_mfma_f32_16x16x32_bf16 v[110:113], v[136:139], v[182:185], v[110:113]
	v_mfma_f32_16x16x32_bf16 v[106:109], v[150:153], v[182:185], v[106:109]
	v_mfma_f32_16x16x32_bf16 v[94:97], v[136:139], v[190:193], v[94:97]
	v_mfma_f32_16x16x32_bf16 v[90:93], v[150:153], v[190:193], v[90:93]
	v_mfma_f32_16x16x32_bf16 v[78:81], v[136:139], v[206:209], v[78:81]
	v_mfma_f32_16x16x32_bf16 v[74:77], v[150:153], v[206:209], v[74:77]
	v_mfma_f32_16x16x32_bf16 v[126:129], v[146:149], v[178:181], v[126:129]
	v_mfma_f32_16x16x32_bf16 v[122:125], v[154:157], v[178:181], v[122:125]
	v_mfma_f32_16x16x32_bf16 v[110:113], v[146:149], v[186:189], v[110:113]
	v_mfma_f32_16x16x32_bf16 v[106:109], v[154:157], v[186:189], v[106:109]
	v_mfma_f32_16x16x32_bf16 v[94:97], v[146:149], v[202:205], v[94:97]
	v_mfma_f32_16x16x32_bf16 v[90:93], v[154:157], v[202:205], v[90:93]
	v_mfma_f32_16x16x32_bf16 v[78:81], v[146:149], v[210:213], v[78:81]
	v_mfma_f32_16x16x32_bf16 v[74:77], v[154:157], v[210:213], v[74:77]
	v_mfma_f32_16x16x32_bf16 v[118:121], v[158:161], v[174:177], v[118:121]
	v_mfma_f32_16x16x32_bf16 v[114:117], v[166:169], v[174:177], v[114:117]
	v_mfma_f32_16x16x32_bf16 v[102:105], v[158:161], v[182:185], v[102:105]
	v_mfma_f32_16x16x32_bf16 v[98:101], v[166:169], v[182:185], v[98:101]
	v_mfma_f32_16x16x32_bf16 v[86:89], v[158:161], v[190:193], v[86:89]
	v_mfma_f32_16x16x32_bf16 v[82:85], v[166:169], v[190:193], v[82:85]
	v_mfma_f32_16x16x32_bf16 v[70:73], v[158:161], v[206:209], v[70:73]
	v_mfma_f32_16x16x32_bf16 v[66:69], v[166:169], v[206:209], v[66:69]
	v_mfma_f32_16x16x32_bf16 v[118:121], v[162:165], v[178:181], v[118:121]
	v_mfma_f32_16x16x32_bf16 v[114:117], v[170:173], v[178:181], v[114:117]
	v_mfma_f32_16x16x32_bf16 v[102:105], v[162:165], v[186:189], v[102:105]
	v_mfma_f32_16x16x32_bf16 v[98:101], v[170:173], v[186:189], v[98:101]
	v_mfma_f32_16x16x32_bf16 v[86:89], v[162:165], v[202:205], v[86:89]
	v_mfma_f32_16x16x32_bf16 v[82:85], v[170:173], v[202:205], v[82:85]
	v_mfma_f32_16x16x32_bf16 v[70:73], v[162:165], v[210:213], v[70:73]
	v_mfma_f32_16x16x32_bf16 v[66:69], v[170:173], v[210:213], v[66:69]
	s_setprio 0
	s_barrier
; #define PG8_STAGE(bufoff, gbase, voff) do { _Pragma("unroll") for (int _i = 0; _i < 2; ++_i) \
;         __builtin_amdgcn_global_load_lds((const unsigned*)((const char*)(gbase) + (voff)[_i]), (LAS unsigned*)(lds + (bufoff) + ldsw + _i * 8192), 16, 0, 0); } while (0)
; #define PG8_LDA(dst, b, h) do { _Pragma("unroll") for (int m = 0; m < 4; ++m) _Pragma("unroll") for (int k = 0; k < 2; ++k) dst[m][k] = *(const LAS bf16x8*)(lds + PG8_SA(b, h) + aoff + m * 2048 + k * 1024); } while (0)
; #define PG8_MMA(ai, bj, At, Bt) do { __builtin_amdgcn_s_setprio(1); _Pragma("unroll") for (int m = 0; m < 4; ++m) _Pragma("unroll") for (int n = 0; n < 2; ++n) _Pragma("unroll") for (int k = 0; k < 2; ++k) \
;         acc[ai][bj][m][n] = __builtin_amdgcn_mfma_f32_16x16x32_bf16(Bt[n][k], At[m][k], acc[ai][bj][m][n], 0, 0, 0); __builtin_amdgcn_s_setprio(0); } while (0)
; #define PG8_WAIT_V(n) asm volatile("s_waitcnt vmcnt(" #n ")" ::: "memory")
; #define PG8_WAIT_L(n) asm volatile("s_waitcnt lgkmcnt(" #n ")" ::: "memory")
; #define PG8_BAR __builtin_amdgcn_s_barrier()
; #define PG8_SCHED __builtin_amdgcn_sched_barrier(0)
; template <class Epi, bool ALIGN_EPI, int M_, int N_, int K_, int LDA, int LDB>
; __device__ __forceinline__ void gemm_phase(LAS unsigned char* lds, const int tid_in, const int G_in, const int bx_in, const Gemm g, const Epi& E) {
;     ...
;             PG8_LDA(At, 1, 1); PG8_STAGE(PG8_SB(1, 0), b3, voffB); PG8_STAGE(PG8_SB(1, 1), b3 + hstepB, voffB); PG8_STAGE(PG8_SA(1, 0), a3, voffA);
;             PG8_WAIT_V(8); PG8_WAIT_L(0); PG8_BAR; PG8_MMA(1, 0, At, B0); PG8_MMA(1, 1, At, B1); PG8_BAR; PG8_SCHED;
;         }
;         if constexpr (ALIGN_EPI) { if (wr == 0) PG8_BAR; }
	s_add_i32 s0, s24, s83
	v_lshl_add_u64 v[200:201], v[200:201], 0, s[54:55]
	s_mov_b32 m0, s0
	ds_read_b128 v[174:177], v145 offset:49152
	ds_read_b128 v[178:181], v145 offset:50176
	ds_read_b128 v[182:185], v145 offset:51200
	ds_read_b128 v[186:189], v145 offset:52224
	ds_read_b128 v[190:193], v145 offset:53248
	ds_read_b128 v[202:205], v145 offset:54272
	ds_read_b128 v[206:209], v145 offset:55296
	ds_read_b128 v[210:213], v145 offset:56320
	global_load_lds_dwordx4 v[200:201], off
	s_add_i32 m0, s0, 0x2000
	s_add_u32 s0, s60, 0x100080
	v_lshl_add_u64 v[200:201], v[214:215], 0, s[54:55]
	s_addc_u32 s1, s61, 0
	s_add_i32 s24, s58, s83
	global_load_lds_dwordx4 v[200:201], off
	v_lshl_add_u64 v[200:201], s[0:1], 0, v[0:1]
	s_mov_b32 m0, s24
	s_nop 0
	global_load_lds_dwordx4 v[200:201], off
	v_lshl_add_u64 v[200:201], s[0:1], 0, v[130:131]
	s_add_i32 m0, s24, 0x2000
	s_nop 0
	global_load_lds_dwordx4 v[200:201], off
	v_lshl_add_u64 v[200:201], v[216:217], 0, s[54:55]
	s_mov_b32 m0, s93
	s_nop 0
	global_load_lds_dwordx4 v[200:201], off
	v_lshl_add_u64 v[200:201], v[218:219], 0, s[54:55]
	s_mov_b32 m0, s94
	s_nop 0
	global_load_lds_dwordx4 v[200:201], off
	s_waitcnt vmcnt(8)
	s_waitcnt lgkmcnt(0)
	s_barrier
	s_setprio 1
	s_waitcnt lgkmcnt(0)
	v_mfma_f32_16x16x32_bf16 v[62:65], v[136:139], v[174:177], v[62:65]
	v_mfma_f32_16x16x32_bf16 v[58:61], v[150:153], v[174:177], v[58:61]
	v_mfma_f32_16x16x32_bf16 v[46:49], v[136:139], v[182:185], v[46:49]
	v_mfma_f32_16x16x32_bf16 v[42:45], v[150:153], v[182:185], v[42:45]
	v_mfma_f32_16x16x32_bf16 v[30:33], v[136:139], v[190:193], v[30:33]
	v_mfma_f32_16x16x32_bf16 v[26:29], v[150:153], v[190:193], v[26:29]
	v_mfma_f32_16x16x32_bf16 v[14:17], v[136:139], v[206:209], v[14:17]
	v_mfma_f32_16x16x32_bf16 v[10:13], v[150:153], v[206:209], v[10:13]
	v_mfma_f32_16x16x32_bf16 v[62:65], v[146:149], v[178:181], v[62:65]
	v_mfma_f32_16x16x32_bf16 v[58:61], v[154:157], v[178:181], v[58:61]
	v_mfma_f32_16x16x32_bf16 v[46:49], v[146:149], v[186:189], v[46:49]
	v_mfma_f32_16x16x32_bf16 v[42:45], v[154:157], v[186:189], v[42:45]
	v_mfma_f32_16x16x32_bf16 v[30:33], v[146:149], v[202:205], v[30:33]
	v_mfma_f32_16x16x32_bf16 v[26:29], v[154:157], v[202:205], v[26:29]
	v_mfma_f32_16x16x32_bf16 v[14:17], v[146:149], v[210:213], v[14:17]
	v_mfma_f32_16x16x32_bf16 v[10:13], v[154:157], v[210:213], v[10:13]
	v_mfma_f32_16x16x32_bf16 v[54:57], v[158:161], v[174:177], v[54:57]
	v_mfma_f32_16x16x32_bf16 v[50:53], v[166:169], v[174:177], v[50:53]
	v_mfma_f32_16x16x32_bf16 v[38:41], v[158:161], v[182:185], v[38:41]
	v_mfma_f32_16x16x32_bf16 v[34:37], v[166:169], v[182:185], v[34:37]
	v_mfma_f32_16x16x32_bf16 v[22:25], v[158:161], v[190:193], v[22:25]
	v_mfma_f32_16x16x32_bf16 v[18:21], v[166:169], v[190:193], v[18:21]
	v_mfma_f32_16x16x32_bf16 v[6:9], v[158:161], v[206:209], v[6:9]
	v_mfma_f32_16x16x32_bf16 v[2:5], v[166:169], v[206:209], v[2:5]
	v_mfma_f32_16x16x32_bf16 v[54:57], v[162:165], v[178:181], v[54:57]
	v_mfma_f32_16x16x32_bf16 v[50:53], v[170:173], v[178:181], v[50:53]
	v_mfma_f32_16x16x32_bf16 v[38:41], v[162:165], v[186:189], v[38:41]
	v_mfma_f32_16x16x32_bf16 v[34:37], v[170:173], v[186:189], v[34:37]
	v_mfma_f32_16x16x32_bf16 v[22:25], v[162:165], v[202:205], v[22:25]
	v_mfma_f32_16x16x32_bf16 v[18:21], v[170:173], v[202:205], v[18:21]
	v_mfma_f32_16x16x32_bf16 v[6:9], v[162:165], v[210:213], v[6:9]
	v_mfma_f32_16x16x32_bf16 v[2:5], v[170:173], v[210:213], v[2:5]
	s_setprio 0
	s_barrier
	s_add_i32 vcc_lo, vcc_lo, 2
	s_add_u32 s86, s86, 0x100
	s_addc_u32 s87, s87, 0
	s_add_u32 s88, s88, 0x100
	s_addc_u32 s89, s89, 0
	s_cmp_gt_u32 vcc_lo, 61
	s_cbranch_scc0 .LBB0_555
	s_and_b64 vcc, exec, s[40:41]
	s_cbranch_vccz .LBB0_558
	s_barrier

; #define PG8_STAGE(bufoff, gbase, voff) do { _Pragma("unroll") for (int _i = 0; _i < 2; ++_i) \
;         __builtin_amdgcn_global_load_lds((const unsigned*)((const char*)(gbase) + (voff)[_i]), (LAS unsigned*)(lds + (bufoff) + ldsw + _i * 8192), 16, 0, 0); } while (0)
; #define PG8_LDA(dst, b, h) do { _Pragma("unroll") for (int m = 0; m < 4; ++m) _Pragma("unroll") for (int k = 0; k < 2; ++k) dst[m][k] = *(const LAS bf16x8*)(lds + PG8_SA(b, h) + aoff + m * 2048 + k * 1024); } while (0)
; #define PG8_LDB(dst, b, h) do { _Pragma("unroll") for (int n = 0; n < 2; ++n) _Pragma("unroll") for (int k = 0; k < 2; ++k) dst[n][k] = *(const LAS bf16x8*)(lds + PG8_SB(b, h) + boff + n * 2048 + k * 1024); } while (0)
; #define PG8_MMA(ai, bj, At, Bt) do { __builtin_amdgcn_s_setprio(1); _Pragma("unroll") for (int m = 0; m < 4; ++m) _Pragma("unroll") for (int n = 0; n < 2; ++n) _Pragma("unroll") for (int k = 0; k < 2; ++k) \
;         acc[ai][bj][m][n] = __builtin_amdgcn_mfma_f32_16x16x32_bf16(Bt[n][k], At[m][k], acc[ai][bj][m][n], 0, 0, 0); __builtin_amdgcn_s_setprio(0); } while (0)
; #define PG8_WAIT_V(n) asm volatile("s_waitcnt vmcnt(" #n ")" ::: "memory")
; #define PG8_WAIT_L(n) asm volatile("s_waitcnt lgkmcnt(" #n ")" ::: "memory")
; #define PG8_BAR __builtin_amdgcn_s_barrier()
; #define PG8_SCHED __builtin_amdgcn_sched_barrier(0)
; template <class Epi, bool ALIGN_EPI, int M_, int N_, int K_, int LDA, int LDB>
; __device__ __forceinline__ void gemm_phase(LAS unsigned char* lds, const int tid_in, const int G_in, const int bx_in, const Gemm g, const Epi& E) {
;     ...
;             const bool last = (t == nt - 2);
;             const char* a1 = cA + (size_t)(t + 1) * kstep;
;             const char* a2 = last ? nA : cA + (size_t)(t + 2) * kstep; const char* b2 = last ? nB : cB + (size_t)(t + 2) * kstep;
;             const char* a3 = a2 + kstep; const char* b3 = b2 + kstep;
;             PG8_LDB(B0, 0, 0); PG8_LDB(B1, 0, 1); PG8_SCHED; PG8_LDA(At, 0, 0); PG8_STAGE(PG8_SA(1, 1), a1 + hstepA, voffA);
;             PG8_WAIT_V(8); PG8_WAIT_L(0); PG8_BAR; PG8_MMA(0, 0, At, B0); PG8_MMA(0, 1, At, B1); PG8_BAR; PG8_SCHED;
;             PG8_LDA(At, 0, 1); PG8_STAGE(PG8_SB(0, 0), b2, voffB); PG8_STAGE(PG8_SB(0, 1), b2 + hstepB, voffB); PG8_STAGE(PG8_SA(0, 0), a2, voffA);
;             PG8_WAIT_V(8); PG8_WAIT_L(0); PG8_BAR; PG8_MMA(1, 0, At, B0); PG8_MMA(1, 1, At, B1); PG8_BAR; PG8_SCHED;
.LBB0_599:
	s_add_u32 s0, s14, 0xfffc0080
	s_addc_u32 s1, s15, -1
	s_add_i32 s24, 0, 0x10000
	s_cmp_eq_u32 s86, 12
	s_cselect_b32 s63, s11, s1
	s_cselect_b32 s62, s13, s0
	v_add_u32_e32 v0, s24, v179
	s_cselect_b32 s61, s45, s85
	s_cselect_b32 s60, s47, s84
	s_add_i32 s66, 0, 0x14000
	ds_read_b128 v[130:133], v0
	ds_read_b128 v[134:137], v0 offset:1024
	ds_read_b128 v[160:163], v0 offset:2048
	ds_read_b128 v[164:167], v0 offset:3072
	v_add_u32_e32 v0, s66, v179
	ds_read_b128 v[168:171], v0
	ds_read_b128 v[172:175], v0 offset:1024
	ds_read_b128 v[184:187], v0 offset:2048
	ds_read_b128 v[202:205], v0 offset:3072
	v_lshl_add_u64 v[176:177], s[14:15], 0, v[156:157]
	s_add_i32 m0, s91, 0xc000
	ds_read_b128 v[206:209], v183
	ds_read_b128 v[210:213], v183 offset:1024
	ds_read_b128 v[214:217], v183 offset:2048
	ds_read_b128 v[218:221], v183 offset:3072
	ds_read_b128 v[222:225], v183 offset:4096
	ds_read_b128 v[226:229], v183 offset:5120
	ds_read_b128 v[250:253], v183 offset:6144
	ds_read_b128 v[188:191], v183 offset:7168
	global_load_lds_dwordx4 v[176:177], off
	v_lshl_add_u64 v[176:177], s[14:15], 0, v[158:159]
	s_add_i32 m0, s91, 0xe000
	s_nop 0
	global_load_lds_dwordx4 v[176:177], off
	s_waitcnt vmcnt(8)
	s_waitcnt lgkmcnt(0)
	s_barrier
	s_setprio 1
	s_waitcnt lgkmcnt(0)
	v_mfma_f32_16x16x32_bf16 v[126:129], v[130:133], v[206:209], v[126:129]
	v_mfma_f32_16x16x32_bf16 v[122:125], v[160:163], v[206:209], v[122:125]
	v_mfma_f32_16x16x32_bf16 v[110:113], v[130:133], v[214:217], v[110:113]
	v_mfma_f32_16x16x32_bf16 v[106:109], v[160:163], v[214:217], v[106:109]
	v_mfma_f32_16x16x32_bf16 v[94:97], v[130:133], v[222:225], v[94:97]
	v_mfma_f32_16x16x32_bf16 v[90:93], v[160:163], v[222:225], v[90:93]
	v_mfma_f32_16x16x32_bf16 v[78:81], v[130:133], v[250:253], v[78:81]
	v_mfma_f32_16x16x32_bf16 v[74:77], v[160:163], v[250:253], v[74:77]
	v_mfma_f32_16x16x32_bf16 v[126:129], v[134:137], v[210:213], v[126:129]
	v_mfma_f32_16x16x32_bf16 v[122:125], v[164:167], v[210:213], v[122:125]
	v_mfma_f32_16x16x32_bf16 v[110:113], v[134:137], v[218:221], v[110:113]
	v_mfma_f32_16x16x32_bf16 v[106:109], v[164:167], v[218:221], v[106:109]
	v_mfma_f32_16x16x32_bf16 v[94:97], v[134:137], v[226:229], v[94:97]
	v_mfma_f32_16x16x32_bf16 v[90:93], v[164:167], v[226:229], v[90:93]
	v_mfma_f32_16x16x32_bf16 v[78:81], v[134:137], v[188:191], v[78:81]
	v_mfma_f32_16x16x32_bf16 v[74:77], v[164:167], v[188:191], v[74:77]
	v_mfma_f32_16x16x32_bf16 v[118:121], v[168:171], v[206:209], v[118:121]
	v_mfma_f32_16x16x32_bf16 v[114:117], v[184:187], v[206:209], v[114:117]
	v_mfma_f32_16x16x32_bf16 v[102:105], v[168:171], v[214:217], v[102:105]
	v_mfma_f32_16x16x32_bf16 v[98:101], v[184:187], v[214:217], v[98:101]
	v_mfma_f32_16x16x32_bf16 v[86:89], v[168:171], v[222:225], v[86:89]
	v_mfma_f32_16x16x32_bf16 v[82:85], v[184:187], v[222:225], v[82:85]
	v_mfma_f32_16x16x32_bf16 v[70:73], v[168:171], v[250:253], v[70:73]
	v_mfma_f32_16x16x32_bf16 v[66:69], v[184:187], v[250:253], v[66:69]
	v_mfma_f32_16x16x32_bf16 v[118:121], v[172:175], v[210:213], v[118:121]
	v_mfma_f32_16x16x32_bf16 v[114:117], v[202:205], v[210:213], v[114:117]
	v_mfma_f32_16x16x32_bf16 v[102:105], v[172:175], v[218:221], v[102:105]
	v_mfma_f32_16x16x32_bf16 v[98:101], v[202:205], v[218:221], v[98:101]
	v_mfma_f32_16x16x32_bf16 v[86:89], v[172:175], v[226:229], v[86:89]
	v_mfma_f32_16x16x32_bf16 v[82:85], v[202:205], v[226:229], v[82:85]
	v_mfma_f32_16x16x32_bf16 v[70:73], v[172:175], v[188:191], v[70:73]
	v_mfma_f32_16x16x32_bf16 v[66:69], v[202:205], v[188:191], v[66:69]
	s_setprio 0
	s_barrier
	s_add_i32 s0, s24, s90
	v_lshl_add_u64 v[176:177], s[60:61], 0, v[140:141]
	s_mov_b32 m0, s0
	ds_read_b128 v[188:191], v183 offset:16384
	ds_read_b128 v[206:209], v183 offset:17408
	ds_read_b128 v[210:213], v183 offset:18432
	ds_read_b128 v[214:217], v183 offset:19456
	ds_read_b128 v[218:221], v183 offset:20480
	ds_read_b128 v[222:225], v183 offset:21504
	ds_read_b128 v[226:229], v183 offset:22528
	ds_read_b128 v[250:253], v183 offset:23552
	global_load_lds_dwordx4 v[176:177], off
	s_add_i32 m0, s0, 0x2000
	s_add_u32 s0, s60, 0x40000
	v_lshl_add_u64 v[192:193], s[60:61], 0, v[144:145]
	s_addc_u32 s1, s61, 0
	s_add_i32 s24, s66, s90
	global_load_lds_dwordx4 v[192:193], off
	v_lshl_add_u64 v[244:245], s[0:1], 0, v[140:141]
	s_mov_b32 m0, s24
	v_lshl_add_u64 v[200:201], s[62:63], 0, v[142:143]
	global_load_lds_dwordx4 v[244:245], off
	v_lshl_add_u64 v[244:245], s[0:1], 0, v[144:145]
	s_add_i32 m0, s24, 0x2000
	s_nop 0
	global_load_lds_dwordx4 v[244:245], off
	v_lshl_add_u64 v[244:245], s[62:63], 0, v[138:139]
	s_mov_b32 m0, s91
	s_nop 0
	global_load_lds_dwordx4 v[244:245], off
	s_mov_b32 m0, s92
	s_nop 0
	global_load_lds_dwordx4 v[200:201], off
	s_waitcnt vmcnt(8)
	s_waitcnt lgkmcnt(0)
	s_barrier
; #define PG8_STAGE(bufoff, gbase, voff) do { _Pragma("unroll") for (int _i = 0; _i < 2; ++_i) \
;         __builtin_amdgcn_global_load_lds((const unsigned*)((const char*)(gbase) + (voff)[_i]), (LAS unsigned*)(lds + (bufoff) + ldsw + _i * 8192), 16, 0, 0); } while (0)
; #define PG8_LDA(dst, b, h) do { _Pragma("unroll") for (int m = 0; m < 4; ++m) _Pragma("unroll") for (int k = 0; k < 2; ++k) dst[m][k] = *(const LAS bf16x8*)(lds + PG8_SA(b, h) + aoff + m * 2048 + k * 1024); } while (0)
; #define PG8_LDB(dst, b, h) do { _Pragma("unroll") for (int n = 0; n < 2; ++n) _Pragma("unroll") for (int k = 0; k < 2; ++k) dst[n][k] = *(const LAS bf16x8*)(lds + PG8_SB(b, h) + boff + n * 2048 + k * 1024); } while (0)
; #define PG8_MMA(ai, bj, At, Bt) do { __builtin_amdgcn_s_setprio(1); _Pragma("unroll") for (int m = 0; m < 4; ++m) _Pragma("unroll") for (int n = 0; n < 2; ++n) _Pragma("unroll") for (int k = 0; k < 2; ++k) \
;         acc[ai][bj][m][n] = __builtin_amdgcn_mfma_f32_16x16x32_bf16(Bt[n][k], At[m][k], acc[ai][bj][m][n], 0, 0, 0); __builtin_amdgcn_s_setprio(0); } while (0)
; #define PG8_WAIT_V(n) asm volatile("s_waitcnt vmcnt(" #n ")" ::: "memory")
; #define PG8_WAIT_L(n) asm volatile("s_waitcnt lgkmcnt(" #n ")" ::: "memory")
; #define PG8_BAR __builtin_amdgcn_s_barrier()
; #define PG8_SCHED __builtin_amdgcn_sched_barrier(0)
; template <class Epi, bool ALIGN_EPI, int M_, int N_, int K_, int LDA, int LDB>
; __device__ __forceinline__ void gemm_phase(LAS unsigned char* lds, const int tid_in, const int G_in, const int bx_in, const Gemm g, const Epi& E) {
;     ...
;             PG8_WAIT_V(8); PG8_WAIT_L(0); PG8_BAR; PG8_MMA(1, 0, At, B0); PG8_MMA(1, 1, At, B1); PG8_BAR; PG8_SCHED;
;             PG8_LDB(B0, 1, 0); PG8_LDB(B1, 1, 1); PG8_SCHED; PG8_LDA(At, 1, 0); PG8_STAGE(PG8_SA(0, 1), a2 + hstepA, voffA);
;             PG8_WAIT_V(8); PG8_WAIT_L(0); PG8_BAR; PG8_MMA(0, 0, At, B0); PG8_MMA(0, 1, At, B1); PG8_BAR; PG8_SCHED;
	s_setprio 1
	s_waitcnt lgkmcnt(0)
	v_mfma_f32_16x16x32_bf16 v[62:65], v[130:133], v[188:191], v[62:65]
	v_mfma_f32_16x16x32_bf16 v[58:61], v[160:163], v[188:191], v[58:61]
	v_mfma_f32_16x16x32_bf16 v[46:49], v[130:133], v[210:213], v[46:49]
	v_mfma_f32_16x16x32_bf16 v[42:45], v[160:163], v[210:213], v[42:45]
	v_mfma_f32_16x16x32_bf16 v[30:33], v[130:133], v[218:221], v[30:33]
	v_mfma_f32_16x16x32_bf16 v[26:29], v[160:163], v[218:221], v[26:29]
	v_mfma_f32_16x16x32_bf16 v[14:17], v[130:133], v[226:229], v[14:17]
	v_mfma_f32_16x16x32_bf16 v[10:13], v[160:163], v[226:229], v[10:13]
	v_mfma_f32_16x16x32_bf16 v[62:65], v[134:137], v[206:209], v[62:65]
	v_mfma_f32_16x16x32_bf16 v[58:61], v[164:167], v[206:209], v[58:61]
	v_mfma_f32_16x16x32_bf16 v[46:49], v[134:137], v[214:217], v[46:49]
	v_mfma_f32_16x16x32_bf16 v[42:45], v[164:167], v[214:217], v[42:45]
	v_mfma_f32_16x16x32_bf16 v[30:33], v[134:137], v[222:225], v[30:33]
	v_mfma_f32_16x16x32_bf16 v[26:29], v[164:167], v[222:225], v[26:29]
	v_mfma_f32_16x16x32_bf16 v[14:17], v[134:137], v[250:253], v[14:17]
	v_mfma_f32_16x16x32_bf16 v[10:13], v[164:167], v[250:253], v[10:13]
	v_mfma_f32_16x16x32_bf16 v[54:57], v[168:171], v[188:191], v[54:57]
	v_mfma_f32_16x16x32_bf16 v[50:53], v[184:187], v[188:191], v[50:53]
	v_mfma_f32_16x16x32_bf16 v[38:41], v[168:171], v[210:213], v[38:41]
	v_mfma_f32_16x16x32_bf16 v[34:37], v[184:187], v[210:213], v[34:37]
	v_mfma_f32_16x16x32_bf16 v[22:25], v[168:171], v[218:221], v[22:25]
	v_mfma_f32_16x16x32_bf16 v[18:21], v[184:187], v[218:221], v[18:21]
	v_mfma_f32_16x16x32_bf16 v[6:9], v[168:171], v[226:229], v[6:9]
	v_mfma_f32_16x16x32_bf16 v[2:5], v[184:187], v[226:229], v[2:5]
	v_mfma_f32_16x16x32_bf16 v[54:57], v[172:175], v[206:209], v[54:57]
	v_mfma_f32_16x16x32_bf16 v[50:53], v[202:205], v[206:209], v[50:53]
	v_mfma_f32_16x16x32_bf16 v[38:41], v[172:175], v[214:217], v[38:41]
	v_mfma_f32_16x16x32_bf16 v[34:37], v[202:205], v[214:217], v[34:37]
	v_mfma_f32_16x16x32_bf16 v[22:25], v[172:175], v[222:225], v[22:25]
	v_mfma_f32_16x16x32_bf16 v[18:21], v[202:205], v[222:225], v[18:21]
	v_mfma_f32_16x16x32_bf16 v[6:9], v[172:175], v[250:253], v[6:9]
	v_mfma_f32_16x16x32_bf16 v[2:5], v[202:205], v[250:253], v[2:5]
	s_setprio 0
	s_barrier
	s_add_i32 s24, 0, 0x18000
	v_add_u32_e32 v0, s24, v179
	s_add_i32 s66, 0, 0x1c000
	ds_read_b128 v[130:133], v0
	ds_read_b128 v[134:137], v0 offset:1024
	ds_read_b128 v[160:163], v0 offset:2048
	ds_read_b128 v[164:167], v0 offset:3072
	v_add_u32_e32 v0, s66, v179
	ds_read_b128 v[168:171], v0
	ds_read_b128 v[172:175], v0 offset:1024
	ds_read_b128 v[184:187], v0 offset:2048
	ds_read_b128 v[188:191], v0 offset:3072
	s_add_u32 s0, s62, 0x40000
	s_addc_u32 s1, s63, 0
	s_mov_b32 m0, s93
	v_lshl_add_u64 v[230:231], s[0:1], 0, v[138:139]
	ds_read_b128 v[202:205], v183 offset:32768
	ds_read_b128 v[206:209], v183 offset:33792
	ds_read_b128 v[210:213], v183 offset:34816
	ds_read_b128 v[214:217], v183 offset:35840
	ds_read_b128 v[218:221], v183 offset:36864
	ds_read_b128 v[222:225], v183 offset:37888
	ds_read_b128 v[226:229], v183 offset:38912
	ds_read_b128 v[250:253], v183 offset:39936
	global_load_lds_dwordx4 v[230:231], off
	v_lshl_add_u64 v[230:231], s[0:1], 0, v[142:143]
	s_mov_b32 m0, s94
	s_nop 0
	global_load_lds_dwordx4 v[230:231], off
	s_waitcnt vmcnt(8)
	s_waitcnt lgkmcnt(0)
	s_barrier
	s_setprio 1
	s_waitcnt lgkmcnt(0)
	v_mfma_f32_16x16x32_bf16 v[126:129], v[130:133], v[202:205], v[126:129]
	v_mfma_f32_16x16x32_bf16 v[122:125], v[160:163], v[202:205], v[122:125]
	v_mfma_f32_16x16x32_bf16 v[110:113], v[130:133], v[210:213], v[110:113]
	v_mfma_f32_16x16x32_bf16 v[106:109], v[160:163], v[210:213], v[106:109]
	v_mfma_f32_16x16x32_bf16 v[94:97], v[130:133], v[218:221], v[94:97]
	v_mfma_f32_16x16x32_bf16 v[90:93], v[160:163], v[218:221], v[90:93]
	v_mfma_f32_16x16x32_bf16 v[78:81], v[130:133], v[226:229], v[78:81]
	v_mfma_f32_16x16x32_bf16 v[74:77], v[160:163], v[226:229], v[74:77]
	v_mfma_f32_16x16x32_bf16 v[126:129], v[134:137], v[206:209], v[126:129]
	v_mfma_f32_16x16x32_bf16 v[122:125], v[164:167], v[206:209], v[122:125]
	v_mfma_f32_16x16x32_bf16 v[110:113], v[134:137], v[214:217], v[110:113]
	v_mfma_f32_16x16x32_bf16 v[106:109], v[164:167], v[214:217], v[106:109]
	v_mfma_f32_16x16x32_bf16 v[94:97], v[134:137], v[222:225], v[94:97]
	v_mfma_f32_16x16x32_bf16 v[90:93], v[164:167], v[222:225], v[90:93]
	v_mfma_f32_16x16x32_bf16 v[78:81], v[134:137], v[250:253], v[78:81]
	v_mfma_f32_16x16x32_bf16 v[74:77], v[164:167], v[250:253], v[74:77]
	v_mfma_f32_16x16x32_bf16 v[118:121], v[168:171], v[202:205], v[118:121]
	v_mfma_f32_16x16x32_bf16 v[114:117], v[184:187], v[202:205], v[114:117]
	v_mfma_f32_16x16x32_bf16 v[102:105], v[168:171], v[210:213], v[102:105]
	v_mfma_f32_16x16x32_bf16 v[98:101], v[184:187], v[210:213], v[98:101]
	v_mfma_f32_16x16x32_bf16 v[86:89], v[168:171], v[218:221], v[86:89]
	v_mfma_f32_16x16x32_bf16 v[82:85], v[184:187], v[218:221], v[82:85]
	v_mfma_f32_16x16x32_bf16 v[70:73], v[168:171], v[226:229], v[70:73]
	v_mfma_f32_16x16x32_bf16 v[66:69], v[184:187], v[226:229], v[66:69]
	v_mfma_f32_16x16x32_bf16 v[118:121], v[172:175], v[206:209], v[118:121]
	v_mfma_f32_16x16x32_bf16 v[114:117], v[188:191], v[206:209], v[114:117]
	v_mfma_f32_16x16x32_bf16 v[102:105], v[172:175], v[214:217], v[102:105]
	v_mfma_f32_16x16x32_bf16 v[98:101], v[188:191], v[214:217], v[98:101]
	v_mfma_f32_16x16x32_bf16 v[86:89], v[172:175], v[222:225], v[86:89]
	v_mfma_f32_16x16x32_bf16 v[82:85], v[188:191], v[222:225], v[82:85]
	v_mfma_f32_16x16x32_bf16 v[70:73], v[172:175], v[250:253], v[70:73]
	v_mfma_f32_16x16x32_bf16 v[66:69], v[188:191], v[250:253], v[66:69]
	s_setprio 0
	s_barrier
; #define PG8_STAGE(bufoff, gbase, voff) do { _Pragma("unroll") for (int _i = 0; _i < 2; ++_i) \
;         __builtin_amdgcn_global_load_lds((const unsigned*)((const char*)(gbase) + (voff)[_i]), (LAS unsigned*)(lds + (bufoff) + ldsw + _i * 8192), 16, 0, 0); } while (0)
; #define PG8_LDA(dst, b, h) do { _Pragma("unroll") for (int m = 0; m < 4; ++m) _Pragma("unroll") for (int k = 0; k < 2; ++k) dst[m][k] = *(const LAS bf16x8*)(lds + PG8_SA(b, h) + aoff + m * 2048 + k * 1024); } while (0)
; #define PG8_MMA(ai, bj, At, Bt) do { __builtin_amdgcn_s_setprio(1); _Pragma("unroll") for (int m = 0; m < 4; ++m) _Pragma("unroll") for (int n = 0; n < 2; ++n) _Pragma("unroll") for (int k = 0; k < 2; ++k) \
;         acc[ai][bj][m][n] = __builtin_amdgcn_mfma_f32_16x16x32_bf16(Bt[n][k], At[m][k], acc[ai][bj][m][n], 0, 0, 0); __builtin_amdgcn_s_setprio(0); } while (0)
; #define PG8_WAIT_V(n) asm volatile("s_waitcnt vmcnt(" #n ")" ::: "memory")
; #define PG8_WAIT_L(n) asm volatile("s_waitcnt lgkmcnt(" #n ")" ::: "memory")
; #define PG8_BAR __builtin_amdgcn_s_barrier()
; #define PG8_SCHED __builtin_amdgcn_sched_barrier(0)
; template <class Epi, bool ALIGN_EPI, int M_, int N_, int K_, int LDA, int LDB>
; __device__ __forceinline__ void gemm_phase(LAS unsigned char* lds, const int tid_in, const int G_in, const int bx_in, const Gemm g, const Epi& E) {
;     ...
;             PG8_LDA(At, 1, 1); PG8_STAGE(PG8_SB(1, 0), b3, voffB); PG8_STAGE(PG8_SB(1, 1), b3 + hstepB, voffB); PG8_STAGE(PG8_SA(1, 0), a3, voffA);
;             PG8_WAIT_V(8); PG8_WAIT_L(0); PG8_BAR; PG8_MMA(1, 0, At, B0); PG8_MMA(1, 1, At, B1); PG8_BAR; PG8_SCHED;
;         }
;         if constexpr (ALIGN_EPI) { if (wr == 0) PG8_BAR; }
	s_add_i32 s0, s24, s90
	v_lshl_add_u64 v[176:177], v[176:177], 0, s[54:55]
	s_mov_b32 m0, s0
	ds_read_b128 v[202:205], v183 offset:49152
	ds_read_b128 v[206:209], v183 offset:50176
	ds_read_b128 v[210:213], v183 offset:51200
	ds_read_b128 v[214:217], v183 offset:52224
	ds_read_b128 v[218:221], v183 offset:53248
	ds_read_b128 v[222:225], v183 offset:54272
	ds_read_b128 v[226:229], v183 offset:55296
	ds_read_b128 v[250:253], v183 offset:56320
	global_load_lds_dwordx4 v[176:177], off
	s_add_i32 m0, s0, 0x2000
	s_add_u32 s0, s60, 0x40080
	v_lshl_add_u64 v[176:177], v[192:193], 0, s[54:55]
	s_addc_u32 s1, s61, 0
	s_add_i32 s24, s66, s90
	global_load_lds_dwordx4 v[176:177], off
	v_lshl_add_u64 v[176:177], s[0:1], 0, v[140:141]
	s_mov_b32 m0, s24
	s_nop 0
	global_load_lds_dwordx4 v[176:177], off
	v_lshl_add_u64 v[176:177], s[0:1], 0, v[144:145]
	s_add_i32 m0, s24, 0x2000
	s_nop 0
	global_load_lds_dwordx4 v[176:177], off
	v_lshl_add_u64 v[176:177], v[244:245], 0, s[54:55]
	s_mov_b32 m0, s97
	s_nop 0
	global_load_lds_dwordx4 v[176:177], off
	v_lshl_add_u64 v[176:177], v[200:201], 0, s[54:55]
	s_mov_b32 m0, s78
	s_nop 0
	global_load_lds_dwordx4 v[176:177], off
	s_waitcnt vmcnt(8)
	s_waitcnt lgkmcnt(0)
	s_barrier
	s_setprio 1
	s_waitcnt lgkmcnt(0)
	v_mfma_f32_16x16x32_bf16 v[62:65], v[130:133], v[202:205], v[62:65]
	v_mfma_f32_16x16x32_bf16 v[58:61], v[160:163], v[202:205], v[58:61]
	v_mfma_f32_16x16x32_bf16 v[46:49], v[130:133], v[210:213], v[46:49]
	v_mfma_f32_16x16x32_bf16 v[42:45], v[160:163], v[210:213], v[42:45]
	v_mfma_f32_16x16x32_bf16 v[30:33], v[130:133], v[218:221], v[30:33]
	v_mfma_f32_16x16x32_bf16 v[26:29], v[160:163], v[218:221], v[26:29]
	v_mfma_f32_16x16x32_bf16 v[14:17], v[130:133], v[226:229], v[14:17]
	v_mfma_f32_16x16x32_bf16 v[10:13], v[160:163], v[226:229], v[10:13]
	v_mfma_f32_16x16x32_bf16 v[62:65], v[134:137], v[206:209], v[62:65]
	v_mfma_f32_16x16x32_bf16 v[58:61], v[164:167], v[206:209], v[58:61]
	v_mfma_f32_16x16x32_bf16 v[46:49], v[134:137], v[214:217], v[46:49]
	v_mfma_f32_16x16x32_bf16 v[42:45], v[164:167], v[214:217], v[42:45]
	v_mfma_f32_16x16x32_bf16 v[30:33], v[134:137], v[222:225], v[30:33]
	v_mfma_f32_16x16x32_bf16 v[26:29], v[164:167], v[222:225], v[26:29]
	v_mfma_f32_16x16x32_bf16 v[14:17], v[134:137], v[250:253], v[14:17]
	v_mfma_f32_16x16x32_bf16 v[10:13], v[164:167], v[250:253], v[10:13]
	v_mfma_f32_16x16x32_bf16 v[54:57], v[168:171], v[202:205], v[54:57]
	v_mfma_f32_16x16x32_bf16 v[50:53], v[184:187], v[202:205], v[50:53]
	v_mfma_f32_16x16x32_bf16 v[38:41], v[168:171], v[210:213], v[38:41]
	v_mfma_f32_16x16x32_bf16 v[34:37], v[184:187], v[210:213], v[34:37]
	v_mfma_f32_16x16x32_bf16 v[22:25], v[168:171], v[218:221], v[22:25]
	v_mfma_f32_16x16x32_bf16 v[18:21], v[184:187], v[218:221], v[18:21]
	v_mfma_f32_16x16x32_bf16 v[6:9], v[168:171], v[226:229], v[6:9]
	v_mfma_f32_16x16x32_bf16 v[2:5], v[184:187], v[226:229], v[2:5]
	v_mfma_f32_16x16x32_bf16 v[54:57], v[172:175], v[206:209], v[54:57]
	v_mfma_f32_16x16x32_bf16 v[50:53], v[188:191], v[206:209], v[50:53]
	v_mfma_f32_16x16x32_bf16 v[38:41], v[172:175], v[214:217], v[38:41]
	v_mfma_f32_16x16x32_bf16 v[34:37], v[188:191], v[214:217], v[34:37]
	v_mfma_f32_16x16x32_bf16 v[22:25], v[172:175], v[222:225], v[22:25]
	v_mfma_f32_16x16x32_bf16 v[18:21], v[188:191], v[222:225], v[18:21]
	v_mfma_f32_16x16x32_bf16 v[6:9], v[172:175], v[250:253], v[6:9]
	v_mfma_f32_16x16x32_bf16 v[2:5], v[188:191], v[250:253], v[2:5]
	s_setprio 0
	s_barrier
	s_add_i32 s86, s86, 2
	s_add_u32 s14, s14, 0x100
	s_addc_u32 s15, s15, 0
	s_add_u32 s84, s84, 0x100
	s_addc_u32 s85, s85, 0
	s_cmp_gt_u32 s86, 13
	s_cbranch_scc0 .LBB0_599
	s_and_b64 vcc, exec, s[42:43]
	s_cbranch_vccz .LBB0_602
	s_barrier

; #define PG8_STAGE(bufoff, gbase, voff) do { _Pragma("unroll") for (int _i = 0; _i < 2; ++_i) \
;         __builtin_amdgcn_global_load_lds((const unsigned*)((const char*)(gbase) + (voff)[_i]), (LAS unsigned*)(lds + (bufoff) + ldsw + _i * 8192), 16, 0, 0); } while (0)
; #define PG8_LDA(dst, b, h) do { _Pragma("unroll") for (int m = 0; m < 4; ++m) _Pragma("unroll") for (int k = 0; k < 2; ++k) dst[m][k] = *(const LAS bf16x8*)(lds + PG8_SA(b, h) + aoff + m * 2048 + k * 1024); } while (0)
; #define PG8_LDB(dst, b, h) do { _Pragma("unroll") for (int n = 0; n < 2; ++n) _Pragma("unroll") for (int k = 0; k < 2; ++k) dst[n][k] = *(const LAS bf16x8*)(lds + PG8_SB(b, h) + boff + n * 2048 + k * 1024); } while (0)
; #define PG8_MMA(ai, bj, At, Bt) do { __builtin_amdgcn_s_setprio(1); _Pragma("unroll") for (int m = 0; m < 4; ++m) _Pragma("unroll") for (int n = 0; n < 2; ++n) _Pragma("unroll") for (int k = 0; k < 2; ++k) \
;         acc[ai][bj][m][n] = __builtin_amdgcn_mfma_f32_16x16x32_bf16(Bt[n][k], At[m][k], acc[ai][bj][m][n], 0, 0, 0); __builtin_amdgcn_s_setprio(0); } while (0)
; #define PG8_WAIT_V(n) asm volatile("s_waitcnt vmcnt(" #n ")" ::: "memory")
; #define PG8_WAIT_L(n) asm volatile("s_waitcnt lgkmcnt(" #n ")" ::: "memory")
; #define PG8_BAR __builtin_amdgcn_s_barrier()
; #define PG8_SCHED __builtin_amdgcn_sched_barrier(0)
; template <class Epi, bool ALIGN_EPI, int M_, int N_, int K_, int LDA, int LDB>
; __device__ __forceinline__ void gemm_phase(LAS unsigned char* lds, const int tid_in, const int G_in, const int bx_in, const Gemm g, const Epi& E) {
;     ...
;             const bool last = (t == nt - 2);
;             const char* a1 = cA + (size_t)(t + 1) * kstep;
;             const char* a2 = last ? nA : cA + (size_t)(t + 2) * kstep; const char* b2 = last ? nB : cB + (size_t)(t + 2) * kstep;
;             const char* a3 = a2 + kstep; const char* b3 = b2 + kstep;
;             PG8_LDB(B0, 0, 0); PG8_LDB(B1, 0, 1); PG8_SCHED; PG8_LDA(At, 0, 0); PG8_STAGE(PG8_SA(1, 1), a1 + hstepA, voffA);
;             PG8_WAIT_V(8); PG8_WAIT_L(0); PG8_BAR; PG8_MMA(0, 0, At, B0); PG8_MMA(0, 1, At, B1); PG8_BAR; PG8_SCHED;
;             PG8_LDA(At, 0, 1); PG8_STAGE(PG8_SB(0, 0), b2, voffB); PG8_STAGE(PG8_SB(0, 1), b2 + hstepB, voffB); PG8_STAGE(PG8_SA(0, 0), a2, voffA);
;             PG8_WAIT_V(8); PG8_WAIT_L(0); PG8_BAR; PG8_MMA(1, 0, At, B0); PG8_MMA(1, 1, At, B1); PG8_BAR; PG8_SCHED;
.LBB0_1832:
	s_add_u32 s15, s88, s94
	s_addc_u32 s24, s89, s95
	s_add_u32 s42, s15, 0x100
	s_addc_u32 s43, s24, 0
	s_and_b64 s[0:1], s[92:93], exec
	s_cselect_b32 s97, s9, s43
	s_cselect_b32 s96, s11, s42
	s_add_u32 s0, s86, s94
	s_addc_u32 s1, s87, s95
	s_add_u32 s42, s0, 0x100
	s_addc_u32 s43, s1, 0
	s_add_i32 s66, 0, 0x10000
	s_and_b64 s[0:1], s[92:93], exec
	s_cselect_b32 vcc_hi, s45, s43
	s_cselect_b32 vcc_lo, s47, s42
	s_add_i32 s93, 0, 0x14000
	s_add_u32 s62, s15, 0x200080
	s_addc_u32 s63, s24, 0
	s_add_i32 s24, s66, s84
	s_add_i32 m0, s14, 0xc000
	s_add_i32 s85, s14, 0xe000
	s_add_i32 s0, s24, 0x2000
	v_add_u32_e32 v0, s66, v163
	s_add_u32 s60, vcc_lo, 0x10000
	ds_read_b128 v[130:133], v0
	ds_read_b128 v[134:137], v0 offset:1024
	ds_read_b128 v[138:141], v0 offset:2048
	ds_read_b128 v[156:159], v0 offset:3072
	v_add_u32_e32 v0, s93, v163
	s_addc_u32 s61, vcc_hi, 0
	s_add_i32 s82, s93, s84
	ds_read_b128 v[166:169], v0
	ds_read_b128 v[170:173], v0 offset:1024
	ds_read_b128 v[174:177], v0 offset:2048
	ds_read_b128 v[178:181], v0 offset:3072
	s_add_i32 s1, s82, 0x2000
	s_add_i32 s83, 0, 0x18000
	s_add_i32 s43, 0, 0x1c000
	s_add_u32 s94, s96, 0x200000
	s_addc_u32 s95, s97, 0
	s_add_i32 s78, s83, s84
	s_add_i32 s42, s78, 0x2000
	s_add_u32 s92, vcc_lo, 0x10080
	s_addc_u32 s93, vcc_hi, 0
	s_add_i32 s66, s43, s84
	s_add_i32 s15, s66, 0x2000
	v_lshl_add_u64 v[142:143], s[62:63], 0, v[144:145]
	ds_read_b128 v[182:185], v165
	ds_read_b128 v[186:189], v165 offset:1024
	ds_read_b128 v[202:205], v165 offset:2048
	ds_read_b128 v[206:209], v165 offset:3072
	ds_read_b128 v[210:213], v165 offset:4096
	ds_read_b128 v[214:217], v165 offset:5120
	ds_read_b128 v[218:221], v165 offset:6144
	ds_read_b128 v[222:225], v165 offset:7168
	global_load_lds_dwordx4 v[142:143], off
	v_lshl_add_u64 v[142:143], s[62:63], 0, v[148:149]
	s_mov_b32 m0, s85
	s_nop 0
	global_load_lds_dwordx4 v[142:143], off
	s_waitcnt vmcnt(8)
	s_waitcnt lgkmcnt(0)
	s_barrier
	s_setprio 1
	s_waitcnt lgkmcnt(0)
	v_mfma_f32_16x16x32_bf16 v[126:129], v[130:133], v[182:185], v[126:129]
	v_mfma_f32_16x16x32_bf16 v[122:125], v[138:141], v[182:185], v[122:125]
	v_mfma_f32_16x16x32_bf16 v[110:113], v[130:133], v[202:205], v[110:113]
	v_mfma_f32_16x16x32_bf16 v[106:109], v[138:141], v[202:205], v[106:109]
	v_mfma_f32_16x16x32_bf16 v[94:97], v[130:133], v[210:213], v[94:97]
	v_mfma_f32_16x16x32_bf16 v[90:93], v[138:141], v[210:213], v[90:93]
	v_mfma_f32_16x16x32_bf16 v[78:81], v[130:133], v[218:221], v[78:81]
	v_mfma_f32_16x16x32_bf16 v[74:77], v[138:141], v[218:221], v[74:77]
	v_mfma_f32_16x16x32_bf16 v[126:129], v[134:137], v[186:189], v[126:129]
	v_mfma_f32_16x16x32_bf16 v[122:125], v[156:159], v[186:189], v[122:125]
	v_mfma_f32_16x16x32_bf16 v[110:113], v[134:137], v[206:209], v[110:113]
	v_mfma_f32_16x16x32_bf16 v[106:109], v[156:159], v[206:209], v[106:109]
	v_mfma_f32_16x16x32_bf16 v[94:97], v[134:137], v[214:217], v[94:97]
	v_mfma_f32_16x16x32_bf16 v[90:93], v[156:159], v[214:217], v[90:93]
	v_mfma_f32_16x16x32_bf16 v[78:81], v[134:137], v[222:225], v[78:81]
	v_mfma_f32_16x16x32_bf16 v[74:77], v[156:159], v[222:225], v[74:77]
	v_mfma_f32_16x16x32_bf16 v[118:121], v[166:169], v[182:185], v[118:121]
	v_mfma_f32_16x16x32_bf16 v[114:117], v[174:177], v[182:185], v[114:117]
	v_mfma_f32_16x16x32_bf16 v[102:105], v[166:169], v[202:205], v[102:105]
	v_mfma_f32_16x16x32_bf16 v[98:101], v[174:177], v[202:205], v[98:101]
	v_mfma_f32_16x16x32_bf16 v[86:89], v[166:169], v[210:213], v[86:89]
	v_mfma_f32_16x16x32_bf16 v[82:85], v[174:177], v[210:213], v[82:85]
	v_mfma_f32_16x16x32_bf16 v[70:73], v[166:169], v[218:221], v[70:73]
	v_mfma_f32_16x16x32_bf16 v[66:69], v[174:177], v[218:221], v[66:69]
	v_mfma_f32_16x16x32_bf16 v[118:121], v[170:173], v[186:189], v[118:121]
	v_mfma_f32_16x16x32_bf16 v[114:117], v[178:181], v[186:189], v[114:117]
	v_mfma_f32_16x16x32_bf16 v[102:105], v[170:173], v[206:209], v[102:105]
	v_mfma_f32_16x16x32_bf16 v[98:101], v[178:181], v[206:209], v[98:101]
	v_mfma_f32_16x16x32_bf16 v[86:89], v[170:173], v[214:217], v[86:89]
	v_mfma_f32_16x16x32_bf16 v[82:85], v[178:181], v[214:217], v[82:85]
	v_mfma_f32_16x16x32_bf16 v[70:73], v[170:173], v[222:225], v[70:73]
	v_mfma_f32_16x16x32_bf16 v[66:69], v[178:181], v[222:225], v[66:69]
	s_setprio 0
	s_barrier
	s_mov_b32 m0, s24
	v_lshl_add_u64 v[142:143], vcc, 0, v[146:147]
	ds_read_b128 v[182:185], v165 offset:16384
	ds_read_b128 v[186:189], v165 offset:17408
	ds_read_b128 v[202:205], v165 offset:18432
	ds_read_b128 v[206:209], v165 offset:19456
	ds_read_b128 v[210:213], v165 offset:20480
	ds_read_b128 v[214:217], v165 offset:21504
	ds_read_b128 v[218:221], v165 offset:22528
	ds_read_b128 v[222:225], v165 offset:23552
	global_load_lds_dwordx4 v[142:143], off
	v_lshl_add_u64 v[160:161], vcc, 0, v[150:151]
	s_mov_b32 m0, s0
	v_lshl_add_u64 v[190:191], s[60:61], 0, v[146:147]
	global_load_lds_dwordx4 v[160:161], off
	s_mov_b32 m0, s82
	v_lshl_add_u64 v[192:193], s[96:97], 0, v[148:149]
	global_load_lds_dwordx4 v[190:191], off
	v_lshl_add_u64 v[190:191], s[60:61], 0, v[150:151]
	s_mov_b32 m0, s1
	s_nop 0
	global_load_lds_dwordx4 v[190:191], off
	v_lshl_add_u64 v[190:191], s[96:97], 0, v[144:145]
	s_mov_b32 m0, s14
	s_nop 0
	global_load_lds_dwordx4 v[190:191], off
	s_mov_b32 m0, s12
	s_nop 0
	global_load_lds_dwordx4 v[192:193], off
	s_waitcnt vmcnt(8)
	s_waitcnt lgkmcnt(0)
	s_barrier
; #define PG8_STAGE(bufoff, gbase, voff) do { _Pragma("unroll") for (int _i = 0; _i < 2; ++_i) \
;         __builtin_amdgcn_global_load_lds((const unsigned*)((const char*)(gbase) + (voff)[_i]), (LAS unsigned*)(lds + (bufoff) + ldsw + _i * 8192), 16, 0, 0); } while (0)
; #define PG8_LDA(dst, b, h) do { _Pragma("unroll") for (int m = 0; m < 4; ++m) _Pragma("unroll") for (int k = 0; k < 2; ++k) dst[m][k] = *(const LAS bf16x8*)(lds + PG8_SA(b, h) + aoff + m * 2048 + k * 1024); } while (0)
; #define PG8_LDB(dst, b, h) do { _Pragma("unroll") for (int n = 0; n < 2; ++n) _Pragma("unroll") for (int k = 0; k < 2; ++k) dst[n][k] = *(const LAS bf16x8*)(lds + PG8_SB(b, h) + boff + n * 2048 + k * 1024); } while (0)
; #define PG8_MMA(ai, bj, At, Bt) do { __builtin_amdgcn_s_setprio(1); _Pragma("unroll") for (int m = 0; m < 4; ++m) _Pragma("unroll") for (int n = 0; n < 2; ++n) _Pragma("unroll") for (int k = 0; k < 2; ++k) \
;         acc[ai][bj][m][n] = __builtin_amdgcn_mfma_f32_16x16x32_bf16(Bt[n][k], At[m][k], acc[ai][bj][m][n], 0, 0, 0); __builtin_amdgcn_s_setprio(0); } while (0)
; #define PG8_WAIT_V(n) asm volatile("s_waitcnt vmcnt(" #n ")" ::: "memory")
; #define PG8_WAIT_L(n) asm volatile("s_waitcnt lgkmcnt(" #n ")" ::: "memory")
; #define PG8_BAR __builtin_amdgcn_s_barrier()
; #define PG8_SCHED __builtin_amdgcn_sched_barrier(0)
; template <class Epi, bool ALIGN_EPI, int M_, int N_, int K_, int LDA, int LDB>
; __device__ __forceinline__ void gemm_phase(LAS unsigned char* lds, const int tid_in, const int G_in, const int bx_in, const Gemm g, const Epi& E) {
;     ...
;             PG8_WAIT_V(8); PG8_WAIT_L(0); PG8_BAR; PG8_MMA(1, 0, At, B0); PG8_MMA(1, 1, At, B1); PG8_BAR; PG8_SCHED;
;             PG8_LDB(B0, 1, 0); PG8_LDB(B1, 1, 1); PG8_SCHED; PG8_LDA(At, 1, 0); PG8_STAGE(PG8_SA(0, 1), a2 + hstepA, voffA);
;             PG8_WAIT_V(8); PG8_WAIT_L(0); PG8_BAR; PG8_MMA(0, 0, At, B0); PG8_MMA(0, 1, At, B1); PG8_BAR; PG8_SCHED;
	s_setprio 1
	s_waitcnt lgkmcnt(0)
	v_mfma_f32_16x16x32_bf16 v[62:65], v[130:133], v[182:185], v[62:65]
	v_mfma_f32_16x16x32_bf16 v[58:61], v[138:141], v[182:185], v[58:61]
	v_mfma_f32_16x16x32_bf16 v[46:49], v[130:133], v[202:205], v[46:49]
	v_mfma_f32_16x16x32_bf16 v[42:45], v[138:141], v[202:205], v[42:45]
	v_mfma_f32_16x16x32_bf16 v[30:33], v[130:133], v[210:213], v[30:33]
	v_mfma_f32_16x16x32_bf16 v[26:29], v[138:141], v[210:213], v[26:29]
	v_mfma_f32_16x16x32_bf16 v[14:17], v[130:133], v[218:221], v[14:17]
	v_mfma_f32_16x16x32_bf16 v[10:13], v[138:141], v[218:221], v[10:13]
	v_mfma_f32_16x16x32_bf16 v[62:65], v[134:137], v[186:189], v[62:65]
	v_mfma_f32_16x16x32_bf16 v[58:61], v[156:159], v[186:189], v[58:61]
	v_mfma_f32_16x16x32_bf16 v[46:49], v[134:137], v[206:209], v[46:49]
	v_mfma_f32_16x16x32_bf16 v[42:45], v[156:159], v[206:209], v[42:45]
	v_mfma_f32_16x16x32_bf16 v[30:33], v[134:137], v[214:217], v[30:33]
	v_mfma_f32_16x16x32_bf16 v[26:29], v[156:159], v[214:217], v[26:29]
	v_mfma_f32_16x16x32_bf16 v[14:17], v[134:137], v[222:225], v[14:17]
	v_mfma_f32_16x16x32_bf16 v[10:13], v[156:159], v[222:225], v[10:13]
	v_mfma_f32_16x16x32_bf16 v[54:57], v[166:169], v[182:185], v[54:57]
	v_mfma_f32_16x16x32_bf16 v[50:53], v[174:177], v[182:185], v[50:53]
	v_mfma_f32_16x16x32_bf16 v[38:41], v[166:169], v[202:205], v[38:41]
	v_mfma_f32_16x16x32_bf16 v[34:37], v[174:177], v[202:205], v[34:37]
	v_mfma_f32_16x16x32_bf16 v[22:25], v[166:169], v[210:213], v[22:25]
	v_mfma_f32_16x16x32_bf16 v[18:21], v[174:177], v[210:213], v[18:21]
	v_mfma_f32_16x16x32_bf16 v[6:9], v[166:169], v[218:221], v[6:9]
	v_mfma_f32_16x16x32_bf16 v[2:5], v[174:177], v[218:221], v[2:5]
	v_mfma_f32_16x16x32_bf16 v[54:57], v[170:173], v[186:189], v[54:57]
	v_mfma_f32_16x16x32_bf16 v[50:53], v[178:181], v[186:189], v[50:53]
	v_mfma_f32_16x16x32_bf16 v[38:41], v[170:173], v[206:209], v[38:41]
	v_mfma_f32_16x16x32_bf16 v[34:37], v[178:181], v[206:209], v[34:37]
	v_mfma_f32_16x16x32_bf16 v[22:25], v[170:173], v[214:217], v[22:25]
	v_mfma_f32_16x16x32_bf16 v[18:21], v[178:181], v[214:217], v[18:21]
	v_mfma_f32_16x16x32_bf16 v[6:9], v[170:173], v[222:225], v[6:9]
	v_mfma_f32_16x16x32_bf16 v[2:5], v[178:181], v[222:225], v[2:5]
	s_setprio 0
	s_barrier
	v_add_u32_e32 v0, s83, v163
	ds_read_b128 v[130:133], v0
	ds_read_b128 v[134:137], v0 offset:1024
	ds_read_b128 v[138:141], v0 offset:2048
	ds_read_b128 v[156:159], v0 offset:3072
	v_add_u32_e32 v0, s43, v163
	ds_read_b128 v[166:169], v0
	ds_read_b128 v[170:173], v0 offset:1024
	ds_read_b128 v[174:177], v0 offset:2048
	ds_read_b128 v[178:181], v0 offset:3072
	s_mov_b32 m0, s13
	v_lshl_add_u64 v[200:201], s[94:95], 0, v[144:145]
	ds_read_b128 v[182:185], v165 offset:32768
	ds_read_b128 v[186:189], v165 offset:33792
	ds_read_b128 v[202:205], v165 offset:34816
	ds_read_b128 v[206:209], v165 offset:35840
	ds_read_b128 v[210:213], v165 offset:36864
	ds_read_b128 v[214:217], v165 offset:37888
	ds_read_b128 v[218:221], v165 offset:38912
	ds_read_b128 v[222:225], v165 offset:39936
	global_load_lds_dwordx4 v[200:201], off
	v_lshl_add_u64 v[200:201], s[94:95], 0, v[148:149]
	s_mov_b32 m0, s34
	s_nop 0
	global_load_lds_dwordx4 v[200:201], off
	s_waitcnt vmcnt(8)
	s_waitcnt lgkmcnt(0)
	s_barrier
	s_setprio 1
	s_waitcnt lgkmcnt(0)
	v_mfma_f32_16x16x32_bf16 v[126:129], v[130:133], v[182:185], v[126:129]
	v_mfma_f32_16x16x32_bf16 v[122:125], v[138:141], v[182:185], v[122:125]
	v_mfma_f32_16x16x32_bf16 v[110:113], v[130:133], v[202:205], v[110:113]
	v_mfma_f32_16x16x32_bf16 v[106:109], v[138:141], v[202:205], v[106:109]
	v_mfma_f32_16x16x32_bf16 v[94:97], v[130:133], v[210:213], v[94:97]
	v_mfma_f32_16x16x32_bf16 v[90:93], v[138:141], v[210:213], v[90:93]
	v_mfma_f32_16x16x32_bf16 v[78:81], v[130:133], v[218:221], v[78:81]
	v_mfma_f32_16x16x32_bf16 v[74:77], v[138:141], v[218:221], v[74:77]
	v_mfma_f32_16x16x32_bf16 v[126:129], v[134:137], v[186:189], v[126:129]
	v_mfma_f32_16x16x32_bf16 v[122:125], v[156:159], v[186:189], v[122:125]
	v_mfma_f32_16x16x32_bf16 v[110:113], v[134:137], v[206:209], v[110:113]
	v_mfma_f32_16x16x32_bf16 v[106:109], v[156:159], v[206:209], v[106:109]
	v_mfma_f32_16x16x32_bf16 v[94:97], v[134:137], v[214:217], v[94:97]
	v_mfma_f32_16x16x32_bf16 v[90:93], v[156:159], v[214:217], v[90:93]
	v_mfma_f32_16x16x32_bf16 v[78:81], v[134:137], v[222:225], v[78:81]
	v_mfma_f32_16x16x32_bf16 v[74:77], v[156:159], v[222:225], v[74:77]
	v_mfma_f32_16x16x32_bf16 v[118:121], v[166:169], v[182:185], v[118:121]
	v_mfma_f32_16x16x32_bf16 v[114:117], v[174:177], v[182:185], v[114:117]
	v_mfma_f32_16x16x32_bf16 v[102:105], v[166:169], v[202:205], v[102:105]
	v_mfma_f32_16x16x32_bf16 v[98:101], v[174:177], v[202:205], v[98:101]
	v_mfma_f32_16x16x32_bf16 v[86:89], v[166:169], v[210:213], v[86:89]
	v_mfma_f32_16x16x32_bf16 v[82:85], v[174:177], v[210:213], v[82:85]
	v_mfma_f32_16x16x32_bf16 v[70:73], v[166:169], v[218:221], v[70:73]
	v_mfma_f32_16x16x32_bf16 v[66:69], v[174:177], v[218:221], v[66:69]
	v_mfma_f32_16x16x32_bf16 v[118:121], v[170:173], v[186:189], v[118:121]
	v_mfma_f32_16x16x32_bf16 v[114:117], v[178:181], v[186:189], v[114:117]
	v_mfma_f32_16x16x32_bf16 v[102:105], v[170:173], v[206:209], v[102:105]
	v_mfma_f32_16x16x32_bf16 v[98:101], v[178:181], v[206:209], v[98:101]
	v_mfma_f32_16x16x32_bf16 v[86:89], v[170:173], v[214:217], v[86:89]
	v_mfma_f32_16x16x32_bf16 v[82:85], v[178:181], v[214:217], v[82:85]
	v_mfma_f32_16x16x32_bf16 v[70:73], v[170:173], v[222:225], v[70:73]
	v_mfma_f32_16x16x32_bf16 v[66:69], v[178:181], v[222:225], v[66:69]
	s_setprio 0
	s_barrier
; #define PG8_STAGE(bufoff, gbase, voff) do { _Pragma("unroll") for (int _i = 0; _i < 2; ++_i) \
;         __builtin_amdgcn_global_load_lds((const unsigned*)((const char*)(gbase) + (voff)[_i]), (LAS unsigned*)(lds + (bufoff) + ldsw + _i * 8192), 16, 0, 0); } while (0)
; #define PG8_LDA(dst, b, h) do { _Pragma("unroll") for (int m = 0; m < 4; ++m) _Pragma("unroll") for (int k = 0; k < 2; ++k) dst[m][k] = *(const LAS bf16x8*)(lds + PG8_SA(b, h) + aoff + m * 2048 + k * 1024); } while (0)
; #define PG8_MMA(ai, bj, At, Bt) do { __builtin_amdgcn_s_setprio(1); _Pragma("unroll") for (int m = 0; m < 4; ++m) _Pragma("unroll") for (int n = 0; n < 2; ++n) _Pragma("unroll") for (int k = 0; k < 2; ++k) \
;         acc[ai][bj][m][n] = __builtin_amdgcn_mfma_f32_16x16x32_bf16(Bt[n][k], At[m][k], acc[ai][bj][m][n], 0, 0, 0); __builtin_amdgcn_s_setprio(0); } while (0)
; #define PG8_WAIT_V(n) asm volatile("s_waitcnt vmcnt(" #n ")" ::: "memory")
; #define PG8_WAIT_L(n) asm volatile("s_waitcnt lgkmcnt(" #n ")" ::: "memory")
; #define PG8_BAR __builtin_amdgcn_s_barrier()
; #define PG8_SCHED __builtin_amdgcn_sched_barrier(0)
; template <class Epi, bool ALIGN_EPI, int M_, int N_, int K_, int LDA, int LDB>
; __device__ __forceinline__ void gemm_phase(LAS unsigned char* lds, const int tid_in, const int G_in, const int bx_in, const Gemm g, const Epi& E) {
;     ...
;             PG8_LDA(At, 1, 1); PG8_STAGE(PG8_SB(1, 0), b3, voffB); PG8_STAGE(PG8_SB(1, 1), b3 + hstepB, voffB); PG8_STAGE(PG8_SA(1, 0), a3, voffA);
;             PG8_WAIT_V(8); PG8_WAIT_L(0); PG8_BAR; PG8_MMA(1, 0, At, B0); PG8_MMA(1, 1, At, B1); PG8_BAR; PG8_SCHED;
;         }
;         if constexpr (ALIGN_EPI) { if (wr == 0) PG8_BAR; }
	s_mov_b32 m0, s78
	v_lshl_add_u64 v[142:143], v[142:143], 0, s[54:55]
	ds_read_b128 v[182:185], v165 offset:49152
	ds_read_b128 v[186:189], v165 offset:50176
	ds_read_b128 v[202:205], v165 offset:51200
	ds_read_b128 v[206:209], v165 offset:52224
	ds_read_b128 v[210:213], v165 offset:53248
	ds_read_b128 v[214:217], v165 offset:54272
	ds_read_b128 v[218:221], v165 offset:55296
	ds_read_b128 v[222:225], v165 offset:56320
	global_load_lds_dwordx4 v[142:143], off
	v_lshl_add_u64 v[142:143], v[160:161], 0, s[54:55]
	s_mov_b32 m0, s42
	s_nop 0
	global_load_lds_dwordx4 v[142:143], off
	v_lshl_add_u64 v[142:143], s[92:93], 0, v[146:147]
	s_mov_b32 m0, s66
	s_nop 0
	global_load_lds_dwordx4 v[142:143], off
	v_lshl_add_u64 v[142:143], s[92:93], 0, v[150:151]
	s_mov_b32 m0, s15
	s_nop 0
	global_load_lds_dwordx4 v[142:143], off
	v_lshl_add_u64 v[142:143], v[190:191], 0, s[54:55]
	s_mov_b32 m0, s75
	s_nop 0
	global_load_lds_dwordx4 v[142:143], off
	v_lshl_add_u64 v[142:143], v[192:193], 0, s[54:55]
	s_mov_b32 m0, s77
	s_nop 0
	global_load_lds_dwordx4 v[142:143], off
	s_waitcnt vmcnt(8)
	s_waitcnt lgkmcnt(0)
	s_barrier
	s_setprio 1
	s_waitcnt lgkmcnt(0)
	v_mfma_f32_16x16x32_bf16 v[62:65], v[130:133], v[182:185], v[62:65]
	v_mfma_f32_16x16x32_bf16 v[58:61], v[138:141], v[182:185], v[58:61]
	v_mfma_f32_16x16x32_bf16 v[46:49], v[130:133], v[202:205], v[46:49]
	v_mfma_f32_16x16x32_bf16 v[42:45], v[138:141], v[202:205], v[42:45]
	v_mfma_f32_16x16x32_bf16 v[30:33], v[130:133], v[210:213], v[30:33]
	v_mfma_f32_16x16x32_bf16 v[26:29], v[138:141], v[210:213], v[26:29]
	v_mfma_f32_16x16x32_bf16 v[14:17], v[130:133], v[218:221], v[14:17]
	v_mfma_f32_16x16x32_bf16 v[10:13], v[138:141], v[218:221], v[10:13]
	v_mfma_f32_16x16x32_bf16 v[62:65], v[134:137], v[186:189], v[62:65]
	v_mfma_f32_16x16x32_bf16 v[58:61], v[156:159], v[186:189], v[58:61]
	v_mfma_f32_16x16x32_bf16 v[46:49], v[134:137], v[206:209], v[46:49]
	v_mfma_f32_16x16x32_bf16 v[42:45], v[156:159], v[206:209], v[42:45]
	v_mfma_f32_16x16x32_bf16 v[30:33], v[134:137], v[214:217], v[30:33]
	v_mfma_f32_16x16x32_bf16 v[26:29], v[156:159], v[214:217], v[26:29]
	v_mfma_f32_16x16x32_bf16 v[14:17], v[134:137], v[222:225], v[14:17]
	v_mfma_f32_16x16x32_bf16 v[10:13], v[156:159], v[222:225], v[10:13]
	v_mfma_f32_16x16x32_bf16 v[54:57], v[166:169], v[182:185], v[54:57]
	v_mfma_f32_16x16x32_bf16 v[50:53], v[174:177], v[182:185], v[50:53]
	v_mfma_f32_16x16x32_bf16 v[38:41], v[166:169], v[202:205], v[38:41]
	v_mfma_f32_16x16x32_bf16 v[34:37], v[174:177], v[202:205], v[34:37]
	v_mfma_f32_16x16x32_bf16 v[22:25], v[166:169], v[210:213], v[22:25]
	v_mfma_f32_16x16x32_bf16 v[18:21], v[174:177], v[210:213], v[18:21]
	v_mfma_f32_16x16x32_bf16 v[6:9], v[166:169], v[218:221], v[6:9]
	v_mfma_f32_16x16x32_bf16 v[2:5], v[174:177], v[218:221], v[2:5]
	v_mfma_f32_16x16x32_bf16 v[54:57], v[170:173], v[186:189], v[54:57]
	v_mfma_f32_16x16x32_bf16 v[50:53], v[178:181], v[186:189], v[50:53]
	v_mfma_f32_16x16x32_bf16 v[38:41], v[170:173], v[206:209], v[38:41]
	v_mfma_f32_16x16x32_bf16 v[34:37], v[178:181], v[206:209], v[34:37]
	v_mfma_f32_16x16x32_bf16 v[22:25], v[170:173], v[214:217], v[22:25]
	v_mfma_f32_16x16x32_bf16 v[18:21], v[178:181], v[214:217], v[18:21]
	v_mfma_f32_16x16x32_bf16 v[6:9], v[170:173], v[222:225], v[6:9]
	v_mfma_f32_16x16x32_bf16 v[2:5], v[178:181], v[222:225], v[2:5]
	s_setprio 0
	s_barrier
	s_andn2_b64 vcc, exec, s[90:91]
	s_mov_b64 s[92:93], -1
	s_mov_b64 s[90:91], 0
	s_mov_b64 s[94:95], 0x100
	s_cbranch_vccz .LBB0_1832
	v_readlane_b32 s0, v255, 40
	v_readlane_b32 s1, v255, 41
	s_and_b64 vcc, exec, s[0:1]
	s_cbranch_vccz .LBB0_1835
	s_barrier
